# attention/pool epilogue bf16 packing (sdwa bit-trick RNE) replaced by v_cvt_pk_bf16_f32 (same RNE)
# speedup vs baseline: 1.0086x; 1.0086x over previous
; #define LAS __attribute__((address_space(3)))
; __device__ __forceinline__ unsigned f2bf(float f) { unsigned u = __builtin_bit_cast(unsigned, f); return (u + 0x7fffu + ((u >> 16) & 1u)) >> 16; }
; __device__ __forceinline__ float bf1(bf16 h) { return __uint_as_float(((unsigned)h) << 16); }
; __device__ __forceinline__ void pool_item(const Args& A, const Ctx& C0, int l, int row0, int t0, int pos0, const float* hist, float* outpool) {
;     ...
;     { const int c = C.tid, gc = c >> 7, wdc = 2 << gc;
;       float s = 0.f;
;       for (int i = 0; i < wdc; ++i) s += bf1(P[(15 - i) * PP + c]);
; #pragma unroll 4
;       for (int t = 0; t < 32; ++t) { const int pos = pos0 + t; const float inv = 1.f / (float)((pos + 1) < wdc ? (pos + 1) : wdc);
;           const float cur = bf1(P[(15 + t) * PP + c]);
;           Dm[t * PP + c] = (bf16)f2bf(s * inv - cur);
;           s += bf1(P[(16 + t) * PP + c]) - bf1(P[(16 + t - wdc) * PP + c]); } }
;     __syncthreads();
;     const int g = C.wave & 3, ddh = C.wave >> 2, tk = C.lane & 31, h = C.lane >> 5;
;     const bf16* PW = WS_PTR(const bf16, WS_PWT) + (size_t)(l * 4 + g) * 128 * 128;
;     f32x16 acc[2];
; #pragma unroll
;     for (int dt = 0; dt < 2; ++dt)
; #pragma unroll
;         for (int r = 0; r < 16; ++r) acc[dt][r] = 0.f;
; #pragma unroll
;     for (int ks = 0; ks < 8; ++ks) { const bf16x8 df = *(const LAS bf16x8*)(Dm + tk * PP + g * 128 + ks * 16 + 8 * h);
; #pragma unroll
;         for (int dt = 0; dt < 2; ++dt) { const bf16x8 af = *(const bf16x8*)(PW + (size_t)(ddh * 64 + dt * 32 + tk) * 128 + ks * 16 + 8 * h);
;             acc[dt] = __builtin_amdgcn_mfma_f32_32x32x16_bf16(af, df, acc[dt], 0, 0, 0); }
;     }
;     const size_t row = (size_t)(row0 + tk);
;     const float* psc = A.in[I_POOLS] + l * 512;
; #pragma unroll
;     for (int dt = 0; dt < 2; ++dt)
; #pragma unroll
;         for (int rq = 0; rq < 4; ++rq) { const int cc = g * 128 + ddh * 64 + dt * 32 + 8 * rq + 4 * h;
;             const v2u gx = *(const v2u*)(U + row * DIN + C_GP + cc); const f32x4 sc = *(const f32x4*)(psc + cc);
.LBB0_254:
	s_add_i32 s1, s16, s0
	s_add_i32 s2, s1, 1
	v_min_i32_e32 v3, s2, v0
	v_cvt_f32_i32_e32 v3, v3
	s_waitcnt lgkmcnt(0)
	v_lshlrev_b32_e32 v5, 16, v5
	s_add_i32 s0, s0, 4
	v_div_scale_f32 v7, s[2:3], v3, v3, 1.0
	v_rcp_f32_e32 v8, v7
	s_add_i32 s2, s1, 2
	v_fma_f32 v9, -v7, v8, 1.0
	v_fmac_f32_e32 v8, v9, v8
	v_div_scale_f32 v9, vcc, 1.0, v3, 1.0
	v_mul_f32_e32 v10, v9, v8
	v_fma_f32 v11, -v7, v10, v9
	v_fmac_f32_e32 v10, v11, v8
	v_fma_f32 v7, -v7, v10, v9
	v_div_fmas_f32 v7, v7, v8, v10
	v_div_fixup_f32 v3, v7, v3, 1.0
	v_fma_f32 v3, v4, v3, -v5
	v_bfe_u32 v5, v3, 16, 1
	v_add3_u32 v3, v3, v5, s33
	ds_write_b16_d16_hi v6, v3 offset:33280
	v_add_u32_e32 v3, v6, v2
	ds_read_u16 v5, v3 offset:1040
	ds_read_u16 v7, v6 offset:1040
	s_waitcnt lgkmcnt(1)
	v_lshlrev_b32_e32 v5, 16, v5
	s_waitcnt lgkmcnt(0)
	v_lshlrev_b32_e32 v7, 16, v7
	v_sub_f32_e32 v5, v7, v5
	v_add_f32_e32 v4, v4, v5
	v_min_i32_e32 v5, s2, v0
	v_cvt_f32_i32_e32 v5, v5
	v_div_scale_f32 v8, s[2:3], v5, v5, 1.0
	v_rcp_f32_e32 v9, v8
	s_add_i32 s2, s1, 3
	s_add_i32 s1, s1, 4
	s_cmp_eq_u32 s0, 32
	v_fma_f32 v10, -v8, v9, 1.0
	v_fmac_f32_e32 v9, v10, v9
	v_div_scale_f32 v10, vcc, 1.0, v5, 1.0
	v_mul_f32_e32 v11, v10, v9
	v_fma_f32 v12, -v8, v11, v10
	v_fmac_f32_e32 v11, v12, v9
	v_fma_f32 v8, -v8, v11, v10
	v_div_fmas_f32 v8, v8, v9, v11
	v_div_fixup_f32 v5, v8, v5, 1.0
	v_fma_f32 v5, v4, v5, -v7
	v_bfe_u32 v7, v5, 16, 1
	v_add3_u32 v5, v5, v7, s33
	ds_write_b16_d16_hi v6, v5 offset:34320
	ds_read_u16 v5, v3 offset:2080
	ds_read_u16 v7, v6 offset:2080
	s_waitcnt lgkmcnt(1)
	v_lshlrev_b32_e32 v5, 16, v5
	s_waitcnt lgkmcnt(0)
	v_lshlrev_b32_e32 v7, 16, v7
	v_sub_f32_e32 v5, v7, v5
	v_add_f32_e32 v4, v4, v5
	v_min_i32_e32 v5, s2, v0
	v_cvt_f32_i32_e32 v5, v5
	v_div_scale_f32 v8, s[2:3], v5, v5, 1.0
	v_rcp_f32_e32 v9, v8
	s_nop 0
	v_fma_f32 v10, -v8, v9, 1.0
	v_fmac_f32_e32 v9, v10, v9
	v_div_scale_f32 v10, vcc, 1.0, v5, 1.0
	v_mul_f32_e32 v11, v10, v9
	v_fma_f32 v12, -v8, v11, v10
	v_fmac_f32_e32 v11, v12, v9
	v_fma_f32 v8, -v8, v11, v10
	v_div_fmas_f32 v8, v8, v9, v11
	v_div_fixup_f32 v5, v8, v5, 1.0
	v_fma_f32 v5, v4, v5, -v7
	v_bfe_u32 v7, v5, 16, 1
	v_add3_u32 v5, v5, v7, s33
	ds_write_b16_d16_hi v6, v5 offset:35360
	ds_read_u16 v5, v3 offset:3120
	ds_read_u16 v7, v6 offset:3120
	s_waitcnt lgkmcnt(1)
	v_lshlrev_b32_e32 v5, 16, v5
	s_waitcnt lgkmcnt(0)
	v_lshlrev_b32_e32 v7, 16, v7
	v_sub_f32_e32 v5, v7, v5
	v_add_f32_e32 v4, v4, v5
	v_min_i32_e32 v5, s1, v0
	v_cvt_f32_i32_e32 v5, v5
	v_div_scale_f32 v8, s[2:3], v5, v5, 1.0
	v_rcp_f32_e32 v9, v8
	s_nop 0
	v_fma_f32 v10, -v8, v9, 1.0
	v_fmac_f32_e32 v9, v10, v9
	v_div_scale_f32 v10, vcc, 1.0, v5, 1.0
	v_mul_f32_e32 v11, v10, v9
	v_fma_f32 v12, -v8, v11, v10
	v_fmac_f32_e32 v11, v12, v9
	v_fma_f32 v8, -v8, v11, v10
	v_div_fmas_f32 v8, v8, v9, v11
	v_div_fixup_f32 v5, v8, v5, 1.0
	v_fma_f32 v5, v4, v5, -v7
	v_bfe_u32 v7, v5, 16, 1
	v_add3_u32 v5, v5, v7, s33
	ds_write_b16_d16_hi v6, v5 offset:36400
	ds_read_u16 v5, v6 offset:4160
	ds_read_u16 v3, v3 offset:4160
	v_add_u32_e32 v7, 0x1040, v6
	s_waitcnt lgkmcnt(1)
	v_lshlrev_b32_e32 v6, 16, v5
	s_waitcnt lgkmcnt(0)
	v_lshlrev_b32_e32 v3, 16, v3
	v_sub_f32_e32 v3, v6, v3
	v_add_f32_e32 v4, v4, v3
	v_mov_b32_e32 v6, v7
	s_cbranch_scc0 .LBB0_254
	s_bfe_u32 s0, s69, 0x20006
	v_readlane_b32 s1, v255, 46
	s_or_b32 s2, s0, s1
	s_ashr_i32 s3, s2, 31
	s_lshl_b64 s[2:3], s[2:3], 15
	s_add_u32 s2, s24, s2
	v_bfe_u32 v48, v34, 5, 1
	v_and_b32_e32 v49, 31, v34
	s_addc_u32 s3, s25, s3
	s_lshl_b32 s1, s0, 8
	v_mul_u32_u24_e32 v2, 0x410, v49
	s_add_i32 s1, s1, 0
	v_lshlrev_b32_e32 v0, 4, v48
	v_add3_u32 v50, s1, v2, v0
	s_ashr_i32 s1, s69, 2
	s_andn2_b32 s1, s1, 63
	v_or_b32_e32 v10, s1, v49
	v_lshl_add_u64 v[2:3], s[2:3], 0, v[0:1]
	s_mov_b64 s[2:3], 0x7900000
	v_ashrrev_i32_e32 v11, 31, v10
	v_lshl_add_u64 v[12:13], v[2:3], 0, s[2:3]
	v_lshlrev_b64 v[2:3], 8, v[10:11]
	v_lshl_add_u64 v[44:45], v[12:13], 0, v[2:3]
	s_barrier
	flat_load_dwordx4 v[2:5], v[44:45]
	ds_read_b128 v[6:9], v50 offset:48880
	ds_read_b128 v[36:39], v50 offset:48912
	s_lshl_b32 s0, s0, 7
	s_add_i32 s0, s0, s1
	v_add_u32_e32 v0, s10, v49
	s_cmp_lg_u64 s[58:59], 0
	s_movk_i32 s2, 0x1e00
	s_waitcnt vmcnt(0) lgkmcnt(0)
	v_mfma_f32_32x32x16_bf16 v[18:33], v[2:5], v[6:9], 0
	v_or_b32_e32 v2, 32, v10
	v_ashrrev_i32_e32 v3, 31, v2
	v_lshlrev_b64 v[2:3], 8, v[2:3]
	v_lshl_add_u64 v[46:47], v[12:13], 0, v[2:3]
	flat_load_dwordx4 v[2:5], v[46:47]
	flat_load_dwordx4 v[40:43], v[44:45] offset:32
	s_waitcnt vmcnt(0) lgkmcnt(0)
	v_mfma_f32_32x32x16_bf16 v[18:33], v[40:43], v[36:39], v[18:33]
	flat_load_dwordx4 v[40:43], v[46:47] offset:32
	v_mfma_f32_32x32x16_bf16 v[2:17], v[2:5], v[6:9], 0
	s_waitcnt vmcnt(0) lgkmcnt(0)
	v_mfma_f32_32x32x16_bf16 v[2:17], v[40:43], v[36:39], v[2:17]
	flat_load_dwordx4 v[40:43], v[44:45] offset:64
	ds_read_b128 v[36:39], v50 offset:48944
	s_waitcnt vmcnt(0) lgkmcnt(0)
	v_mfma_f32_32x32x16_bf16 v[18:33], v[40:43], v[36:39], v[18:33]
	flat_load_dwordx4 v[40:43], v[46:47] offset:64
	s_waitcnt vmcnt(0) lgkmcnt(0)
	v_mfma_f32_32x32x16_bf16 v[2:17], v[40:43], v[36:39], v[2:17]
	flat_load_dwordx4 v[40:43], v[44:45] offset:96
	ds_read_b128 v[36:39], v50 offset:48976
	s_waitcnt vmcnt(0) lgkmcnt(0)
	v_mfma_f32_32x32x16_bf16 v[18:33], v[40:43], v[36:39], v[18:33]
	flat_load_dwordx4 v[40:43], v[46:47] offset:96
	s_waitcnt vmcnt(0) lgkmcnt(0)
	v_mfma_f32_32x32x16_bf16 v[2:17], v[40:43], v[36:39], v[2:17]
	flat_load_dwordx4 v[40:43], v[44:45] offset:128
	ds_read_b128 v[36:39], v50 offset:49008
	s_waitcnt vmcnt(0) lgkmcnt(0)
	v_mfma_f32_32x32x16_bf16 v[18:33], v[40:43], v[36:39], v[18:33]
	flat_load_dwordx4 v[40:43], v[46:47] offset:128
	s_waitcnt vmcnt(0) lgkmcnt(0)
; __device__ __forceinline__ unsigned pk2(float lo, float hi) { return f2bf(lo) | (f2bf(hi) << 16); }
; __device__ __forceinline__ float bflo(unsigned w) { return __uint_as_float(w << 16); }
; __device__ __forceinline__ float bfhi(unsigned w) { return __uint_as_float(w & 0xffff0000u); }
; __device__ __forceinline__ float silu(float x) { return x / (1.f + __expf(-x)); }
; __device__ __forceinline__ void pool_item(const Args& A, const Ctx& C0, int l, int row0, int t0, int pos0, const float* hist, float* outpool) {
;     ...
;     const size_t row = (size_t)(row0 + tk);
;     const float* psc = A.in[I_POOLS] + l * 512;
; #pragma unroll
;     for (int dt = 0; dt < 2; ++dt)
; #pragma unroll
;         for (int rq = 0; rq < 4; ++rq) { const int cc = g * 128 + ddh * 64 + dt * 32 + 8 * rq + 4 * h;
;             const v2u gx = *(const v2u*)(U + row * DIN + C_GP + cc); const f32x4 sc = *(const f32x4*)(psc + cc);
;             const float o0 = acc[dt][4 * rq] * sc.x * silu(bflo(gx.x)), o1 = acc[dt][4 * rq + 1] * sc.y * silu(bfhi(gx.x)), o2 = acc[dt][4 * rq + 2] * sc.z * silu(bflo(gx.y)), o3 = acc[dt][4 * rq + 3] * sc.w * silu(bfhi(gx.y));
;             v2u o; o.x = pk2(o0, o1); o.y = pk2(o2, o3);
;             *(v2u*)(MIX + row * D + cc) = o; }
	v_mfma_f32_32x32x16_bf16 v[2:17], v[40:43], v[36:39], v[2:17]
	flat_load_dwordx4 v[40:43], v[44:45] offset:160
	ds_read_b128 v[36:39], v50 offset:49040
	s_waitcnt vmcnt(0) lgkmcnt(0)
	v_mfma_f32_32x32x16_bf16 v[18:33], v[40:43], v[36:39], v[18:33]
	flat_load_dwordx4 v[40:43], v[46:47] offset:160
	s_waitcnt vmcnt(0) lgkmcnt(0)
	v_mfma_f32_32x32x16_bf16 v[2:17], v[40:43], v[36:39], v[2:17]
	flat_load_dwordx4 v[40:43], v[44:45] offset:192
	ds_read_b128 v[36:39], v50 offset:49072
	s_waitcnt vmcnt(0) lgkmcnt(0)
	v_mfma_f32_32x32x16_bf16 v[18:33], v[40:43], v[36:39], v[18:33]
	flat_load_dwordx4 v[40:43], v[46:47] offset:192
	s_waitcnt vmcnt(0) lgkmcnt(0)
	v_mfma_f32_32x32x16_bf16 v[2:17], v[40:43], v[36:39], v[2:17]
	flat_load_dwordx4 v[40:43], v[44:45] offset:224
	ds_read_b128 v[36:39], v50 offset:49104
	s_waitcnt vmcnt(0) lgkmcnt(0)
	v_mfma_f32_32x32x16_bf16 v[18:33], v[40:43], v[36:39], v[18:33]
	flat_load_dwordx4 v[40:43], v[46:47] offset:224
	s_nop 10
	v_mov_b32_e32 v52, v18
	v_mov_b32_e32 v53, v20
	s_waitcnt vmcnt(0) lgkmcnt(0)
	v_mfma_f32_32x32x16_bf16 v[2:17], v[40:43], v[36:39], v[2:17]
	v_lshl_or_b32 v36, v48, 2, s0
	v_mov_b64_e32 v[38:39], s[60:61]
	s_movk_i32 s0, 0x2b00
	v_ashrrev_i32_e32 v37, 31, v36
	v_mad_u64_u32 v[38:39], s[0:1], v0, s0, v[38:39]
	v_lshlrev_b64 v[46:47], 1, v[36:37]
	v_lshl_add_u64 v[38:39], v[38:39], 0, v[46:47]
	flat_load_dwordx2 v[48:49], v[38:39] offset:1024
	v_lshlrev_b64 v[40:41], 12, v[0:1]
	v_lshl_add_u64 v[36:37], v[36:37], 2, s[78:79]
	v_lshl_add_u64 v[44:45], s[24:25], 0, v[40:41]
	global_load_dwordx4 v[40:43], v[36:37], off
	s_waitcnt vmcnt(0) lgkmcnt(0)
	v_lshlrev_b32_e32 v0, 16, v49
	v_lshlrev_b32_e32 v56, 16, v48
	v_mul_f32_e32 v50, 0xbfb8aa3b, v56
	v_mul_f32_e32 v18, 0xbfb8aa3b, v0
	v_exp_f32_e32 v50, v50
	v_exp_f32_e32 v51, v18
	v_mov_b32_e32 v54, v40
	v_mov_b32_e32 v55, v42
	v_and_b32_e32 v57, 0xffff0000, v49
	v_pk_add_f32 v[50:51], v[50:51], 1.0 op_sel_hi:[1,0]
	v_and_b32_e32 v58, 0xffff0000, v48
	v_div_scale_f32 v18, s[0:1], v51, v51, v0
	v_rcp_f32_e32 v20, v18
	v_mul_f32_e32 v48, 0xbfb8aa3b, v58
	v_exp_f32_e32 v48, v48
	v_pk_mul_f32 v[52:53], v[52:53], v[54:55]
	v_fma_f32 v40, -v18, v20, 1.0
	v_fmac_f32_e32 v20, v40, v20
	v_div_scale_f32 v40, vcc, v0, v51, v0
	v_mul_f32_e32 v42, v40, v20
	v_fma_f32 v49, -v18, v42, v40
	v_fmac_f32_e32 v42, v49, v20
	v_fma_f32 v18, -v18, v42, v40
	v_div_fmas_f32 v18, v18, v20, v42
	v_div_fixup_f32 v51, v18, v51, v0
	v_div_scale_f32 v0, s[0:1], v50, v50, v56
	v_rcp_f32_e32 v18, v0
	s_nop 0
	v_fma_f32 v20, -v0, v18, 1.0
	v_fmac_f32_e32 v18, v20, v18
	v_div_scale_f32 v20, vcc, v56, v50, v56
	v_mul_f32_e32 v40, v20, v18
	v_fma_f32 v42, -v0, v40, v20
	v_fmac_f32_e32 v40, v42, v18
	v_fma_f32 v0, -v0, v40, v20
	v_div_fmas_f32 v0, v0, v18, v40
	v_div_fixup_f32 v50, v0, v50, v56
	v_mul_f32_e32 v0, 0xbfb8aa3b, v57
	v_exp_f32_e32 v49, v0
	v_mov_b32_e32 v20, v19
	v_mov_b32_e32 v42, v41
	v_pk_mul_f32 v[18:19], v[20:21], v[42:43]
	v_pk_add_f32 v[20:21], v[48:49], 1.0 op_sel_hi:[1,0]
	v_pk_mul_f32 v[50:51], v[52:53], v[50:51]
	v_div_scale_f32 v0, s[0:1], v21, v21, v57
	v_rcp_f32_e32 v40, v0
	s_nop 0
	v_fma_f32 v41, -v0, v40, 1.0
	v_fmac_f32_e32 v40, v41, v40
	v_div_scale_f32 v41, vcc, v57, v21, v57
	v_mul_f32_e32 v42, v41, v40
	v_fma_f32 v43, -v0, v42, v41
	v_fmac_f32_e32 v42, v43, v40
	v_fma_f32 v0, -v0, v42, v41
	v_div_fmas_f32 v0, v0, v40, v42
	v_div_fixup_f32 v21, v0, v21, v57
	v_div_scale_f32 v0, s[0:1], v20, v20, v58
	v_rcp_f32_e32 v40, v0
	s_mov_b64 s[0:1], 0x7b27900
	v_fma_f32 v41, -v0, v40, 1.0
	v_fmac_f32_e32 v40, v41, v40
	v_div_scale_f32 v41, vcc, v58, v20, v58
	v_mul_f32_e32 v42, v41, v40
	v_fma_f32 v43, -v0, v42, v41
	v_fmac_f32_e32 v42, v43, v40
	v_fma_f32 v0, -v0, v42, v41
	v_div_fmas_f32 v0, v0, v40, v42
	v_div_fixup_f32 v20, v0, v20, v58
	v_pk_mul_f32 v[18:19], v[18:19], v[20:21]
	v_lshl_add_u64 v[40:41], v[44:45], 0, v[46:47]
	v_cvt_pk_bf16_f32 v21, v51, v19
	v_cvt_pk_bf16_f32 v20, v50, v18
	v_lshl_add_u64 v[18:19], v[40:41], 0, s[0:1]
	s_mov_b32 s0, 0x7b27000
	v_add_co_u32_e32 v40, vcc, s0, v40
	v_mov_b32_e32 v46, v22
	s_nop 0
	v_addc_co_u32_e32 v41, vcc, 0, v41, vcc
	flat_store_dwordx2 v[40:41], v[20:21] offset:2304
	flat_load_dwordx2 v[20:21], v[38:39] offset:1040
	s_nop 0
	global_load_dwordx4 v[40:43], v[36:37], off offset:32
	v_mov_b32_e32 v47, v24
	s_waitcnt vmcnt(0) lgkmcnt(0)
	v_lshlrev_b32_e32 v0, 16, v21
	v_lshlrev_b32_e32 v50, 16, v20
	v_mul_f32_e32 v44, 0xbfb8aa3b, v50
	v_and_b32_e32 v51, 0xffff0000, v21
	v_mul_f32_e32 v21, 0xbfb8aa3b, v0
	v_exp_f32_e32 v44, v44
	v_exp_f32_e32 v45, v21
	v_mov_b32_e32 v48, v40
	v_mov_b32_e32 v49, v42
	v_and_b32_e32 v52, 0xffff0000, v20
	v_pk_add_f32 v[44:45], v[44:45], 1.0 op_sel_hi:[1,0]
	v_mul_f32_e32 v20, 0xbfb8aa3b, v52
	v_div_scale_f32 v21, s[0:1], v45, v45, v0
	v_rcp_f32_e32 v22, v21
	v_exp_f32_e32 v20, v20
	v_pk_mul_f32 v[46:47], v[46:47], v[48:49]
	v_fma_f32 v24, -v21, v22, 1.0
	v_fmac_f32_e32 v22, v24, v22
	v_div_scale_f32 v24, vcc, v0, v45, v0
	v_mul_f32_e32 v40, v24, v22
	v_fma_f32 v42, -v21, v40, v24
	v_fmac_f32_e32 v40, v42, v22
	v_fma_f32 v21, -v21, v40, v24
	v_div_fmas_f32 v21, v21, v22, v40
	v_div_fixup_f32 v45, v21, v45, v0
	v_div_scale_f32 v0, s[0:1], v44, v44, v50
	v_rcp_f32_e32 v21, v0
	v_mov_b32_e32 v42, v41
	v_fma_f32 v22, -v0, v21, 1.0
	v_fmac_f32_e32 v21, v22, v21
	v_div_scale_f32 v22, vcc, v50, v44, v50
	v_mul_f32_e32 v24, v22, v21
	v_fma_f32 v40, -v0, v24, v22
	v_fmac_f32_e32 v24, v40, v21
	v_fma_f32 v0, -v0, v24, v22
	v_div_fmas_f32 v0, v0, v21, v24
	v_div_fixup_f32 v44, v0, v44, v50
	v_mul_f32_e32 v0, 0xbfb8aa3b, v51
	v_exp_f32_e32 v21, v0
	v_mov_b32_e32 v24, v23
	v_pk_mul_f32 v[22:23], v[24:25], v[42:43]
	v_pk_mul_f32 v[44:45], v[46:47], v[44:45]
	v_pk_add_f32 v[20:21], v[20:21], 1.0 op_sel_hi:[1,0]
	v_mov_b32_e32 v42, v26
	v_div_scale_f32 v0, s[0:1], v21, v21, v51
	v_rcp_f32_e32 v24, v0
	v_mov_b32_e32 v43, v28
	v_fma_f32 v25, -v0, v24, 1.0
	v_fmac_f32_e32 v24, v25, v24
	v_div_scale_f32 v25, vcc, v51, v21, v51
	v_mul_f32_e32 v40, v25, v24
	v_fma_f32 v41, -v0, v40, v25
	v_fmac_f32_e32 v40, v41, v24
	v_fma_f32 v0, -v0, v40, v25
	v_div_fmas_f32 v0, v0, v24, v40
	v_div_fixup_f32 v21, v0, v21, v51
	v_div_scale_f32 v0, s[0:1], v20, v20, v52
	v_rcp_f32_e32 v24, v0
	s_nop 0
	v_fma_f32 v25, -v0, v24, 1.0
	v_fmac_f32_e32 v24, v25, v24
	v_div_scale_f32 v25, vcc, v52, v20, v52
	v_mul_f32_e32 v40, v25, v24
	v_fma_f32 v41, -v0, v40, v25
	v_fmac_f32_e32 v40, v41, v24
	v_fma_f32 v0, -v0, v40, v25
	v_div_fmas_f32 v0, v0, v24, v40
	v_div_fixup_f32 v20, v0, v20, v52
	v_pk_mul_f32 v[20:21], v[22:23], v[20:21]
	v_cvt_pk_bf16_f32 v21, v45, v21
	v_cvt_pk_bf16_f32 v20, v44, v20
	flat_store_dwordx2 v[18:19], v[20:21] offset:16
	flat_load_dwordx2 v[24:25], v[38:39] offset:1056
	s_nop 0
	global_load_dwordx4 v[20:23], v[36:37], off offset:64
	s_waitcnt vmcnt(0) lgkmcnt(0)
; __device__ __forceinline__ unsigned pk2(float lo, float hi) { return f2bf(lo) | (f2bf(hi) << 16); }
; __device__ __forceinline__ float bflo(unsigned w) { return __uint_as_float(w << 16); }
; __device__ __forceinline__ float bfhi(unsigned w) { return __uint_as_float(w & 0xffff0000u); }
; __device__ __forceinline__ float silu(float x) { return x / (1.f + __expf(-x)); }
; __device__ __forceinline__ void pool_item(const Args& A, const Ctx& C0, int l, int row0, int t0, int pos0, const float* hist, float* outpool) {
;     ...
; #pragma unroll
;     for (int dt = 0; dt < 2; ++dt)
; #pragma unroll
;         for (int rq = 0; rq < 4; ++rq) { const int cc = g * 128 + ddh * 64 + dt * 32 + 8 * rq + 4 * h;
;             const v2u gx = *(const v2u*)(U + row * DIN + C_GP + cc); const f32x4 sc = *(const f32x4*)(psc + cc);
;             const float o0 = acc[dt][4 * rq] * sc.x * silu(bflo(gx.x)), o1 = acc[dt][4 * rq + 1] * sc.y * silu(bfhi(gx.x)), o2 = acc[dt][4 * rq + 2] * sc.z * silu(bflo(gx.y)), o3 = acc[dt][4 * rq + 3] * sc.w * silu(bfhi(gx.y));
;             v2u o; o.x = pk2(o0, o1); o.y = pk2(o2, o3);
;             *(v2u*)(MIX + row * D + cc) = o; }
	v_lshlrev_b32_e32 v0, 16, v25
	v_lshlrev_b32_e32 v46, 16, v24
	v_mul_f32_e32 v40, 0xbfb8aa3b, v46
	v_mov_b32_e32 v44, v20
	v_mul_f32_e32 v20, 0xbfb8aa3b, v0
	v_exp_f32_e32 v40, v40
	v_exp_f32_e32 v41, v20
	v_mov_b32_e32 v45, v22
	v_and_b32_e32 v47, 0xffff0000, v25
	v_and_b32_e32 v48, 0xffff0000, v24
	v_pk_add_f32 v[40:41], v[40:41], 1.0 op_sel_hi:[1,0]
	v_mul_f32_e32 v24, 0xbfb8aa3b, v48
	v_div_scale_f32 v20, s[0:1], v41, v41, v0
	v_rcp_f32_e32 v22, v20
	v_exp_f32_e32 v24, v24
	v_pk_mul_f32 v[42:43], v[42:43], v[44:45]
	v_fma_f32 v25, -v20, v22, 1.0
	v_fmac_f32_e32 v22, v25, v22
	v_div_scale_f32 v25, vcc, v0, v41, v0
	v_mul_f32_e32 v26, v25, v22
	v_fma_f32 v28, -v20, v26, v25
	v_fmac_f32_e32 v26, v28, v22
	v_fma_f32 v20, -v20, v26, v25
	v_div_fmas_f32 v20, v20, v22, v26
	v_div_fixup_f32 v41, v20, v41, v0
	v_div_scale_f32 v0, s[0:1], v40, v40, v46
	v_rcp_f32_e32 v20, v0
	v_mov_b32_e32 v28, v27
	v_fma_f32 v22, -v0, v20, 1.0
	v_fmac_f32_e32 v20, v22, v20
	v_div_scale_f32 v22, vcc, v46, v40, v46
	v_mul_f32_e32 v25, v22, v20
	v_fma_f32 v26, -v0, v25, v22
	v_fmac_f32_e32 v25, v26, v20
	v_fma_f32 v0, -v0, v25, v22
	v_div_fmas_f32 v0, v0, v20, v25
	v_div_fixup_f32 v40, v0, v40, v46
	v_mul_f32_e32 v0, 0xbfb8aa3b, v47
	v_exp_f32_e32 v25, v0
	v_mov_b32_e32 v22, v21
	v_pk_mul_f32 v[20:21], v[28:29], v[22:23]
	v_pk_mul_f32 v[40:41], v[42:43], v[40:41]
	v_pk_add_f32 v[22:23], v[24:25], 1.0 op_sel_hi:[1,0]
	v_mov_b32_e32 v28, v30
	v_div_scale_f32 v0, s[0:1], v23, v23, v47
	v_rcp_f32_e32 v24, v0
	v_mov_b32_e32 v29, v32
	v_fma_f32 v25, -v0, v24, 1.0
	v_fmac_f32_e32 v24, v25, v24
	v_div_scale_f32 v25, vcc, v47, v23, v47
	v_mul_f32_e32 v26, v25, v24
	v_fma_f32 v27, -v0, v26, v25
	v_fmac_f32_e32 v26, v27, v24
	v_fma_f32 v0, -v0, v26, v25
	v_div_fmas_f32 v0, v0, v24, v26
	v_div_fixup_f32 v23, v0, v23, v47
	v_div_scale_f32 v0, s[0:1], v22, v22, v48
	v_rcp_f32_e32 v24, v0
	s_nop 0
	v_fma_f32 v25, -v0, v24, 1.0
	v_fmac_f32_e32 v24, v25, v24
	v_div_scale_f32 v25, vcc, v48, v22, v48
	v_mul_f32_e32 v26, v25, v24
	v_fma_f32 v27, -v0, v26, v25
	v_fmac_f32_e32 v26, v27, v24
	v_fma_f32 v0, -v0, v26, v25
	v_div_fmas_f32 v0, v0, v24, v26
	v_div_fixup_f32 v22, v0, v22, v48
	v_pk_mul_f32 v[20:21], v[20:21], v[22:23]
	v_cvt_pk_bf16_f32 v21, v41, v21
	v_cvt_pk_bf16_f32 v20, v40, v20
	flat_store_dwordx2 v[18:19], v[20:21] offset:32
	flat_load_dwordx2 v[20:21], v[38:39] offset:1072
	s_nop 0
	global_load_dwordx4 v[22:25], v[36:37], off offset:96
	s_waitcnt vmcnt(0) lgkmcnt(0)
	v_lshlrev_b32_e32 v0, 16, v21
	v_lshlrev_b32_e32 v42, 16, v20
	v_mul_f32_e32 v26, 0xbfb8aa3b, v42
	v_and_b32_e32 v43, 0xffff0000, v21
	v_mul_f32_e32 v21, 0xbfb8aa3b, v0
	v_exp_f32_e32 v26, v26
	v_exp_f32_e32 v27, v21
	v_mov_b32_e32 v40, v22
	v_mov_b32_e32 v41, v24
	v_and_b32_e32 v44, 0xffff0000, v20
	v_pk_add_f32 v[26:27], v[26:27], 1.0 op_sel_hi:[1,0]
	v_mul_f32_e32 v20, 0xbfb8aa3b, v44
	v_div_scale_f32 v21, s[0:1], v27, v27, v0
	v_rcp_f32_e32 v22, v21
	v_exp_f32_e32 v20, v20
	v_pk_mul_f32 v[28:29], v[28:29], v[40:41]
	v_fma_f32 v24, -v21, v22, 1.0
	v_fmac_f32_e32 v22, v24, v22
	v_div_scale_f32 v24, vcc, v0, v27, v0
	v_mul_f32_e32 v30, v24, v22
	v_fma_f32 v32, -v21, v30, v24
	v_fmac_f32_e32 v30, v32, v22
	v_fma_f32 v21, -v21, v30, v24
	v_div_fmas_f32 v21, v21, v22, v30
	v_div_fixup_f32 v27, v21, v27, v0
	v_div_scale_f32 v0, s[0:1], v26, v26, v42
	v_rcp_f32_e32 v21, v0
	v_mov_b32_e32 v32, v31
	v_fma_f32 v22, -v0, v21, 1.0
	v_fmac_f32_e32 v21, v22, v21
	v_div_scale_f32 v22, vcc, v42, v26, v42
	v_mul_f32_e32 v24, v22, v21
	v_fma_f32 v30, -v0, v24, v22
	v_fmac_f32_e32 v24, v30, v21
	v_fma_f32 v0, -v0, v24, v22
	v_div_fmas_f32 v0, v0, v21, v24
	v_div_fixup_f32 v26, v0, v26, v42
	v_mul_f32_e32 v0, 0xbfb8aa3b, v43
	v_exp_f32_e32 v21, v0
	v_mov_b32_e32 v24, v23
	v_pk_mul_f32 v[22:23], v[32:33], v[24:25]
	v_pk_mul_f32 v[26:27], v[28:29], v[26:27]
	v_pk_add_f32 v[20:21], v[20:21], 1.0 op_sel_hi:[1,0]
	s_nop 0
	v_div_scale_f32 v0, s[0:1], v21, v21, v43
	v_rcp_f32_e32 v24, v0
	s_nop 0
	v_fma_f32 v25, -v0, v24, 1.0
	v_fmac_f32_e32 v24, v25, v24
	v_div_scale_f32 v25, vcc, v43, v21, v43
	v_mul_f32_e32 v28, v25, v24
	v_fma_f32 v29, -v0, v28, v25
	v_fmac_f32_e32 v28, v29, v24
	v_fma_f32 v0, -v0, v28, v25
	v_div_fmas_f32 v0, v0, v24, v28
	v_div_fixup_f32 v21, v0, v21, v43
	v_div_scale_f32 v0, s[0:1], v20, v20, v44
	v_rcp_f32_e32 v24, v0
	s_nop 0
	v_fma_f32 v25, -v0, v24, 1.0
	v_fmac_f32_e32 v24, v25, v24
	v_div_scale_f32 v25, vcc, v44, v20, v44
	v_mul_f32_e32 v28, v25, v24
	v_fma_f32 v29, -v0, v28, v25
	v_fmac_f32_e32 v28, v29, v24
	v_fma_f32 v0, -v0, v28, v25
	v_div_fmas_f32 v0, v0, v24, v28
	v_div_fixup_f32 v20, v0, v20, v44
	v_pk_mul_f32 v[20:21], v[22:23], v[20:21]
	v_cvt_pk_bf16_f32 v21, v27, v21
	v_cvt_pk_bf16_f32 v20, v26, v20
	flat_store_dwordx2 v[18:19], v[20:21] offset:48
	flat_load_dwordx2 v[20:21], v[38:39] offset:1088
	s_nop 0
	global_load_dwordx4 v[22:25], v[36:37], off offset:128
	v_mov_b32_e32 v28, v2
	v_mov_b32_e32 v29, v4
	s_waitcnt vmcnt(0) lgkmcnt(0)
; __device__ __forceinline__ unsigned pk2(float lo, float hi) { return f2bf(lo) | (f2bf(hi) << 16); }
; __device__ __forceinline__ float bflo(unsigned w) { return __uint_as_float(w << 16); }
; __device__ __forceinline__ float bfhi(unsigned w) { return __uint_as_float(w & 0xffff0000u); }
; __device__ __forceinline__ float silu(float x) { return x / (1.f + __expf(-x)); }
; __device__ __forceinline__ void pool_item(const Args& A, const Ctx& C0, int l, int row0, int t0, int pos0, const float* hist, float* outpool) {
;     ...
; #pragma unroll
;     for (int dt = 0; dt < 2; ++dt)
; #pragma unroll
;         for (int rq = 0; rq < 4; ++rq) { const int cc = g * 128 + ddh * 64 + dt * 32 + 8 * rq + 4 * h;
;             const v2u gx = *(const v2u*)(U + row * DIN + C_GP + cc); const f32x4 sc = *(const f32x4*)(psc + cc);
;             const float o0 = acc[dt][4 * rq] * sc.x * silu(bflo(gx.x)), o1 = acc[dt][4 * rq + 1] * sc.y * silu(bfhi(gx.x)), o2 = acc[dt][4 * rq + 2] * sc.z * silu(bflo(gx.y)), o3 = acc[dt][4 * rq + 3] * sc.w * silu(bfhi(gx.y));
;             v2u o; o.x = pk2(o0, o1); o.y = pk2(o2, o3);
;             *(v2u*)(MIX + row * D + cc) = o; }
	v_lshlrev_b32_e32 v0, 16, v21
	v_lshlrev_b32_e32 v32, 16, v20
	v_mul_f32_e32 v26, 0xbfb8aa3b, v32
	v_mul_f32_e32 v2, 0xbfb8aa3b, v0
	v_exp_f32_e32 v26, v26
	v_exp_f32_e32 v27, v2
	v_and_b32_e32 v33, 0xffff0000, v21
	v_mov_b32_e32 v30, v22
	v_mov_b32_e32 v31, v24
	v_pk_add_f32 v[26:27], v[26:27], 1.0 op_sel_hi:[1,0]
	v_and_b32_e32 v40, 0xffff0000, v20
	v_div_scale_f32 v2, s[0:1], v27, v27, v0
	v_rcp_f32_e32 v4, v2
	v_mul_f32_e32 v20, 0xbfb8aa3b, v40
	v_exp_f32_e32 v20, v20
	v_pk_mul_f32 v[28:29], v[28:29], v[30:31]
	v_fma_f32 v21, -v2, v4, 1.0
	v_fmac_f32_e32 v4, v21, v4
	v_div_scale_f32 v21, vcc, v0, v27, v0
	v_mul_f32_e32 v22, v21, v4
	v_fma_f32 v24, -v2, v22, v21
	v_fmac_f32_e32 v22, v24, v4
	v_fma_f32 v2, -v2, v22, v21
	v_div_fmas_f32 v2, v2, v4, v22
	v_div_fixup_f32 v27, v2, v27, v0
	v_div_scale_f32 v0, s[0:1], v26, v26, v32
	v_rcp_f32_e32 v2, v0
	v_mov_b32_e32 v24, v23
	v_fma_f32 v4, -v0, v2, 1.0
	v_fmac_f32_e32 v2, v4, v2
	v_div_scale_f32 v4, vcc, v32, v26, v32
	v_mul_f32_e32 v21, v4, v2
	v_fma_f32 v22, -v0, v21, v4
	v_fmac_f32_e32 v21, v22, v2
	v_fma_f32 v0, -v0, v21, v4
	v_div_fmas_f32 v0, v0, v2, v21
	v_div_fixup_f32 v26, v0, v26, v32
	v_mul_f32_e32 v0, 0xbfb8aa3b, v33
	v_exp_f32_e32 v21, v0
	v_mov_b32_e32 v4, v3
	v_pk_mul_f32 v[2:3], v[4:5], v[24:25]
	v_pk_mul_f32 v[26:27], v[28:29], v[26:27]
	v_pk_add_f32 v[4:5], v[20:21], 1.0 op_sel_hi:[1,0]
	v_mov_b32_e32 v24, v6
	v_div_scale_f32 v0, s[0:1], v5, v5, v33
	v_rcp_f32_e32 v20, v0
	v_mov_b32_e32 v25, v8
	v_fma_f32 v21, -v0, v20, 1.0
	v_fmac_f32_e32 v20, v21, v20
	v_div_scale_f32 v21, vcc, v33, v5, v33
	v_mul_f32_e32 v22, v21, v20
	v_fma_f32 v23, -v0, v22, v21
	v_fmac_f32_e32 v22, v23, v20
	v_fma_f32 v0, -v0, v22, v21
	v_div_fmas_f32 v0, v0, v20, v22
	v_div_fixup_f32 v5, v0, v5, v33
	v_div_scale_f32 v0, s[0:1], v4, v4, v40
	v_rcp_f32_e32 v20, v0
	s_nop 0
	v_fma_f32 v21, -v0, v20, 1.0
	v_fmac_f32_e32 v20, v21, v20
	v_div_scale_f32 v21, vcc, v40, v4, v40
	v_mul_f32_e32 v22, v21, v20
	v_fma_f32 v23, -v0, v22, v21
	v_fmac_f32_e32 v22, v23, v20
	v_fma_f32 v0, -v0, v22, v21
	v_div_fmas_f32 v0, v0, v20, v22
	v_div_fixup_f32 v4, v0, v4, v40
	v_pk_mul_f32 v[2:3], v[2:3], v[4:5]
	v_cvt_pk_bf16_f32 v3, v27, v3
	v_cvt_pk_bf16_f32 v2, v26, v2
	flat_store_dwordx2 v[18:19], v[2:3] offset:64
	flat_load_dwordx2 v[20:21], v[38:39] offset:1104
	s_nop 0
	global_load_dwordx4 v[2:5], v[36:37], off offset:160
	s_waitcnt vmcnt(0) lgkmcnt(0)
	v_lshlrev_b32_e32 v0, 16, v21
	v_lshlrev_b32_e32 v28, 16, v20
	v_mul_f32_e32 v22, 0xbfb8aa3b, v28
	v_mov_b32_e32 v26, v2
	v_mul_f32_e32 v2, 0xbfb8aa3b, v0
	v_exp_f32_e32 v22, v22
	v_exp_f32_e32 v23, v2
	v_mov_b32_e32 v27, v4
	v_and_b32_e32 v29, 0xffff0000, v21
	v_and_b32_e32 v30, 0xffff0000, v20
	v_pk_add_f32 v[22:23], v[22:23], 1.0 op_sel_hi:[1,0]
	v_mul_f32_e32 v20, 0xbfb8aa3b, v30
	v_div_scale_f32 v2, s[0:1], v23, v23, v0
	v_rcp_f32_e32 v4, v2
	v_exp_f32_e32 v20, v20
	v_pk_mul_f32 v[24:25], v[24:25], v[26:27]
	v_fma_f32 v6, -v2, v4, 1.0
	v_fmac_f32_e32 v4, v6, v4
	v_div_scale_f32 v6, vcc, v0, v23, v0
	v_mul_f32_e32 v8, v6, v4
	v_fma_f32 v21, -v2, v8, v6
	v_fmac_f32_e32 v8, v21, v4
	v_fma_f32 v2, -v2, v8, v6
	v_div_fmas_f32 v2, v2, v4, v8
	v_div_fixup_f32 v23, v2, v23, v0
	v_div_scale_f32 v0, s[0:1], v22, v22, v28
	v_rcp_f32_e32 v2, v0
	s_nop 0
	v_fma_f32 v4, -v0, v2, 1.0
	v_fmac_f32_e32 v2, v4, v2
	v_div_scale_f32 v4, vcc, v28, v22, v28
	v_mul_f32_e32 v6, v4, v2
	v_fma_f32 v8, -v0, v6, v4
	v_fmac_f32_e32 v6, v8, v2
	v_fma_f32 v0, -v0, v6, v4
	v_div_fmas_f32 v0, v0, v2, v6
	v_div_fixup_f32 v22, v0, v22, v28
	v_mul_f32_e32 v0, 0xbfb8aa3b, v29
	v_exp_f32_e32 v21, v0
	v_mov_b32_e32 v8, v7
	v_mov_b32_e32 v4, v3
	v_pk_mul_f32 v[2:3], v[8:9], v[4:5]
	v_pk_add_f32 v[4:5], v[20:21], 1.0 op_sel_hi:[1,0]
	v_pk_mul_f32 v[22:23], v[24:25], v[22:23]
	v_div_scale_f32 v0, s[0:1], v5, v5, v29
	v_rcp_f32_e32 v6, v0
	v_mov_b32_e32 v20, v10
	v_mov_b32_e32 v21, v12
	v_fma_f32 v7, -v0, v6, 1.0
	v_fmac_f32_e32 v6, v7, v6
	v_div_scale_f32 v7, vcc, v29, v5, v29
	v_mul_f32_e32 v8, v7, v6
	v_fma_f32 v9, -v0, v8, v7
	v_fmac_f32_e32 v8, v9, v6
	v_fma_f32 v0, -v0, v8, v7
	v_div_fmas_f32 v0, v0, v6, v8
	v_div_fixup_f32 v5, v0, v5, v29
	v_div_scale_f32 v0, s[0:1], v4, v4, v30
	v_rcp_f32_e32 v6, v0
	s_nop 0
	v_fma_f32 v7, -v0, v6, 1.0
	v_fmac_f32_e32 v6, v7, v6
	v_div_scale_f32 v7, vcc, v30, v4, v30
	v_mul_f32_e32 v8, v7, v6
	v_fma_f32 v9, -v0, v8, v7
	v_fmac_f32_e32 v8, v9, v6
	v_fma_f32 v0, -v0, v8, v7
	v_div_fmas_f32 v0, v0, v6, v8
	v_div_fixup_f32 v4, v0, v4, v30
	v_pk_mul_f32 v[2:3], v[2:3], v[4:5]
	v_cvt_pk_bf16_f32 v3, v23, v3
	v_cvt_pk_bf16_f32 v2, v22, v2
	flat_store_dwordx2 v[18:19], v[2:3] offset:80
	flat_load_dwordx2 v[6:7], v[38:39] offset:1120
	s_nop 0
	global_load_dwordx4 v[2:5], v[36:37], off offset:192
	s_waitcnt vmcnt(0) lgkmcnt(0)
; __device__ __forceinline__ unsigned pk2(float lo, float hi) { return f2bf(lo) | (f2bf(hi) << 16); }
; __device__ __forceinline__ float bflo(unsigned w) { return __uint_as_float(w << 16); }
; __device__ __forceinline__ float bfhi(unsigned w) { return __uint_as_float(w & 0xffff0000u); }
; __device__ __forceinline__ float bf1(bf16 h) { return __uint_as_float(((unsigned)h) << 16); }
; __device__ __forceinline__ float silu(float x) { return x / (1.f + __expf(-x)); }
; __device__ __forceinline__ void pool_item(const Args& A, const Ctx& C0, int l, int row0, int t0, int pos0, const float* hist, float* outpool) {
;     ...
; #pragma unroll
;     for (int dt = 0; dt < 2; ++dt)
; #pragma unroll
;         for (int rq = 0; rq < 4; ++rq) { const int cc = g * 128 + ddh * 64 + dt * 32 + 8 * rq + 4 * h;
;             const v2u gx = *(const v2u*)(U + row * DIN + C_GP + cc); const f32x4 sc = *(const f32x4*)(psc + cc);
;             const float o0 = acc[dt][4 * rq] * sc.x * silu(bflo(gx.x)), o1 = acc[dt][4 * rq + 1] * sc.y * silu(bfhi(gx.x)), o2 = acc[dt][4 * rq + 2] * sc.z * silu(bflo(gx.y)), o3 = acc[dt][4 * rq + 3] * sc.w * silu(bfhi(gx.y));
;             v2u o; o.x = pk2(o0, o1); o.y = pk2(o2, o3);
;             *(v2u*)(MIX + row * D + cc) = o; }
;     if (outpool) for (int idx = C.tid; idx < 15 * 512; idx += 512) { const int rr = idx >> 9, cc = idx & 511; outpool[idx] = bf1(P[(32 + rr) * PP + cc]); }
	v_lshlrev_b32_e32 v0, 16, v7
	v_lshlrev_b32_e32 v24, 16, v6
	v_mul_f32_e32 v8, 0xbfb8aa3b, v24
	v_mov_b32_e32 v22, v2
	v_mul_f32_e32 v2, 0xbfb8aa3b, v0
	v_exp_f32_e32 v8, v8
	v_exp_f32_e32 v9, v2
	v_mov_b32_e32 v23, v4
	v_and_b32_e32 v25, 0xffff0000, v7
	v_and_b32_e32 v26, 0xffff0000, v6
	v_pk_add_f32 v[8:9], v[8:9], 1.0 op_sel_hi:[1,0]
	v_mul_f32_e32 v6, 0xbfb8aa3b, v26
	v_div_scale_f32 v2, s[0:1], v9, v9, v0
	v_rcp_f32_e32 v4, v2
	v_exp_f32_e32 v6, v6
	v_pk_mul_f32 v[20:21], v[20:21], v[22:23]
	v_fma_f32 v7, -v2, v4, 1.0
	v_fmac_f32_e32 v4, v7, v4
	v_div_scale_f32 v7, vcc, v0, v9, v0
	v_mul_f32_e32 v10, v7, v4
	v_fma_f32 v12, -v2, v10, v7
	v_fmac_f32_e32 v10, v12, v4
	v_fma_f32 v2, -v2, v10, v7
	v_div_fmas_f32 v2, v2, v4, v10
	v_div_fixup_f32 v9, v2, v9, v0
	v_div_scale_f32 v0, s[0:1], v8, v8, v24
	v_rcp_f32_e32 v2, v0
	v_mov_b32_e32 v12, v11
	v_fma_f32 v4, -v0, v2, 1.0
	v_fmac_f32_e32 v2, v4, v2
	v_div_scale_f32 v4, vcc, v24, v8, v24
	v_mul_f32_e32 v7, v4, v2
	v_fma_f32 v10, -v0, v7, v4
	v_fmac_f32_e32 v7, v10, v2
	v_fma_f32 v0, -v0, v7, v4
	v_div_fmas_f32 v0, v0, v2, v7
	v_div_fixup_f32 v8, v0, v8, v24
	v_mul_f32_e32 v0, 0xbfb8aa3b, v25
	v_exp_f32_e32 v7, v0
	v_mov_b32_e32 v4, v3
	v_pk_mul_f32 v[2:3], v[12:13], v[4:5]
	v_pk_mul_f32 v[8:9], v[20:21], v[8:9]
	v_pk_add_f32 v[4:5], v[6:7], 1.0 op_sel_hi:[1,0]
	s_nop 0
	v_div_scale_f32 v0, s[0:1], v5, v5, v25
	v_rcp_f32_e32 v6, v0
	s_nop 0
	v_fma_f32 v7, -v0, v6, 1.0
	v_fmac_f32_e32 v6, v7, v6
	v_div_scale_f32 v7, vcc, v25, v5, v25
	v_mul_f32_e32 v10, v7, v6
	v_fma_f32 v11, -v0, v10, v7
	v_fmac_f32_e32 v10, v11, v6
	v_fma_f32 v0, -v0, v10, v7
	v_div_fmas_f32 v0, v0, v6, v10
	v_div_fixup_f32 v5, v0, v5, v25
	v_div_scale_f32 v0, s[0:1], v4, v4, v26
	v_rcp_f32_e32 v6, v0
	s_nop 0
	v_fma_f32 v7, -v0, v6, 1.0
	v_fmac_f32_e32 v6, v7, v6
	v_div_scale_f32 v7, vcc, v26, v4, v26
	v_mul_f32_e32 v10, v7, v6
	v_fma_f32 v11, -v0, v10, v7
	v_fmac_f32_e32 v10, v11, v6
	v_fma_f32 v0, -v0, v10, v7
	v_div_fmas_f32 v0, v0, v6, v10
	v_div_fixup_f32 v4, v0, v4, v26
	v_pk_mul_f32 v[2:3], v[2:3], v[4:5]
	v_cvt_pk_bf16_f32 v3, v9, v3
	v_cvt_pk_bf16_f32 v2, v8, v2
	flat_store_dwordx2 v[18:19], v[2:3] offset:96
	flat_load_dwordx2 v[2:3], v[38:39] offset:1136
	s_nop 0
	global_load_dwordx4 v[4:7], v[36:37], off offset:224
	v_mov_b32_e32 v10, v14
	v_mov_b32_e32 v11, v16
	v_mov_b32_e32 v16, v15
	s_waitcnt vmcnt(0) lgkmcnt(0)
	v_lshlrev_b32_e32 v0, 16, v3
	v_lshlrev_b32_e32 v20, 16, v2
	v_mul_f32_e32 v8, 0xbfb8aa3b, v20
	v_and_b32_e32 v21, 0xffff0000, v3
	v_mul_f32_e32 v3, 0xbfb8aa3b, v0
	v_exp_f32_e32 v8, v8
	v_exp_f32_e32 v9, v3
	v_mov_b32_e32 v12, v4
	v_mov_b32_e32 v13, v6
	v_pk_mul_f32 v[10:11], v[10:11], v[12:13]
	v_pk_add_f32 v[8:9], v[8:9], 1.0 op_sel_hi:[1,0]
	v_and_b32_e32 v22, 0xffff0000, v2
	v_div_scale_f32 v3, s[0:1], v9, v9, v0
	v_rcp_f32_e32 v4, v3
	v_mul_f32_e32 v2, 0xbfb8aa3b, v22
	v_exp_f32_e32 v2, v2
	v_fma_f32 v6, -v3, v4, 1.0
	v_fmac_f32_e32 v4, v6, v4
	v_div_scale_f32 v6, vcc, v0, v9, v0
	v_mul_f32_e32 v12, v6, v4
	v_fma_f32 v13, -v3, v12, v6
	v_fmac_f32_e32 v12, v13, v4
	v_fma_f32 v3, -v3, v12, v6
	v_div_fmas_f32 v3, v3, v4, v12
	v_div_fixup_f32 v9, v3, v9, v0
	v_div_scale_f32 v0, s[0:1], v8, v8, v20
	v_rcp_f32_e32 v3, v0
	s_nop 0
	v_fma_f32 v4, -v0, v3, 1.0
	v_fmac_f32_e32 v3, v4, v3
	v_div_scale_f32 v4, vcc, v20, v8, v20
	v_mul_f32_e32 v6, v4, v3
	v_fma_f32 v12, -v0, v6, v4
	v_fmac_f32_e32 v6, v12, v3
	v_fma_f32 v0, -v0, v6, v4
	v_div_fmas_f32 v0, v0, v3, v6
	v_div_fixup_f32 v8, v0, v8, v20
	v_mul_f32_e32 v0, 0xbfb8aa3b, v21
	v_exp_f32_e32 v3, v0
	v_mov_b32_e32 v6, v5
	v_pk_mul_f32 v[4:5], v[16:17], v[6:7]
	v_pk_mul_f32 v[8:9], v[10:11], v[8:9]
	v_pk_add_f32 v[2:3], v[2:3], 1.0 op_sel_hi:[1,0]
	s_nop 0
	v_div_scale_f32 v0, s[0:1], v3, v3, v21
	v_rcp_f32_e32 v6, v0
	s_nop 0
	v_fma_f32 v7, -v0, v6, 1.0
	v_fmac_f32_e32 v6, v7, v6
	v_div_scale_f32 v7, vcc, v21, v3, v21
	v_mul_f32_e32 v10, v7, v6
	v_fma_f32 v11, -v0, v10, v7
	v_fmac_f32_e32 v10, v11, v6
	v_fma_f32 v0, -v0, v10, v7
	v_div_fmas_f32 v0, v0, v6, v10
	v_div_fixup_f32 v3, v0, v3, v21
	v_div_scale_f32 v0, s[0:1], v2, v2, v22
	v_rcp_f32_e32 v6, v0
	s_cselect_b64 s[0:1], -1, 0
	v_fma_f32 v7, -v0, v6, 1.0
	v_fmac_f32_e32 v6, v7, v6
	v_div_scale_f32 v7, vcc, v22, v2, v22
	v_mul_f32_e32 v10, v7, v6
	v_fma_f32 v11, -v0, v10, v7
	v_fmac_f32_e32 v10, v11, v6
	v_fma_f32 v0, -v0, v10, v7
	v_div_fmas_f32 v0, v0, v6, v10
	v_div_fixup_f32 v2, v0, v2, v22
	v_pk_mul_f32 v[2:3], v[4:5], v[2:3]
	v_cmp_gt_i32_e32 vcc, s2, v34
	v_cvt_pk_bf16_f32 v3, v9, v3
	v_cvt_pk_bf16_f32 v2, v8, v2
	s_and_b64 s[2:3], s[0:1], vcc
	flat_store_dwordx2 v[18:19], v[2:3] offset:112
	s_and_saveexec_b64 s[0:1], s[2:3]
	s_cbranch_execz .LBB0_263
	v_max_i32_e32 v2, 0x1c00, v34
	v_sub_u32_e32 v2, v2, v34
	v_and_b32_e32 v0, 0x1ff, v34
	v_add_u32_e32 v2, 0x1ff, v2
	s_movk_i32 s2, 0x1ff
	v_cmp_lt_u32_e32 vcc, s2, v2
	s_mov_b64 s[2:3], -1
	v_lshl_add_u32 v0, v0, 1, 0
	s_and_saveexec_b64 s[24:25], vcc
	s_cbranch_execz .LBB0_260
	v_lshrrev_b32_e32 v2, 9, v2
	v_add_u32_e32 v4, 1, v2
	v_and_b32_e32 v5, 0xfffffe, v4
	s_mov_b64 s[30:31], 0
	v_mov_b32_e32 v6, v5
	v_mov_b64_e32 v[2:3], v[34:35]
	s_movk_i32 s2, 0x410

; __device__ __forceinline__ unsigned pk2(float lo, float hi) { return f2bf(lo) | (f2bf(hi) << 16); }
; __device__ __forceinline__ float bflo(unsigned w) { return __uint_as_float(w << 16); }
; __device__ __forceinline__ float bfhi(unsigned w) { return __uint_as_float(w & 0xffff0000u); }
; __device__ __forceinline__ float silu(float x) { return x / (1.f + __expf(-x)); }
; __device__ __forceinline__ void attn_unit(const Args& A, const Ctx& C0, int l, int u_qrow0, int u_nq, int u_krow0, int u_krow1, int u_krow2, int u_g, const float* u_ck, const float* u_cv, unsigned u_vmask) {
;     ...
;         const size_t row = (size_t)(u.qrow0 + qi);
; #pragma unroll
;         for (int dt = 0; dt < 2; ++dt)
; #pragma unroll
;             for (int rq = 0; rq < 4; ++rq) { const int d = dt * 32 + 8 * rq + 4 * h;
;                 const v2u gx = gxa[qt][dt][rq];
;                 const float o0 = oacc[dt][4 * rq] * silu(bflo(gx.x)), o1 = oacc[dt][4 * rq + 1] * silu(bfhi(gx.x)), o2 = oacc[dt][4 * rq + 2] * silu(bflo(gx.y)), o3 = oacc[dt][4 * rq + 3] * silu(bfhi(gx.y));
;                 v2u o; o.x = pk2(o0, o1); o.y = pk2(o2, o3);
;                 *(v2u*)(MIX + row * D + 512 + hq * 64 + d) = o; }
.LBB0_492:
	v_lshlrev_b32_e32 v0, 12, v184
	v_and_b32_e32 v43, 0xffff0000, v162
	v_lshl_add_u64 v[34:35], s[0:1], 0, v[0:1]
	v_lshlrev_b32_e32 v0, 16, v163
	v_lshlrev_b32_e32 v39, 16, v162
	v_mul_f32_e32 v37, 0xbfb8aa3b, v43
	v_mul_f32_e32 v36, 0xbfb8aa3b, v39
	v_exp_f32_e32 v38, v37
	v_mul_f32_e32 v37, 0xbfb8aa3b, v0
	v_exp_f32_e32 v36, v36
	v_exp_f32_e32 v37, v37
	v_and_b32_e32 v42, 0xffff0000, v163
	v_lshl_add_u64 v[34:35], s[58:59], 1, v[34:35]
	v_pk_add_f32 v[36:37], v[36:37], 1.0 op_sel_hi:[1,0]
	s_nop 0
	v_div_scale_f32 v40, s[2:3], v37, v37, v0
	v_rcp_f32_e32 v41, v40
	s_nop 0
	v_fma_f32 v44, -v40, v41, 1.0
	v_fmac_f32_e32 v41, v44, v41
	v_div_scale_f32 v44, vcc, v0, v37, v0
	v_mul_f32_e32 v45, v44, v41
	v_fma_f32 v46, -v40, v45, v44
	v_fmac_f32_e32 v45, v46, v41
	v_fma_f32 v40, -v40, v45, v44
	v_div_fmas_f32 v40, v40, v41, v45
	v_div_fixup_f32 v37, v40, v37, v0
	v_div_scale_f32 v0, s[2:3], v36, v36, v39
	v_rcp_f32_e32 v40, v0
	s_nop 0
	v_fma_f32 v41, -v0, v40, 1.0
	v_fmac_f32_e32 v40, v41, v40
	v_div_scale_f32 v41, vcc, v39, v36, v39
	v_mul_f32_e32 v44, v41, v40
	v_fma_f32 v45, -v0, v44, v41
	v_fmac_f32_e32 v44, v45, v40
	v_fma_f32 v0, -v0, v44, v41
	v_div_fmas_f32 v0, v0, v40, v44
	v_div_fixup_f32 v36, v0, v36, v39
	v_mul_f32_e32 v0, 0xbfb8aa3b, v42
	v_exp_f32_e32 v39, v0
	v_mov_b32_e32 v40, v18
	v_mov_b32_e32 v41, v20
	v_pk_mul_f32 v[36:37], v[36:37], v[40:41]
	v_pk_add_f32 v[38:39], v[38:39], 1.0 op_sel_hi:[1,0]
	s_nop 0
	v_div_scale_f32 v0, s[2:3], v39, v39, v42
	v_rcp_f32_e32 v18, v0
	s_nop 0
	v_fma_f32 v20, -v0, v18, 1.0
	v_fmac_f32_e32 v18, v20, v18
	v_div_scale_f32 v20, vcc, v42, v39, v42
	v_mul_f32_e32 v40, v20, v18
	v_fma_f32 v41, -v0, v40, v20
	v_fmac_f32_e32 v40, v41, v18
	v_fma_f32 v0, -v0, v40, v20
	v_div_fmas_f32 v0, v0, v18, v40
	v_div_fixup_f32 v39, v0, v39, v42
	v_div_scale_f32 v0, s[2:3], v38, v38, v43
	v_rcp_f32_e32 v18, v0
	s_mov_b64 s[2:3], 0x7b27d00
	v_fma_f32 v20, -v0, v18, 1.0
	v_fmac_f32_e32 v18, v20, v18
	v_div_scale_f32 v20, vcc, v43, v38, v43
	v_mul_f32_e32 v40, v20, v18
	v_fma_f32 v41, -v0, v40, v20
	v_fmac_f32_e32 v40, v41, v18
	v_fma_f32 v0, -v0, v40, v20
	v_div_fmas_f32 v0, v0, v18, v40
	v_div_fixup_f32 v38, v0, v38, v43
	v_mov_b32_e32 v20, v19
	v_pk_mul_f32 v[18:19], v[38:39], v[20:21]
	v_cvt_pk_bf16_f32 v21, v37, v19
	v_lshlrev_b32_e32 v0, 1, v191
	v_lshl_add_u64 v[34:35], v[34:35], 0, v[0:1]
	v_cvt_pk_bf16_f32 v20, v36, v18
	v_lshl_add_u64 v[18:19], v[34:35], 0, s[2:3]
	s_mov_b32 s2, 0x7b27000
	v_add_co_u32_e32 v34, vcc, s2, v34
	v_and_b32_e32 v39, 0xffff0000, v160
	s_nop 0
	v_addc_co_u32_e32 v35, vcc, 0, v35, vcc
	flat_store_dwordx2 v[34:35], v[20:21] offset:3328
	v_lshlrev_b32_e32 v35, 16, v161
	v_lshlrev_b32_e32 v36, 16, v160
	v_mul_f32_e32 v21, 0xbfb8aa3b, v39
	v_mul_f32_e32 v20, 0xbfb8aa3b, v36
	v_exp_f32_e32 v34, v21
	v_mul_f32_e32 v21, 0xbfb8aa3b, v35
	v_exp_f32_e32 v20, v20
	v_exp_f32_e32 v21, v21
	v_and_b32_e32 v38, 0xffff0000, v161
	v_pk_add_f32 v[20:21], v[20:21], 1.0 op_sel_hi:[1,0]
	s_nop 0
	v_div_scale_f32 v37, s[2:3], v21, v21, v35
	v_rcp_f32_e32 v40, v37
	s_nop 0
	v_fma_f32 v41, -v37, v40, 1.0
	v_fmac_f32_e32 v40, v41, v40
	v_div_scale_f32 v41, vcc, v35, v21, v35
	v_mul_f32_e32 v42, v41, v40
	v_fma_f32 v43, -v37, v42, v41
	v_fmac_f32_e32 v42, v43, v40
	v_fma_f32 v37, -v37, v42, v41
	v_div_fmas_f32 v37, v37, v40, v42
	v_div_fixup_f32 v21, v37, v21, v35
	v_div_scale_f32 v35, s[2:3], v20, v20, v36
	v_rcp_f32_e32 v37, v35
	s_nop 0
	v_fma_f32 v40, -v35, v37, 1.0
	v_fmac_f32_e32 v37, v40, v37
	v_div_scale_f32 v40, vcc, v36, v20, v36
	v_mul_f32_e32 v41, v40, v37
	v_fma_f32 v42, -v35, v41, v40
	v_fmac_f32_e32 v41, v42, v37
	v_fma_f32 v35, -v35, v41, v40
	v_div_fmas_f32 v35, v35, v37, v41
	v_div_fixup_f32 v20, v35, v20, v36
	v_mov_b32_e32 v36, v22
	v_mul_f32_e32 v22, 0xbfb8aa3b, v38
	v_exp_f32_e32 v35, v22
	v_mov_b32_e32 v37, v24
	v_pk_mul_f32 v[20:21], v[20:21], v[36:37]
	v_pk_add_f32 v[34:35], v[34:35], 1.0 op_sel_hi:[1,0]
	s_nop 0
	v_div_scale_f32 v22, s[2:3], v35, v35, v38
	v_rcp_f32_e32 v24, v22
	s_nop 0
	v_fma_f32 v36, -v22, v24, 1.0
	v_fmac_f32_e32 v24, v36, v24
	v_div_scale_f32 v36, vcc, v38, v35, v38
	v_mul_f32_e32 v37, v36, v24
	v_fma_f32 v40, -v22, v37, v36
	v_fmac_f32_e32 v37, v40, v24
	v_fma_f32 v22, -v22, v37, v36
	v_div_fmas_f32 v22, v22, v24, v37
	v_div_fixup_f32 v35, v22, v35, v38
	v_div_scale_f32 v22, s[2:3], v34, v34, v39
	v_rcp_f32_e32 v24, v22
	s_nop 0
	v_fma_f32 v36, -v22, v24, 1.0
	v_fmac_f32_e32 v24, v36, v24
	v_div_scale_f32 v36, vcc, v39, v34, v39
	v_mul_f32_e32 v37, v36, v24
	v_fma_f32 v38, -v22, v37, v36
	v_fmac_f32_e32 v37, v38, v24
	v_fma_f32 v22, -v22, v37, v36
	v_div_fmas_f32 v22, v22, v24, v37
	v_div_fixup_f32 v34, v22, v34, v39
	v_mov_b32_e32 v24, v23
	v_pk_mul_f32 v[22:23], v[34:35], v[24:25]
	v_cvt_pk_bf16_f32 v21, v21, v23
	v_cvt_pk_bf16_f32 v20, v20, v22
	v_and_b32_e32 v35, 0xffff0000, v158
	flat_store_dwordx2 v[18:19], v[20:21] offset:16
	v_lshlrev_b32_e32 v23, 16, v159
	v_lshlrev_b32_e32 v24, 16, v158
	v_mul_f32_e32 v21, 0xbfb8aa3b, v35
	v_mul_f32_e32 v20, 0xbfb8aa3b, v24
	v_exp_f32_e32 v22, v21
	v_mul_f32_e32 v21, 0xbfb8aa3b, v23
	v_exp_f32_e32 v20, v20
	v_exp_f32_e32 v21, v21
	v_and_b32_e32 v34, 0xffff0000, v159
	v_pk_add_f32 v[20:21], v[20:21], 1.0 op_sel_hi:[1,0]
	s_nop 0
	v_div_scale_f32 v25, s[2:3], v21, v21, v23
	v_rcp_f32_e32 v36, v25
	s_nop 0
	v_fma_f32 v37, -v25, v36, 1.0
	v_fmac_f32_e32 v36, v37, v36
	v_div_scale_f32 v37, vcc, v23, v21, v23
	v_mul_f32_e32 v38, v37, v36
	v_fma_f32 v39, -v25, v38, v37
	v_fmac_f32_e32 v38, v39, v36
	v_fma_f32 v25, -v25, v38, v37
	v_div_fmas_f32 v25, v25, v36, v38
	v_div_fixup_f32 v21, v25, v21, v23
; __device__ __forceinline__ unsigned pk2(float lo, float hi) { return f2bf(lo) | (f2bf(hi) << 16); }
; __device__ __forceinline__ float bflo(unsigned w) { return __uint_as_float(w << 16); }
; __device__ __forceinline__ float bfhi(unsigned w) { return __uint_as_float(w & 0xffff0000u); }
; __device__ __forceinline__ float silu(float x) { return x / (1.f + __expf(-x)); }
; __device__ __forceinline__ void attn_unit(const Args& A, const Ctx& C0, int l, int u_qrow0, int u_nq, int u_krow0, int u_krow1, int u_krow2, int u_g, const float* u_ck, const float* u_cv, unsigned u_vmask) {
;     ...
;         const size_t row = (size_t)(u.qrow0 + qi);
; #pragma unroll
;         for (int dt = 0; dt < 2; ++dt)
; #pragma unroll
;             for (int rq = 0; rq < 4; ++rq) { const int d = dt * 32 + 8 * rq + 4 * h;
;                 const v2u gx = gxa[qt][dt][rq];
;                 const float o0 = oacc[dt][4 * rq] * silu(bflo(gx.x)), o1 = oacc[dt][4 * rq + 1] * silu(bfhi(gx.x)), o2 = oacc[dt][4 * rq + 2] * silu(bflo(gx.y)), o3 = oacc[dt][4 * rq + 3] * silu(bfhi(gx.y));
;                 v2u o; o.x = pk2(o0, o1); o.y = pk2(o2, o3);
;                 *(v2u*)(MIX + row * D + 512 + hq * 64 + d) = o; }
	v_div_scale_f32 v23, s[2:3], v20, v20, v24
	v_rcp_f32_e32 v25, v23
	s_nop 0
	v_fma_f32 v36, -v23, v25, 1.0
	v_fmac_f32_e32 v25, v36, v25
	v_div_scale_f32 v36, vcc, v24, v20, v24
	v_mul_f32_e32 v37, v36, v25
	v_fma_f32 v38, -v23, v37, v36
	v_fmac_f32_e32 v37, v38, v25
	v_fma_f32 v23, -v23, v37, v36
	v_div_fmas_f32 v23, v23, v25, v37
	v_div_fixup_f32 v20, v23, v20, v24
	v_mul_f32_e32 v23, 0xbfb8aa3b, v34
	v_exp_f32_e32 v23, v23
	v_mov_b32_e32 v24, v26
	v_mov_b32_e32 v25, v28
	v_pk_mul_f32 v[20:21], v[20:21], v[24:25]
	v_pk_add_f32 v[22:23], v[22:23], 1.0 op_sel_hi:[1,0]
	s_nop 0
	v_div_scale_f32 v24, s[2:3], v23, v23, v34
	v_rcp_f32_e32 v25, v24
	s_nop 0
	v_fma_f32 v26, -v24, v25, 1.0
	v_fmac_f32_e32 v25, v26, v25
	v_div_scale_f32 v26, vcc, v34, v23, v34
	v_mul_f32_e32 v28, v26, v25
	v_fma_f32 v36, -v24, v28, v26
	v_fmac_f32_e32 v28, v36, v25
	v_fma_f32 v24, -v24, v28, v26
	v_div_fmas_f32 v24, v24, v25, v28
	v_div_fixup_f32 v23, v24, v23, v34
	v_div_scale_f32 v24, s[2:3], v22, v22, v35
	v_rcp_f32_e32 v25, v24
	s_nop 0
	v_fma_f32 v26, -v24, v25, 1.0
	v_fmac_f32_e32 v25, v26, v25
	v_div_scale_f32 v26, vcc, v35, v22, v35
	v_mul_f32_e32 v28, v26, v25
	v_fma_f32 v34, -v24, v28, v26
	v_fmac_f32_e32 v28, v34, v25
	v_fma_f32 v24, -v24, v28, v26
	v_div_fmas_f32 v24, v24, v25, v28
	v_div_fixup_f32 v22, v24, v22, v35
	v_mov_b32_e32 v28, v27
	v_pk_mul_f32 v[22:23], v[22:23], v[28:29]
	v_cvt_pk_bf16_f32 v21, v21, v23
	v_cvt_pk_bf16_f32 v20, v20, v22
	v_and_b32_e32 v27, 0xffff0000, v156
	flat_store_dwordx2 v[18:19], v[20:21] offset:32
	v_lshlrev_b32_e32 v23, 16, v157
	v_lshlrev_b32_e32 v24, 16, v156
	v_mul_f32_e32 v21, 0xbfb8aa3b, v27
	v_mul_f32_e32 v20, 0xbfb8aa3b, v24
	v_exp_f32_e32 v22, v21
	v_mul_f32_e32 v21, 0xbfb8aa3b, v23
	v_exp_f32_e32 v20, v20
	v_exp_f32_e32 v21, v21
	v_and_b32_e32 v26, 0xffff0000, v157
	v_pk_add_f32 v[20:21], v[20:21], 1.0 op_sel_hi:[1,0]
	s_nop 0
	v_div_scale_f32 v25, s[2:3], v21, v21, v23
	v_rcp_f32_e32 v28, v25
	s_nop 0
	v_fma_f32 v29, -v25, v28, 1.0
	v_fmac_f32_e32 v28, v29, v28
	v_div_scale_f32 v29, vcc, v23, v21, v23
	v_mul_f32_e32 v34, v29, v28
	v_fma_f32 v35, -v25, v34, v29
	v_fmac_f32_e32 v34, v35, v28
	v_fma_f32 v25, -v25, v34, v29
	v_div_fmas_f32 v25, v25, v28, v34
	v_div_fixup_f32 v21, v25, v21, v23
	v_div_scale_f32 v23, s[2:3], v20, v20, v24
	v_rcp_f32_e32 v25, v23
	s_nop 0
	v_fma_f32 v28, -v23, v25, 1.0
	v_fmac_f32_e32 v25, v28, v25
	v_div_scale_f32 v28, vcc, v24, v20, v24
	v_mul_f32_e32 v29, v28, v25
	v_fma_f32 v34, -v23, v29, v28
	v_fmac_f32_e32 v29, v34, v25
	v_fma_f32 v23, -v23, v29, v28
	v_div_fmas_f32 v23, v23, v25, v29
	v_div_fixup_f32 v20, v23, v20, v24
	v_mul_f32_e32 v23, 0xbfb8aa3b, v26
	v_exp_f32_e32 v23, v23
	v_mov_b32_e32 v24, v30
	v_mov_b32_e32 v25, v32
	v_pk_mul_f32 v[20:21], v[20:21], v[24:25]
	v_pk_add_f32 v[22:23], v[22:23], 1.0 op_sel_hi:[1,0]
	v_mov_b32_e32 v32, v31
	v_div_scale_f32 v24, s[2:3], v23, v23, v26
	v_rcp_f32_e32 v25, v24
	s_nop 0
	v_fma_f32 v28, -v24, v25, 1.0
	v_fmac_f32_e32 v25, v28, v25
	v_div_scale_f32 v28, vcc, v26, v23, v26
	v_mul_f32_e32 v29, v28, v25
	v_fma_f32 v30, -v24, v29, v28
	v_fmac_f32_e32 v29, v30, v25
	v_fma_f32 v24, -v24, v29, v28
	v_div_fmas_f32 v24, v24, v25, v29
	v_div_fixup_f32 v23, v24, v23, v26
	v_div_scale_f32 v24, s[2:3], v22, v22, v27
	v_rcp_f32_e32 v25, v24
	s_nop 0
	v_fma_f32 v26, -v24, v25, 1.0
	v_fmac_f32_e32 v25, v26, v25
	v_div_scale_f32 v26, vcc, v27, v22, v27
	v_mul_f32_e32 v28, v26, v25
	v_fma_f32 v29, -v24, v28, v26
	v_fmac_f32_e32 v28, v29, v25
	v_fma_f32 v24, -v24, v28, v26
	v_div_fmas_f32 v24, v24, v25, v28
	v_div_fixup_f32 v22, v24, v22, v27
	v_pk_mul_f32 v[22:23], v[22:23], v[32:33]
	v_cvt_pk_bf16_f32 v21, v21, v23
	v_cvt_pk_bf16_f32 v20, v20, v22
	v_and_b32_e32 v27, 0xffff0000, v154
	flat_store_dwordx2 v[18:19], v[20:21] offset:48
	v_lshlrev_b32_e32 v23, 16, v155
	v_lshlrev_b32_e32 v24, 16, v154
	v_mul_f32_e32 v21, 0xbfb8aa3b, v27
	v_mul_f32_e32 v20, 0xbfb8aa3b, v24
	v_exp_f32_e32 v22, v21
	v_mul_f32_e32 v21, 0xbfb8aa3b, v23
	v_exp_f32_e32 v20, v20
	v_exp_f32_e32 v21, v21
	v_and_b32_e32 v26, 0xffff0000, v155
	v_pk_add_f32 v[20:21], v[20:21], 1.0 op_sel_hi:[1,0]
	s_nop 0
	v_div_scale_f32 v25, s[2:3], v21, v21, v23
	v_rcp_f32_e32 v28, v25
	s_nop 0
	v_fma_f32 v29, -v25, v28, 1.0
	v_fmac_f32_e32 v28, v29, v28
	v_div_scale_f32 v29, vcc, v23, v21, v23
	v_mul_f32_e32 v30, v29, v28
	v_fma_f32 v31, -v25, v30, v29
	v_fmac_f32_e32 v30, v31, v28
	v_fma_f32 v25, -v25, v30, v29
	v_div_fmas_f32 v25, v25, v28, v30
	v_div_fixup_f32 v21, v25, v21, v23
	v_div_scale_f32 v23, s[2:3], v20, v20, v24
	v_rcp_f32_e32 v25, v23
	s_nop 0
	v_fma_f32 v28, -v23, v25, 1.0
	v_fmac_f32_e32 v25, v28, v25
	v_div_scale_f32 v28, vcc, v24, v20, v24
	v_mul_f32_e32 v29, v28, v25
	v_fma_f32 v30, -v23, v29, v28
	v_fmac_f32_e32 v29, v30, v25
	v_fma_f32 v23, -v23, v29, v28
	v_div_fmas_f32 v23, v23, v25, v29
	v_div_fixup_f32 v20, v23, v20, v24
	v_mov_b32_e32 v24, v2
	v_mul_f32_e32 v2, 0xbfb8aa3b, v26
	v_exp_f32_e32 v23, v2
	v_mov_b32_e32 v25, v4
	v_pk_mul_f32 v[20:21], v[20:21], v[24:25]
	v_pk_add_f32 v[22:23], v[22:23], 1.0 op_sel_hi:[1,0]
	s_nop 0
	v_div_scale_f32 v2, s[2:3], v23, v23, v26
	v_rcp_f32_e32 v4, v2
	s_nop 0
	v_fma_f32 v24, -v2, v4, 1.0
	v_fmac_f32_e32 v4, v24, v4
	v_div_scale_f32 v24, vcc, v26, v23, v26
	v_mul_f32_e32 v25, v24, v4
	v_fma_f32 v28, -v2, v25, v24
	v_fmac_f32_e32 v25, v28, v4
	v_fma_f32 v2, -v2, v25, v24
	v_div_fmas_f32 v2, v2, v4, v25
	v_div_fixup_f32 v23, v2, v23, v26
	v_div_scale_f32 v2, s[2:3], v22, v22, v27
	v_rcp_f32_e32 v4, v2
	s_nop 0
	v_fma_f32 v24, -v2, v4, 1.0
	v_fmac_f32_e32 v4, v24, v4
	v_div_scale_f32 v24, vcc, v27, v22, v27
	v_mul_f32_e32 v25, v24, v4
; __device__ __forceinline__ unsigned pk2(float lo, float hi) { return f2bf(lo) | (f2bf(hi) << 16); }
; __device__ __forceinline__ float bflo(unsigned w) { return __uint_as_float(w << 16); }
; __device__ __forceinline__ float bfhi(unsigned w) { return __uint_as_float(w & 0xffff0000u); }
; __device__ __forceinline__ float silu(float x) { return x / (1.f + __expf(-x)); }
; __device__ __forceinline__ void attn_unit(const Args& A, const Ctx& C0, int l, int u_qrow0, int u_nq, int u_krow0, int u_krow1, int u_krow2, int u_g, const float* u_ck, const float* u_cv, unsigned u_vmask) {
;     ...
;         const size_t row = (size_t)(u.qrow0 + qi);
; #pragma unroll
;         for (int dt = 0; dt < 2; ++dt)
; #pragma unroll
;             for (int rq = 0; rq < 4; ++rq) { const int d = dt * 32 + 8 * rq + 4 * h;
;                 const v2u gx = gxa[qt][dt][rq];
;                 const float o0 = oacc[dt][4 * rq] * silu(bflo(gx.x)), o1 = oacc[dt][4 * rq + 1] * silu(bfhi(gx.x)), o2 = oacc[dt][4 * rq + 2] * silu(bflo(gx.y)), o3 = oacc[dt][4 * rq + 3] * silu(bfhi(gx.y));
;                 v2u o; o.x = pk2(o0, o1); o.y = pk2(o2, o3);
;                 *(v2u*)(MIX + row * D + 512 + hq * 64 + d) = o; }
	v_fma_f32 v26, -v2, v25, v24
	v_fmac_f32_e32 v25, v26, v4
	v_fma_f32 v2, -v2, v25, v24
	v_div_fmas_f32 v2, v2, v4, v25
	v_div_fixup_f32 v22, v2, v22, v27
	v_mov_b32_e32 v4, v3
	v_pk_mul_f32 v[2:3], v[22:23], v[4:5]
	v_cvt_pk_bf16_f32 v3, v21, v3
	v_cvt_pk_bf16_f32 v2, v20, v2
	v_and_b32_e32 v23, 0xffff0000, v152
	flat_store_dwordx2 v[18:19], v[2:3] offset:64
	v_lshlrev_b32_e32 v5, 16, v153
	v_lshlrev_b32_e32 v20, 16, v152
	v_mul_f32_e32 v3, 0xbfb8aa3b, v23
	v_mul_f32_e32 v2, 0xbfb8aa3b, v20
	v_exp_f32_e32 v4, v3
	v_mul_f32_e32 v3, 0xbfb8aa3b, v5
	v_exp_f32_e32 v2, v2
	v_exp_f32_e32 v3, v3
	v_and_b32_e32 v22, 0xffff0000, v153
	v_pk_add_f32 v[2:3], v[2:3], 1.0 op_sel_hi:[1,0]
	s_nop 0
	v_div_scale_f32 v21, s[2:3], v3, v3, v5
	v_rcp_f32_e32 v24, v21
	s_nop 0
	v_fma_f32 v25, -v21, v24, 1.0
	v_fmac_f32_e32 v24, v25, v24
	v_div_scale_f32 v25, vcc, v5, v3, v5
	v_mul_f32_e32 v26, v25, v24
	v_fma_f32 v27, -v21, v26, v25
	v_fmac_f32_e32 v26, v27, v24
	v_fma_f32 v21, -v21, v26, v25
	v_div_fmas_f32 v21, v21, v24, v26
	v_div_fixup_f32 v3, v21, v3, v5
	v_div_scale_f32 v5, s[2:3], v2, v2, v20
	v_rcp_f32_e32 v21, v5
	s_nop 0
	v_fma_f32 v24, -v5, v21, 1.0
	v_fmac_f32_e32 v21, v24, v21
	v_div_scale_f32 v24, vcc, v20, v2, v20
	v_mul_f32_e32 v25, v24, v21
	v_fma_f32 v26, -v5, v25, v24
	v_fmac_f32_e32 v25, v26, v21
	v_fma_f32 v5, -v5, v25, v24
	v_div_fmas_f32 v5, v5, v21, v25
	v_div_fixup_f32 v2, v5, v2, v20
	v_mul_f32_e32 v5, 0xbfb8aa3b, v22
	v_exp_f32_e32 v5, v5
	v_mov_b32_e32 v20, v6
	v_mov_b32_e32 v21, v8
	v_pk_mul_f32 v[2:3], v[2:3], v[20:21]
	v_pk_add_f32 v[4:5], v[4:5], 1.0 op_sel_hi:[1,0]
	s_nop 0
	v_div_scale_f32 v6, s[2:3], v5, v5, v22
	v_rcp_f32_e32 v8, v6
	s_nop 0
	v_fma_f32 v20, -v6, v8, 1.0
	v_fmac_f32_e32 v8, v20, v8
	v_div_scale_f32 v20, vcc, v22, v5, v22
	v_mul_f32_e32 v21, v20, v8
	v_fma_f32 v24, -v6, v21, v20
	v_fmac_f32_e32 v21, v24, v8
	v_fma_f32 v6, -v6, v21, v20
	v_div_fmas_f32 v6, v6, v8, v21
	v_div_fixup_f32 v5, v6, v5, v22
	v_div_scale_f32 v6, s[2:3], v4, v4, v23
	v_rcp_f32_e32 v8, v6
	s_nop 0
	v_fma_f32 v20, -v6, v8, 1.0
	v_fmac_f32_e32 v8, v20, v8
	v_div_scale_f32 v20, vcc, v23, v4, v23
	v_mul_f32_e32 v21, v20, v8
	v_fma_f32 v22, -v6, v21, v20
	v_fmac_f32_e32 v21, v22, v8
	v_fma_f32 v6, -v6, v21, v20
	v_div_fmas_f32 v6, v6, v8, v21
	v_div_fixup_f32 v4, v6, v4, v23
	v_mov_b32_e32 v8, v7
	v_pk_mul_f32 v[4:5], v[4:5], v[8:9]
	v_cvt_pk_bf16_f32 v3, v3, v5
	v_cvt_pk_bf16_f32 v2, v2, v4
	v_and_b32_e32 v9, 0xffff0000, v150
	flat_store_dwordx2 v[18:19], v[2:3] offset:80
	v_lshlrev_b32_e32 v5, 16, v151
	v_lshlrev_b32_e32 v6, 16, v150
	v_mul_f32_e32 v3, 0xbfb8aa3b, v9
	v_mul_f32_e32 v2, 0xbfb8aa3b, v6
	v_exp_f32_e32 v4, v3
	v_mul_f32_e32 v3, 0xbfb8aa3b, v5
	v_exp_f32_e32 v2, v2
	v_exp_f32_e32 v3, v3
	v_and_b32_e32 v8, 0xffff0000, v151
	v_pk_add_f32 v[2:3], v[2:3], 1.0 op_sel_hi:[1,0]
	s_nop 0
	v_div_scale_f32 v7, s[2:3], v3, v3, v5
	v_rcp_f32_e32 v20, v7
	s_nop 0
	v_fma_f32 v21, -v7, v20, 1.0
	v_fmac_f32_e32 v20, v21, v20
	v_div_scale_f32 v21, vcc, v5, v3, v5
	v_mul_f32_e32 v22, v21, v20
	v_fma_f32 v23, -v7, v22, v21
	v_fmac_f32_e32 v22, v23, v20
	v_fma_f32 v7, -v7, v22, v21
	v_div_fmas_f32 v7, v7, v20, v22
	v_div_fixup_f32 v3, v7, v3, v5
	v_div_scale_f32 v5, s[2:3], v2, v2, v6
	v_rcp_f32_e32 v7, v5
	s_nop 0
	v_fma_f32 v20, -v5, v7, 1.0
	v_fmac_f32_e32 v7, v20, v7
	v_div_scale_f32 v20, vcc, v6, v2, v6
	v_mul_f32_e32 v21, v20, v7
	v_fma_f32 v22, -v5, v21, v20
	v_fmac_f32_e32 v21, v22, v7
	v_fma_f32 v5, -v5, v21, v20
	v_div_fmas_f32 v5, v5, v7, v21
	v_div_fixup_f32 v2, v5, v2, v6
	v_mul_f32_e32 v5, 0xbfb8aa3b, v8
	v_exp_f32_e32 v5, v5
	v_mov_b32_e32 v6, v10
	v_mov_b32_e32 v7, v12
	v_pk_mul_f32 v[2:3], v[2:3], v[6:7]
	v_pk_add_f32 v[4:5], v[4:5], 1.0 op_sel_hi:[1,0]
	s_nop 0
	v_div_scale_f32 v6, s[2:3], v5, v5, v8
	v_rcp_f32_e32 v7, v6
	s_nop 0
	v_fma_f32 v10, -v6, v7, 1.0
	v_fmac_f32_e32 v7, v10, v7
	v_div_scale_f32 v10, vcc, v8, v5, v8
	v_mul_f32_e32 v12, v10, v7
	v_fma_f32 v20, -v6, v12, v10
	v_fmac_f32_e32 v12, v20, v7
	v_fma_f32 v6, -v6, v12, v10
	v_div_fmas_f32 v6, v6, v7, v12
	v_div_fixup_f32 v5, v6, v5, v8
	v_div_scale_f32 v6, s[2:3], v4, v4, v9
	v_rcp_f32_e32 v7, v6
	s_nop 0
	v_fma_f32 v8, -v6, v7, 1.0
	v_fmac_f32_e32 v7, v8, v7
	v_div_scale_f32 v8, vcc, v9, v4, v9
	v_mul_f32_e32 v10, v8, v7
	v_fma_f32 v12, -v6, v10, v8
	v_fmac_f32_e32 v10, v12, v7
	v_fma_f32 v6, -v6, v10, v8
	v_div_fmas_f32 v6, v6, v7, v10
	v_div_fixup_f32 v4, v6, v4, v9
	v_mov_b32_e32 v12, v11
	v_pk_mul_f32 v[4:5], v[4:5], v[12:13]
	v_cvt_pk_bf16_f32 v3, v3, v5
	v_cvt_pk_bf16_f32 v2, v2, v4
	v_and_b32_e32 v9, 0xffff0000, v148
	flat_store_dwordx2 v[18:19], v[2:3] offset:96
	v_lshlrev_b32_e32 v5, 16, v149
	v_lshlrev_b32_e32 v6, 16, v148
	v_mul_f32_e32 v3, 0xbfb8aa3b, v9
	v_mul_f32_e32 v2, 0xbfb8aa3b, v6
	v_exp_f32_e32 v4, v3
	v_mul_f32_e32 v3, 0xbfb8aa3b, v5
	v_exp_f32_e32 v2, v2
	v_exp_f32_e32 v3, v3
	v_and_b32_e32 v8, 0xffff0000, v149
	v_pk_add_f32 v[2:3], v[2:3], 1.0 op_sel_hi:[1,0]
	s_nop 0
	v_div_scale_f32 v7, s[2:3], v3, v3, v5
	v_rcp_f32_e32 v10, v7
	s_nop 0
	v_fma_f32 v11, -v7, v10, 1.0
	v_fmac_f32_e32 v10, v11, v10
	v_div_scale_f32 v11, vcc, v5, v3, v5
	v_mul_f32_e32 v12, v11, v10
	v_fma_f32 v13, -v7, v12, v11
	v_fmac_f32_e32 v12, v13, v10
	v_fma_f32 v7, -v7, v12, v11
	v_div_fmas_f32 v7, v7, v10, v12
	v_div_fixup_f32 v3, v7, v3, v5
	v_div_scale_f32 v5, s[2:3], v2, v2, v6
	v_rcp_f32_e32 v7, v5
	s_nop 0
	v_fma_f32 v10, -v5, v7, 1.0
	v_fmac_f32_e32 v7, v10, v7
	v_div_scale_f32 v10, vcc, v6, v2, v6
	v_mul_f32_e32 v11, v10, v7
	v_fma_f32 v12, -v5, v11, v10
	v_fmac_f32_e32 v11, v12, v7
	v_fma_f32 v5, -v5, v11, v10
	v_div_fmas_f32 v5, v5, v7, v11
	v_div_fixup_f32 v2, v5, v2, v6
	v_mul_f32_e32 v5, 0xbfb8aa3b, v8
	v_exp_f32_e32 v5, v5
	v_mov_b32_e32 v6, v14
	v_mov_b32_e32 v7, v16
	v_pk_mul_f32 v[2:3], v[2:3], v[6:7]
	v_pk_add_f32 v[4:5], v[4:5], 1.0 op_sel_hi:[1,0]
	v_mov_b32_e32 v16, v15
	v_div_scale_f32 v6, s[2:3], v5, v5, v8
	v_rcp_f32_e32 v7, v6
	s_nop 0
	v_fma_f32 v10, -v6, v7, 1.0
	v_fmac_f32_e32 v7, v10, v7
	v_div_scale_f32 v10, vcc, v8, v5, v8
	v_mul_f32_e32 v11, v10, v7
	v_fma_f32 v12, -v6, v11, v10
	v_fmac_f32_e32 v11, v12, v7
	v_fma_f32 v6, -v6, v11, v10
	v_div_fmas_f32 v6, v6, v7, v11
	v_div_fixup_f32 v5, v6, v5, v8
	v_div_scale_f32 v6, s[2:3], v4, v4, v9
	v_rcp_f32_e32 v7, v6
	s_nop 0
	v_fma_f32 v8, -v6, v7, 1.0
	v_fmac_f32_e32 v7, v8, v7
	v_div_scale_f32 v8, vcc, v9, v4, v9
	v_mul_f32_e32 v10, v8, v7
	v_fma_f32 v11, -v6, v10, v8
	v_fmac_f32_e32 v10, v11, v7
	v_fma_f32 v6, -v6, v10, v8
	v_div_fmas_f32 v6, v6, v7, v10
	v_div_fixup_f32 v4, v6, v4, v9
	v_pk_mul_f32 v[4:5], v[4:5], v[16:17]
	v_cvt_pk_bf16_f32 v3, v3, v5
	v_cvt_pk_bf16_f32 v2, v2, v4
	s_andn2_b64 vcc, exec, s[62:63]
	flat_store_dwordx2 v[18:19], v[2:3] offset:112
	s_cbranch_vccnz .LBB0_667
; #define LAS __attribute__((address_space(3)))
; __device__ __forceinline__ void attn_unit(const Args& A, const Ctx& C0, int l, int u_qrow0, int u_nq, int u_krow0, int u_krow1, int u_krow2, int u_g, const float* u_ck, const float* u_cv, unsigned u_vmask) {
;     ...
;     for (int qt = 0; qt < 2; ++qt) { if (qt * 32 < u.nq) {
;         const int qi = qt * 32 + li;
;         bf16x8 qf[4];
; #pragma unroll
;         for (int ks = 0; ks < 4; ++ks) qf[ks] = qfa[qt][ks];
;         f32x16 sacc[6];
; #pragma unroll
;         for (int kt = 0; kt < 6; ++kt) {
; #pragma unroll
;             for (int r = 0; r < 16; ++r) sacc[kt][r] = 0.f;
; #pragma unroll
;             for (int ks = 0; ks < 4; ++ks) { const bf16x8 kf = *(const LAS bf16x8*)(Ks + (kt * 32 + li) * KP + ks * 16 + 8 * h);
;                 sacc[kt] = __builtin_amdgcn_mfma_f32_32x32x16_bf16(kf, qf[ks], sacc[kt], 0, 0, 0); }
;             asm volatile("" ::: "memory");
;         }
	v_mul_u32_u24_e32 v2, 0x90, v187
	v_add_u32_e32 v118, v190, v2
	ds_read_b128 v[2:5], v118
	s_and_b64 vcc, exec, s[38:39]
	s_waitcnt lgkmcnt(0)
	v_mfma_f32_32x32x16_bf16 v[82:97], v[2:5], v[114:117], 0
	ds_read_b128 v[2:5], v118 offset:32
	s_waitcnt lgkmcnt(0)
	v_mfma_f32_32x32x16_bf16 v[82:97], v[2:5], v[110:113], v[82:97]
	ds_read_b128 v[2:5], v118 offset:64
	s_waitcnt lgkmcnt(0)
	v_mfma_f32_32x32x16_bf16 v[82:97], v[2:5], v[106:109], v[82:97]
	ds_read_b128 v[2:5], v118 offset:96
	s_waitcnt lgkmcnt(0)
	v_mfma_f32_32x32x16_bf16 v[82:97], v[2:5], v[102:105], v[82:97]
	ds_read_b128 v[2:5], v118 offset:4608
	s_waitcnt lgkmcnt(0)
	v_mfma_f32_32x32x16_bf16 v[66:81], v[2:5], v[114:117], 0
	ds_read_b128 v[2:5], v118 offset:4640
	s_waitcnt lgkmcnt(0)
	v_mfma_f32_32x32x16_bf16 v[66:81], v[2:5], v[110:113], v[66:81]
	ds_read_b128 v[2:5], v118 offset:4672
	s_waitcnt lgkmcnt(0)
	v_mfma_f32_32x32x16_bf16 v[66:81], v[2:5], v[106:109], v[66:81]
	ds_read_b128 v[2:5], v118 offset:4704
	s_waitcnt lgkmcnt(0)
	v_mfma_f32_32x32x16_bf16 v[66:81], v[2:5], v[102:105], v[66:81]
	ds_read_b128 v[2:5], v118 offset:9216
	s_waitcnt lgkmcnt(0)
	v_mfma_f32_32x32x16_bf16 v[50:65], v[2:5], v[114:117], 0
	ds_read_b128 v[2:5], v118 offset:9248
	s_waitcnt lgkmcnt(0)
	v_mfma_f32_32x32x16_bf16 v[50:65], v[2:5], v[110:113], v[50:65]
	ds_read_b128 v[2:5], v118 offset:9280
	s_waitcnt lgkmcnt(0)
	v_mfma_f32_32x32x16_bf16 v[50:65], v[2:5], v[106:109], v[50:65]
	ds_read_b128 v[2:5], v118 offset:9312
	s_waitcnt lgkmcnt(0)
	v_mfma_f32_32x32x16_bf16 v[50:65], v[2:5], v[102:105], v[50:65]
	ds_read_b128 v[2:5], v118 offset:13824
	s_waitcnt lgkmcnt(0)
	v_mfma_f32_32x32x16_bf16 v[34:49], v[2:5], v[114:117], 0
	ds_read_b128 v[2:5], v118 offset:13856
	s_waitcnt lgkmcnt(0)
	v_mfma_f32_32x32x16_bf16 v[34:49], v[2:5], v[110:113], v[34:49]
	ds_read_b128 v[2:5], v118 offset:13888
	s_waitcnt lgkmcnt(0)
	v_mfma_f32_32x32x16_bf16 v[34:49], v[2:5], v[106:109], v[34:49]
	ds_read_b128 v[2:5], v118 offset:13920
	ds_read_b128 v[18:21], v118 offset:18464
	s_waitcnt lgkmcnt(0)
	v_mfma_f32_32x32x16_bf16 v[34:49], v[2:5], v[102:105], v[34:49]
	ds_read_b128 v[2:5], v118 offset:18432
	s_waitcnt lgkmcnt(0)
	v_mfma_f32_32x32x16_bf16 v[2:17], v[2:5], v[114:117], 0
	v_mfma_f32_32x32x16_bf16 v[2:17], v[18:21], v[110:113], v[2:17]
	ds_read_b128 v[18:21], v118 offset:18496
	s_waitcnt lgkmcnt(0)
	v_mfma_f32_32x32x16_bf16 v[2:17], v[18:21], v[106:109], v[2:17]
	ds_read_b128 v[18:21], v118 offset:18528
	s_waitcnt lgkmcnt(0)
	v_mfma_f32_32x32x16_bf16 v[2:17], v[18:21], v[102:105], v[2:17]
	ds_read_b128 v[18:21], v118 offset:23040
	s_waitcnt lgkmcnt(0)
	v_mfma_f32_32x32x16_bf16 v[18:33], v[18:21], v[114:117], 0
	ds_read_b128 v[114:117], v118 offset:23072
	s_waitcnt lgkmcnt(0)
	v_mfma_f32_32x32x16_bf16 v[18:33], v[114:117], v[110:113], v[18:33]
	ds_read_b128 v[110:113], v118 offset:23104
	s_waitcnt lgkmcnt(0)
	v_mfma_f32_32x32x16_bf16 v[18:33], v[110:113], v[106:109], v[18:33]
	ds_read_b128 v[108:111], v118 offset:23136
	v_mov_b32_e32 v106, 0xf149f2ca
	v_mov_b32_e32 v107, 0xf149f2ca
	s_waitcnt lgkmcnt(0)
	v_mfma_f32_32x32x16_bf16 v[18:33], v[108:111], v[102:105], v[18:33]
	s_cbranch_vccz .LBB0_580
	s_and_b64 vcc, exec, s[38:39]
	s_cbranch_vccz .LBB0_581

; __device__ __forceinline__ unsigned pk2(float lo, float hi) { return f2bf(lo) | (f2bf(hi) << 16); }
; __device__ __forceinline__ float bflo(unsigned w) { return __uint_as_float(w << 16); }
; __device__ __forceinline__ float bfhi(unsigned w) { return __uint_as_float(w & 0xffff0000u); }
; __device__ __forceinline__ float silu(float x) { return x / (1.f + __expf(-x)); }
; __device__ __forceinline__ void attn_unit(const Args& A, const Ctx& C0, int l, int u_qrow0, int u_nq, int u_krow0, int u_krow1, int u_krow2, int u_g, const float* u_ck, const float* u_cv, unsigned u_vmask) {
;     ...
;         const size_t row = (size_t)(u.qrow0 + qi);
; #pragma unroll
;         for (int dt = 0; dt < 2; ++dt)
; #pragma unroll
;             for (int rq = 0; rq < 4; ++rq) { const int d = dt * 32 + 8 * rq + 4 * h;
;                 const v2u gx = gxa[qt][dt][rq];
;                 const float o0 = oacc[dt][4 * rq] * silu(bflo(gx.x)), o1 = oacc[dt][4 * rq + 1] * silu(bfhi(gx.x)), o2 = oacc[dt][4 * rq + 2] * silu(bflo(gx.y)), o3 = oacc[dt][4 * rq + 3] * silu(bfhi(gx.y));
;                 v2u o; o.x = pk2(o0, o1); o.y = pk2(o2, o3);
;                 *(v2u*)(MIX + row * D + 512 + hq * 64 + d) = o; }
.LBB0_666:
	v_and_b32_e32 v43, 0xffff0000, v146
	v_lshlrev_b32_e32 v39, 16, v147
	v_lshlrev_b32_e32 v40, 16, v146
	v_mul_f32_e32 v37, 0xbfb8aa3b, v43
	v_mul_f32_e32 v36, 0xbfb8aa3b, v40
	v_exp_f32_e32 v38, v37
	v_mul_f32_e32 v37, 0xbfb8aa3b, v39
	v_exp_f32_e32 v36, v36
	v_exp_f32_e32 v37, v37
	v_mov_b32_e32 v34, 0x10000
	v_lshl_add_u32 v34, v184, 11, v34
	v_mov_b32_e32 v35, v1
	v_pk_add_f32 v[36:37], v[36:37], 1.0 op_sel_hi:[1,0]
	v_lshl_add_u64 v[34:35], v[34:35], 1, s[0:1]
	v_div_scale_f32 v41, s[0:1], v37, v37, v39
	v_rcp_f32_e32 v44, v41
	v_and_b32_e32 v42, 0xffff0000, v147
	v_lshl_add_u64 v[34:35], s[58:59], 1, v[34:35]
	v_lshl_add_u64 v[34:35], v[34:35], 0, v[0:1]
	v_fma_f32 v45, -v41, v44, 1.0
	v_fmac_f32_e32 v44, v45, v44
	v_div_scale_f32 v45, vcc, v39, v37, v39
	v_mul_f32_e32 v46, v45, v44
	v_fma_f32 v47, -v41, v46, v45
	v_fmac_f32_e32 v46, v47, v44
	v_fma_f32 v41, -v41, v46, v45
	v_div_fmas_f32 v41, v41, v44, v46
	v_div_fixup_f32 v37, v41, v37, v39
	v_div_scale_f32 v39, s[0:1], v36, v36, v40
	v_rcp_f32_e32 v41, v39
	v_lshlrev_b32_e32 v0, 16, v145
	v_fma_f32 v44, -v39, v41, 1.0
	v_fmac_f32_e32 v41, v44, v41
	v_div_scale_f32 v44, vcc, v40, v36, v40
	v_mul_f32_e32 v45, v44, v41
	v_fma_f32 v46, -v39, v45, v44
	v_fmac_f32_e32 v45, v46, v41
	v_fma_f32 v39, -v39, v45, v44
	v_div_fmas_f32 v39, v39, v41, v45
	v_div_fixup_f32 v36, v39, v36, v40
	v_mov_b32_e32 v40, v18
	v_mul_f32_e32 v18, 0xbfb8aa3b, v42
	v_exp_f32_e32 v39, v18
	v_mov_b32_e32 v41, v20
	v_pk_mul_f32 v[36:37], v[36:37], v[40:41]
	v_pk_add_f32 v[38:39], v[38:39], 1.0 op_sel_hi:[1,0]
	s_nop 0
	v_div_scale_f32 v18, s[0:1], v39, v39, v42
	v_rcp_f32_e32 v20, v18
	s_nop 0
	v_fma_f32 v40, -v18, v20, 1.0
	v_fmac_f32_e32 v20, v40, v20
	v_div_scale_f32 v40, vcc, v42, v39, v42
	v_mul_f32_e32 v41, v40, v20
	v_fma_f32 v44, -v18, v41, v40
	v_fmac_f32_e32 v41, v44, v20
	v_fma_f32 v18, -v18, v41, v40
	v_div_fmas_f32 v18, v18, v20, v41
	v_div_fixup_f32 v39, v18, v39, v42
	v_div_scale_f32 v18, s[0:1], v38, v38, v43
	v_rcp_f32_e32 v20, v18
	s_mov_b64 s[0:1], 0x7b27d00
	v_fma_f32 v40, -v18, v20, 1.0
	v_fmac_f32_e32 v20, v40, v20
	v_div_scale_f32 v40, vcc, v43, v38, v43
	v_mul_f32_e32 v41, v40, v20
	v_fma_f32 v42, -v18, v41, v40
	v_fmac_f32_e32 v41, v42, v20
	v_fma_f32 v18, -v18, v41, v40
	v_div_fmas_f32 v18, v18, v20, v41
	v_div_fixup_f32 v38, v18, v38, v43
	v_mov_b32_e32 v20, v19
	v_pk_mul_f32 v[18:19], v[38:39], v[20:21]
	v_and_b32_sdwa v20, v37, v252 dst_sel:DWORD dst_unused:UNUSED_PAD src0_sel:WORD_1 src1_sel:DWORD
	v_and_b32_sdwa v21, v36, v252 dst_sel:DWORD dst_unused:UNUSED_PAD src0_sel:WORD_1 src1_sel:DWORD
	v_add3_u32 v36, v36, v21, s33
	v_add3_u32 v20, v37, v20, s33
	v_and_b32_sdwa v21, v19, v252 dst_sel:DWORD dst_unused:UNUSED_PAD src0_sel:WORD_1 src1_sel:DWORD
	v_and_b32_sdwa v37, v18, v252 dst_sel:DWORD dst_unused:UNUSED_PAD src0_sel:WORD_1 src1_sel:DWORD
	v_add3_u32 v19, v19, v21, s33
	v_add3_u32 v18, v18, v37, s33
	v_and_b32_e32 v19, 0xffff0000, v19
	v_and_b32_e32 v18, 0xffff0000, v18
	v_or_b32_sdwa v21, v19, v20 dst_sel:DWORD dst_unused:UNUSED_PAD src0_sel:DWORD src1_sel:WORD_1
	v_or_b32_sdwa v20, v18, v36 dst_sel:DWORD dst_unused:UNUSED_PAD src0_sel:DWORD src1_sel:WORD_1
	v_lshl_add_u64 v[18:19], v[34:35], 0, s[0:1]
	s_mov_b32 s0, 0x7b27000
	v_add_co_u32_e32 v34, vcc, s0, v34
	v_and_b32_e32 v39, 0xffff0000, v144
	s_nop 0
	v_addc_co_u32_e32 v35, vcc, 0, v35, vcc
	flat_store_dwordx2 v[34:35], v[20:21] offset:3328
	v_lshlrev_b32_e32 v35, 16, v144
	v_mul_f32_e32 v21, 0xbfb8aa3b, v39
	v_mul_f32_e32 v20, 0xbfb8aa3b, v35
	v_exp_f32_e32 v34, v21
	v_mul_f32_e32 v21, 0xbfb8aa3b, v0
	v_exp_f32_e32 v20, v20
	v_exp_f32_e32 v21, v21
	v_and_b32_e32 v38, 0xffff0000, v145
	v_pk_add_f32 v[20:21], v[20:21], 1.0 op_sel_hi:[1,0]
	s_nop 0
	v_div_scale_f32 v36, s[0:1], v21, v21, v0
	v_rcp_f32_e32 v37, v36
	s_nop 0
	v_fma_f32 v40, -v36, v37, 1.0
	v_fmac_f32_e32 v37, v40, v37
	v_div_scale_f32 v40, vcc, v0, v21, v0
	v_mul_f32_e32 v41, v40, v37
	v_fma_f32 v42, -v36, v41, v40
	v_fmac_f32_e32 v41, v42, v37
	v_fma_f32 v36, -v36, v41, v40
	v_div_fmas_f32 v36, v36, v37, v41
	v_div_fixup_f32 v21, v36, v21, v0
	v_div_scale_f32 v0, s[0:1], v20, v20, v35
	v_rcp_f32_e32 v36, v0
	s_nop 0
	v_fma_f32 v37, -v0, v36, 1.0
	v_fmac_f32_e32 v36, v37, v36
	v_div_scale_f32 v37, vcc, v35, v20, v35
	v_mul_f32_e32 v40, v37, v36
	v_fma_f32 v41, -v0, v40, v37
	v_fmac_f32_e32 v40, v41, v36
	v_fma_f32 v0, -v0, v40, v37
	v_div_fmas_f32 v0, v0, v36, v40
	v_div_fixup_f32 v20, v0, v20, v35
	v_mul_f32_e32 v0, 0xbfb8aa3b, v38
	v_exp_f32_e32 v35, v0
	v_mov_b32_e32 v36, v22
	v_mov_b32_e32 v37, v24
	v_pk_mul_f32 v[20:21], v[20:21], v[36:37]
	v_pk_add_f32 v[34:35], v[34:35], 1.0 op_sel_hi:[1,0]
	s_nop 0
	v_div_scale_f32 v0, s[0:1], v35, v35, v38
	v_rcp_f32_e32 v22, v0
	s_nop 0
	v_fma_f32 v24, -v0, v22, 1.0
	v_fmac_f32_e32 v22, v24, v22
	v_div_scale_f32 v24, vcc, v38, v35, v38
	v_mul_f32_e32 v36, v24, v22
	v_fma_f32 v37, -v0, v36, v24
	v_fmac_f32_e32 v36, v37, v22
	v_fma_f32 v0, -v0, v36, v24
	v_div_fmas_f32 v0, v0, v22, v36
	v_div_fixup_f32 v35, v0, v35, v38
	v_div_scale_f32 v0, s[0:1], v34, v34, v39
	v_rcp_f32_e32 v22, v0
	s_nop 0
	v_fma_f32 v24, -v0, v22, 1.0
	v_fmac_f32_e32 v22, v24, v22
	v_div_scale_f32 v24, vcc, v39, v34, v39
	v_mul_f32_e32 v36, v24, v22
	v_fma_f32 v37, -v0, v36, v24
	v_fmac_f32_e32 v36, v37, v22
	v_fma_f32 v0, -v0, v36, v24
	v_div_fmas_f32 v0, v0, v22, v36
	v_div_fixup_f32 v34, v0, v34, v39
	v_mov_b32_e32 v24, v23
	v_pk_mul_f32 v[22:23], v[34:35], v[24:25]
	v_cvt_pk_bf16_f32 v21, v21, v23
	v_cvt_pk_bf16_f32 v20, v20, v22
	v_and_b32_e32 v35, 0xffff0000, v140
	flat_store_dwordx2 v[18:19], v[20:21] offset:16
; __device__ __forceinline__ unsigned pk2(float lo, float hi) { return f2bf(lo) | (f2bf(hi) << 16); }
; __device__ __forceinline__ float bflo(unsigned w) { return __uint_as_float(w << 16); }
; __device__ __forceinline__ float bfhi(unsigned w) { return __uint_as_float(w & 0xffff0000u); }
; __device__ __forceinline__ float silu(float x) { return x / (1.f + __expf(-x)); }
; __device__ __forceinline__ void attn_unit(const Args& A, const Ctx& C0, int l, int u_qrow0, int u_nq, int u_krow0, int u_krow1, int u_krow2, int u_g, const float* u_ck, const float* u_cv, unsigned u_vmask) {
;     ...
;         const size_t row = (size_t)(u.qrow0 + qi);
; #pragma unroll
;         for (int dt = 0; dt < 2; ++dt)
; #pragma unroll
;             for (int rq = 0; rq < 4; ++rq) { const int d = dt * 32 + 8 * rq + 4 * h;
;                 const v2u gx = gxa[qt][dt][rq];
;                 const float o0 = oacc[dt][4 * rq] * silu(bflo(gx.x)), o1 = oacc[dt][4 * rq + 1] * silu(bfhi(gx.x)), o2 = oacc[dt][4 * rq + 2] * silu(bflo(gx.y)), o3 = oacc[dt][4 * rq + 3] * silu(bfhi(gx.y));
;                 v2u o; o.x = pk2(o0, o1); o.y = pk2(o2, o3);
;                 *(v2u*)(MIX + row * D + 512 + hq * 64 + d) = o; }
	v_lshlrev_b32_e32 v0, 16, v141
	v_lshlrev_b32_e32 v23, 16, v140
	v_mul_f32_e32 v21, 0xbfb8aa3b, v35
	v_mul_f32_e32 v20, 0xbfb8aa3b, v23
	v_exp_f32_e32 v22, v21
	v_mul_f32_e32 v21, 0xbfb8aa3b, v0
	v_exp_f32_e32 v20, v20
	v_exp_f32_e32 v21, v21
	v_and_b32_e32 v34, 0xffff0000, v141
	v_pk_add_f32 v[20:21], v[20:21], 1.0 op_sel_hi:[1,0]
	s_nop 0
	v_div_scale_f32 v24, s[0:1], v21, v21, v0
	v_rcp_f32_e32 v25, v24
	s_nop 0
	v_fma_f32 v36, -v24, v25, 1.0
	v_fmac_f32_e32 v25, v36, v25
	v_div_scale_f32 v36, vcc, v0, v21, v0
	v_mul_f32_e32 v37, v36, v25
	v_fma_f32 v38, -v24, v37, v36
	v_fmac_f32_e32 v37, v38, v25
	v_fma_f32 v24, -v24, v37, v36
	v_div_fmas_f32 v24, v24, v25, v37
	v_div_fixup_f32 v21, v24, v21, v0
	v_div_scale_f32 v0, s[0:1], v20, v20, v23
	v_rcp_f32_e32 v24, v0
	s_nop 0
	v_fma_f32 v25, -v0, v24, 1.0
	v_fmac_f32_e32 v24, v25, v24
	v_div_scale_f32 v25, vcc, v23, v20, v23
	v_mul_f32_e32 v36, v25, v24
	v_fma_f32 v37, -v0, v36, v25
	v_fmac_f32_e32 v36, v37, v24
	v_fma_f32 v0, -v0, v36, v25
	v_div_fmas_f32 v0, v0, v24, v36
	v_div_fixup_f32 v20, v0, v20, v23
	v_mul_f32_e32 v0, 0xbfb8aa3b, v34
	v_exp_f32_e32 v23, v0
	v_mov_b32_e32 v24, v26
	v_mov_b32_e32 v25, v28
	v_pk_mul_f32 v[20:21], v[20:21], v[24:25]
	v_pk_add_f32 v[22:23], v[22:23], 1.0 op_sel_hi:[1,0]
	s_nop 0
	v_div_scale_f32 v0, s[0:1], v23, v23, v34
	v_rcp_f32_e32 v24, v0
	s_nop 0
	v_fma_f32 v25, -v0, v24, 1.0
	v_fmac_f32_e32 v24, v25, v24
	v_div_scale_f32 v25, vcc, v34, v23, v34
	v_mul_f32_e32 v26, v25, v24
	v_fma_f32 v28, -v0, v26, v25
	v_fmac_f32_e32 v26, v28, v24
	v_fma_f32 v0, -v0, v26, v25
	v_div_fmas_f32 v0, v0, v24, v26
	v_div_fixup_f32 v23, v0, v23, v34
	v_div_scale_f32 v0, s[0:1], v22, v22, v35
	v_rcp_f32_e32 v24, v0
	s_nop 0
	v_fma_f32 v25, -v0, v24, 1.0
	v_fmac_f32_e32 v24, v25, v24
	v_div_scale_f32 v25, vcc, v35, v22, v35
	v_mul_f32_e32 v26, v25, v24
	v_fma_f32 v28, -v0, v26, v25
	v_fmac_f32_e32 v26, v28, v24
	v_fma_f32 v0, -v0, v26, v25
	v_div_fmas_f32 v0, v0, v24, v26
	v_div_fixup_f32 v22, v0, v22, v35
	v_mov_b32_e32 v28, v27
	v_pk_mul_f32 v[22:23], v[22:23], v[28:29]
	v_cvt_pk_bf16_f32 v21, v21, v23
	v_cvt_pk_bf16_f32 v20, v20, v22
	v_and_b32_e32 v27, 0xffff0000, v138
	flat_store_dwordx2 v[18:19], v[20:21] offset:32
	v_lshlrev_b32_e32 v0, 16, v139
	v_lshlrev_b32_e32 v23, 16, v138
	v_mul_f32_e32 v21, 0xbfb8aa3b, v27
	v_mul_f32_e32 v20, 0xbfb8aa3b, v23
	v_exp_f32_e32 v22, v21
	v_mul_f32_e32 v21, 0xbfb8aa3b, v0
	v_exp_f32_e32 v20, v20
	v_exp_f32_e32 v21, v21
	v_and_b32_e32 v26, 0xffff0000, v139
	v_pk_add_f32 v[20:21], v[20:21], 1.0 op_sel_hi:[1,0]
	s_nop 0
	v_div_scale_f32 v24, s[0:1], v21, v21, v0
	v_rcp_f32_e32 v25, v24
	s_nop 0
	v_fma_f32 v28, -v24, v25, 1.0
	v_fmac_f32_e32 v25, v28, v25
	v_div_scale_f32 v28, vcc, v0, v21, v0
	v_mul_f32_e32 v29, v28, v25
	v_fma_f32 v34, -v24, v29, v28
	v_fmac_f32_e32 v29, v34, v25
	v_fma_f32 v24, -v24, v29, v28
	v_div_fmas_f32 v24, v24, v25, v29
	v_div_fixup_f32 v21, v24, v21, v0
	v_div_scale_f32 v0, s[0:1], v20, v20, v23
	v_rcp_f32_e32 v24, v0
	s_nop 0
	v_fma_f32 v25, -v0, v24, 1.0
	v_fmac_f32_e32 v24, v25, v24
	v_div_scale_f32 v25, vcc, v23, v20, v23
	v_mul_f32_e32 v28, v25, v24
	v_fma_f32 v29, -v0, v28, v25
	v_fmac_f32_e32 v28, v29, v24
	v_fma_f32 v0, -v0, v28, v25
	v_div_fmas_f32 v0, v0, v24, v28
	v_div_fixup_f32 v20, v0, v20, v23
	v_mul_f32_e32 v0, 0xbfb8aa3b, v26
	v_exp_f32_e32 v23, v0
	v_mov_b32_e32 v24, v30
	v_mov_b32_e32 v25, v32
	v_pk_mul_f32 v[20:21], v[20:21], v[24:25]
	v_pk_add_f32 v[22:23], v[22:23], 1.0 op_sel_hi:[1,0]
	v_mov_b32_e32 v32, v31
	v_div_scale_f32 v0, s[0:1], v23, v23, v26
	v_rcp_f32_e32 v24, v0
	s_nop 0
	v_fma_f32 v25, -v0, v24, 1.0
	v_fmac_f32_e32 v24, v25, v24
	v_div_scale_f32 v25, vcc, v26, v23, v26
	v_mul_f32_e32 v28, v25, v24
	v_fma_f32 v29, -v0, v28, v25
	v_fmac_f32_e32 v28, v29, v24
	v_fma_f32 v0, -v0, v28, v25
	v_div_fmas_f32 v0, v0, v24, v28
	v_div_fixup_f32 v23, v0, v23, v26
	v_div_scale_f32 v0, s[0:1], v22, v22, v27
	v_rcp_f32_e32 v24, v0
	s_nop 0
	v_fma_f32 v25, -v0, v24, 1.0
	v_fmac_f32_e32 v24, v25, v24
	v_div_scale_f32 v25, vcc, v27, v22, v27
	v_mul_f32_e32 v26, v25, v24
	v_fma_f32 v28, -v0, v26, v25
	v_fmac_f32_e32 v26, v28, v24
	v_fma_f32 v0, -v0, v26, v25
	v_div_fmas_f32 v0, v0, v24, v26
	v_div_fixup_f32 v22, v0, v22, v27
	v_pk_mul_f32 v[22:23], v[22:23], v[32:33]
	v_cvt_pk_bf16_f32 v21, v21, v23
	v_cvt_pk_bf16_f32 v20, v20, v22
	v_and_b32_e32 v27, 0xffff0000, v136
	flat_store_dwordx2 v[18:19], v[20:21] offset:48
	v_lshlrev_b32_e32 v0, 16, v137
	v_lshlrev_b32_e32 v23, 16, v136
	v_mul_f32_e32 v21, 0xbfb8aa3b, v27
	v_mul_f32_e32 v20, 0xbfb8aa3b, v23
	v_exp_f32_e32 v22, v21
	v_mul_f32_e32 v21, 0xbfb8aa3b, v0
	v_exp_f32_e32 v20, v20
	v_exp_f32_e32 v21, v21
	v_and_b32_e32 v26, 0xffff0000, v137
	v_pk_add_f32 v[20:21], v[20:21], 1.0 op_sel_hi:[1,0]
	s_nop 0
	v_div_scale_f32 v24, s[0:1], v21, v21, v0
	v_rcp_f32_e32 v25, v24
	s_nop 0
	v_fma_f32 v28, -v24, v25, 1.0
	v_fmac_f32_e32 v25, v28, v25
	v_div_scale_f32 v28, vcc, v0, v21, v0
	v_mul_f32_e32 v29, v28, v25
	v_fma_f32 v30, -v24, v29, v28
	v_fmac_f32_e32 v29, v30, v25
	v_fma_f32 v24, -v24, v29, v28
	v_div_fmas_f32 v24, v24, v25, v29
	v_div_fixup_f32 v21, v24, v21, v0
	v_div_scale_f32 v0, s[0:1], v20, v20, v23
	v_rcp_f32_e32 v24, v0
	s_nop 0
	v_fma_f32 v25, -v0, v24, 1.0
	v_fmac_f32_e32 v24, v25, v24
	v_div_scale_f32 v25, vcc, v23, v20, v23
	v_mul_f32_e32 v28, v25, v24
	v_fma_f32 v29, -v0, v28, v25
	v_fmac_f32_e32 v28, v29, v24
	v_fma_f32 v0, -v0, v28, v25
	v_div_fmas_f32 v0, v0, v24, v28
	v_div_fixup_f32 v20, v0, v20, v23
	v_mul_f32_e32 v0, 0xbfb8aa3b, v26
	v_exp_f32_e32 v23, v0
	v_mov_b32_e32 v24, v2
	v_mov_b32_e32 v25, v4
; __device__ __forceinline__ unsigned pk2(float lo, float hi) { return f2bf(lo) | (f2bf(hi) << 16); }
; __device__ __forceinline__ float bflo(unsigned w) { return __uint_as_float(w << 16); }
; __device__ __forceinline__ float bfhi(unsigned w) { return __uint_as_float(w & 0xffff0000u); }
; __device__ __forceinline__ float silu(float x) { return x / (1.f + __expf(-x)); }
; __device__ __forceinline__ void attn_unit(const Args& A, const Ctx& C0, int l, int u_qrow0, int u_nq, int u_krow0, int u_krow1, int u_krow2, int u_g, const float* u_ck, const float* u_cv, unsigned u_vmask) {
;     ...
;         const size_t row = (size_t)(u.qrow0 + qi);
; #pragma unroll
;         for (int dt = 0; dt < 2; ++dt)
; #pragma unroll
;             for (int rq = 0; rq < 4; ++rq) { const int d = dt * 32 + 8 * rq + 4 * h;
;                 const v2u gx = gxa[qt][dt][rq];
;                 const float o0 = oacc[dt][4 * rq] * silu(bflo(gx.x)), o1 = oacc[dt][4 * rq + 1] * silu(bfhi(gx.x)), o2 = oacc[dt][4 * rq + 2] * silu(bflo(gx.y)), o3 = oacc[dt][4 * rq + 3] * silu(bfhi(gx.y));
;                 v2u o; o.x = pk2(o0, o1); o.y = pk2(o2, o3);
;                 *(v2u*)(MIX + row * D + 512 + hq * 64 + d) = o; }
	v_pk_mul_f32 v[20:21], v[20:21], v[24:25]
	v_pk_add_f32 v[22:23], v[22:23], 1.0 op_sel_hi:[1,0]
	s_nop 0
	v_div_scale_f32 v0, s[0:1], v23, v23, v26
	v_rcp_f32_e32 v2, v0
	s_nop 0
	v_fma_f32 v4, -v0, v2, 1.0
	v_fmac_f32_e32 v2, v4, v2
	v_div_scale_f32 v4, vcc, v26, v23, v26
	v_mul_f32_e32 v24, v4, v2
	v_fma_f32 v25, -v0, v24, v4
	v_fmac_f32_e32 v24, v25, v2
	v_fma_f32 v0, -v0, v24, v4
	v_div_fmas_f32 v0, v0, v2, v24
	v_div_fixup_f32 v23, v0, v23, v26
	v_div_scale_f32 v0, s[0:1], v22, v22, v27
	v_rcp_f32_e32 v2, v0
	s_nop 0
	v_fma_f32 v4, -v0, v2, 1.0
	v_fmac_f32_e32 v2, v4, v2
	v_div_scale_f32 v4, vcc, v27, v22, v27
	v_mul_f32_e32 v24, v4, v2
	v_fma_f32 v25, -v0, v24, v4
	v_fmac_f32_e32 v24, v25, v2
	v_fma_f32 v0, -v0, v24, v4
	v_div_fmas_f32 v0, v0, v2, v24
	v_div_fixup_f32 v22, v0, v22, v27
	v_mov_b32_e32 v4, v3
	v_pk_mul_f32 v[2:3], v[22:23], v[4:5]
	v_cvt_pk_bf16_f32 v3, v21, v3
	v_cvt_pk_bf16_f32 v2, v20, v2
	v_and_b32_e32 v23, 0xffff0000, v134
	flat_store_dwordx2 v[18:19], v[2:3] offset:64
	v_lshlrev_b32_e32 v0, 16, v135
	v_lshlrev_b32_e32 v5, 16, v134
	v_mul_f32_e32 v3, 0xbfb8aa3b, v23
	v_mul_f32_e32 v2, 0xbfb8aa3b, v5
	v_exp_f32_e32 v4, v3
	v_mul_f32_e32 v3, 0xbfb8aa3b, v0
	v_exp_f32_e32 v2, v2
	v_exp_f32_e32 v3, v3
	v_and_b32_e32 v22, 0xffff0000, v135
	v_pk_add_f32 v[2:3], v[2:3], 1.0 op_sel_hi:[1,0]
	s_nop 0
	v_div_scale_f32 v20, s[0:1], v3, v3, v0
	v_rcp_f32_e32 v21, v20
	s_nop 0
	v_fma_f32 v24, -v20, v21, 1.0
	v_fmac_f32_e32 v21, v24, v21
	v_div_scale_f32 v24, vcc, v0, v3, v0
	v_mul_f32_e32 v25, v24, v21
	v_fma_f32 v26, -v20, v25, v24
	v_fmac_f32_e32 v25, v26, v21
	v_fma_f32 v20, -v20, v25, v24
	v_div_fmas_f32 v20, v20, v21, v25
	v_div_fixup_f32 v3, v20, v3, v0
	v_div_scale_f32 v0, s[0:1], v2, v2, v5
	v_rcp_f32_e32 v20, v0
	s_nop 0
	v_fma_f32 v21, -v0, v20, 1.0
	v_fmac_f32_e32 v20, v21, v20
	v_div_scale_f32 v21, vcc, v5, v2, v5
	v_mul_f32_e32 v24, v21, v20
	v_fma_f32 v25, -v0, v24, v21
	v_fmac_f32_e32 v24, v25, v20
	v_fma_f32 v0, -v0, v24, v21
	v_div_fmas_f32 v0, v0, v20, v24
	v_div_fixup_f32 v2, v0, v2, v5
	v_mul_f32_e32 v0, 0xbfb8aa3b, v22
	v_exp_f32_e32 v5, v0
	v_mov_b32_e32 v20, v6
	v_mov_b32_e32 v21, v8
	v_pk_mul_f32 v[2:3], v[2:3], v[20:21]
	v_pk_add_f32 v[4:5], v[4:5], 1.0 op_sel_hi:[1,0]
	s_nop 0
	v_div_scale_f32 v0, s[0:1], v5, v5, v22
	v_rcp_f32_e32 v6, v0
	s_nop 0
	v_fma_f32 v8, -v0, v6, 1.0
	v_fmac_f32_e32 v6, v8, v6
	v_div_scale_f32 v8, vcc, v22, v5, v22
	v_mul_f32_e32 v20, v8, v6
	v_fma_f32 v21, -v0, v20, v8
	v_fmac_f32_e32 v20, v21, v6
	v_fma_f32 v0, -v0, v20, v8
	v_div_fmas_f32 v0, v0, v6, v20
	v_div_fixup_f32 v5, v0, v5, v22
	v_div_scale_f32 v0, s[0:1], v4, v4, v23
	v_rcp_f32_e32 v6, v0
	s_nop 0
	v_fma_f32 v8, -v0, v6, 1.0
	v_fmac_f32_e32 v6, v8, v6
	v_div_scale_f32 v8, vcc, v23, v4, v23
	v_mul_f32_e32 v20, v8, v6
	v_fma_f32 v21, -v0, v20, v8
	v_fmac_f32_e32 v20, v21, v6
	v_fma_f32 v0, -v0, v20, v8
	v_div_fmas_f32 v0, v0, v6, v20
	v_div_fixup_f32 v4, v0, v4, v23
	v_mov_b32_e32 v8, v7
	v_pk_mul_f32 v[4:5], v[4:5], v[8:9]
	v_cvt_pk_bf16_f32 v3, v3, v5
	v_cvt_pk_bf16_f32 v2, v2, v4
	v_and_b32_e32 v9, 0xffff0000, v132
	flat_store_dwordx2 v[18:19], v[2:3] offset:80
	v_lshlrev_b32_e32 v0, 16, v133
	v_lshlrev_b32_e32 v5, 16, v132
	v_mul_f32_e32 v3, 0xbfb8aa3b, v9
	v_mul_f32_e32 v2, 0xbfb8aa3b, v5
	v_exp_f32_e32 v4, v3
	v_mul_f32_e32 v3, 0xbfb8aa3b, v0
	v_exp_f32_e32 v2, v2
	v_exp_f32_e32 v3, v3
	v_and_b32_e32 v8, 0xffff0000, v133
	v_pk_add_f32 v[2:3], v[2:3], 1.0 op_sel_hi:[1,0]
	s_nop 0
	v_div_scale_f32 v6, s[0:1], v3, v3, v0
	v_rcp_f32_e32 v7, v6
	s_nop 0
	v_fma_f32 v20, -v6, v7, 1.0
	v_fmac_f32_e32 v7, v20, v7
	v_div_scale_f32 v20, vcc, v0, v3, v0
	v_mul_f32_e32 v21, v20, v7
	v_fma_f32 v22, -v6, v21, v20
; __device__ __forceinline__ unsigned pk2(float lo, float hi) { return f2bf(lo) | (f2bf(hi) << 16); }
; __device__ __forceinline__ float bflo(unsigned w) { return __uint_as_float(w << 16); }
; __device__ __forceinline__ float bfhi(unsigned w) { return __uint_as_float(w & 0xffff0000u); }
; __device__ __forceinline__ float silu(float x) { return x / (1.f + __expf(-x)); }
; __device__ __forceinline__ void attn_unit(const Args& A, const Ctx& C0, int l, int u_qrow0, int u_nq, int u_krow0, int u_krow1, int u_krow2, int u_g, const float* u_ck, const float* u_cv, unsigned u_vmask) {
;     ...
;         const size_t row = (size_t)(u.qrow0 + qi);
; #pragma unroll
;         for (int dt = 0; dt < 2; ++dt)
; #pragma unroll
;             for (int rq = 0; rq < 4; ++rq) { const int d = dt * 32 + 8 * rq + 4 * h;
;                 const v2u gx = gxa[qt][dt][rq];
;                 const float o0 = oacc[dt][4 * rq] * silu(bflo(gx.x)), o1 = oacc[dt][4 * rq + 1] * silu(bfhi(gx.x)), o2 = oacc[dt][4 * rq + 2] * silu(bflo(gx.y)), o3 = oacc[dt][4 * rq + 3] * silu(bfhi(gx.y));
;                 v2u o; o.x = pk2(o0, o1); o.y = pk2(o2, o3);
;                 *(v2u*)(MIX + row * D + 512 + hq * 64 + d) = o; }
	v_fmac_f32_e32 v21, v22, v7
	v_fma_f32 v6, -v6, v21, v20
	v_div_fmas_f32 v6, v6, v7, v21
	v_div_fixup_f32 v3, v6, v3, v0
	v_div_scale_f32 v0, s[0:1], v2, v2, v5
	v_rcp_f32_e32 v6, v0
	s_nop 0
	v_fma_f32 v7, -v0, v6, 1.0
	v_fmac_f32_e32 v6, v7, v6
	v_div_scale_f32 v7, vcc, v5, v2, v5
	v_mul_f32_e32 v20, v7, v6
	v_fma_f32 v21, -v0, v20, v7
	v_fmac_f32_e32 v20, v21, v6
	v_fma_f32 v0, -v0, v20, v7
	v_div_fmas_f32 v0, v0, v6, v20
	v_div_fixup_f32 v2, v0, v2, v5
	v_mul_f32_e32 v0, 0xbfb8aa3b, v8
	v_exp_f32_e32 v5, v0
	v_mov_b32_e32 v6, v10
	v_mov_b32_e32 v7, v12
	v_pk_mul_f32 v[2:3], v[2:3], v[6:7]
	v_pk_add_f32 v[4:5], v[4:5], 1.0 op_sel_hi:[1,0]
	s_nop 0
	v_div_scale_f32 v0, s[0:1], v5, v5, v8
	v_rcp_f32_e32 v6, v0
	s_nop 0
	v_fma_f32 v7, -v0, v6, 1.0
	v_fmac_f32_e32 v6, v7, v6
	v_div_scale_f32 v7, vcc, v8, v5, v8
	v_mul_f32_e32 v10, v7, v6
	v_fma_f32 v12, -v0, v10, v7
	v_fmac_f32_e32 v10, v12, v6
	v_fma_f32 v0, -v0, v10, v7
	v_div_fmas_f32 v0, v0, v6, v10
	v_div_fixup_f32 v5, v0, v5, v8
	v_div_scale_f32 v0, s[0:1], v4, v4, v9
	v_rcp_f32_e32 v6, v0
	v_mov_b32_e32 v12, v11
	v_fma_f32 v7, -v0, v6, 1.0
	v_fmac_f32_e32 v6, v7, v6
	v_div_scale_f32 v7, vcc, v9, v4, v9
	v_mul_f32_e32 v8, v7, v6
	v_fma_f32 v10, -v0, v8, v7
	v_fmac_f32_e32 v8, v10, v6
	v_fma_f32 v0, -v0, v8, v7
	v_div_fmas_f32 v0, v0, v6, v8
	v_div_fixup_f32 v4, v0, v4, v9
	v_pk_mul_f32 v[4:5], v[4:5], v[12:13]
	v_cvt_pk_bf16_f32 v3, v3, v5
	v_cvt_pk_bf16_f32 v2, v2, v4
	v_and_b32_e32 v9, 0xffff0000, v130
	flat_store_dwordx2 v[18:19], v[2:3] offset:96
	v_lshlrev_b32_e32 v0, 16, v131
	v_lshlrev_b32_e32 v5, 16, v130
	v_mul_f32_e32 v3, 0xbfb8aa3b, v9
	v_mul_f32_e32 v2, 0xbfb8aa3b, v5
	v_exp_f32_e32 v4, v3
	v_mul_f32_e32 v3, 0xbfb8aa3b, v0
	v_exp_f32_e32 v2, v2
	v_exp_f32_e32 v3, v3
	v_and_b32_e32 v8, 0xffff0000, v131
	v_pk_add_f32 v[2:3], v[2:3], 1.0 op_sel_hi:[1,0]
	s_nop 0
	v_div_scale_f32 v6, s[0:1], v3, v3, v0
	v_rcp_f32_e32 v7, v6
	s_nop 0
	v_fma_f32 v10, -v6, v7, 1.0
	v_fmac_f32_e32 v7, v10, v7
	v_div_scale_f32 v10, vcc, v0, v3, v0
	v_mul_f32_e32 v11, v10, v7
	v_fma_f32 v12, -v6, v11, v10
	v_fmac_f32_e32 v11, v12, v7
	v_fma_f32 v6, -v6, v11, v10
	v_div_fmas_f32 v6, v6, v7, v11
	v_div_fixup_f32 v3, v6, v3, v0
	v_div_scale_f32 v0, s[0:1], v2, v2, v5
	v_rcp_f32_e32 v6, v0
	s_nop 0
	v_fma_f32 v7, -v0, v6, 1.0
	v_fmac_f32_e32 v6, v7, v6
	v_div_scale_f32 v7, vcc, v5, v2, v5
	v_mul_f32_e32 v10, v7, v6
	v_fma_f32 v11, -v0, v10, v7
	v_fmac_f32_e32 v10, v11, v6
	v_fma_f32 v0, -v0, v10, v7
	v_div_fmas_f32 v0, v0, v6, v10
	v_div_fixup_f32 v2, v0, v2, v5
	v_mul_f32_e32 v0, 0xbfb8aa3b, v8
	v_exp_f32_e32 v5, v0
	v_mov_b32_e32 v6, v14
	v_mov_b32_e32 v7, v16
	v_pk_mul_f32 v[2:3], v[2:3], v[6:7]
	v_pk_add_f32 v[4:5], v[4:5], 1.0 op_sel_hi:[1,0]
	v_mov_b32_e32 v16, v15
	v_div_scale_f32 v0, s[0:1], v5, v5, v8
	v_rcp_f32_e32 v6, v0
	s_nop 0
	v_fma_f32 v7, -v0, v6, 1.0
	v_fmac_f32_e32 v6, v7, v6
	v_div_scale_f32 v7, vcc, v8, v5, v8
	v_mul_f32_e32 v10, v7, v6
	v_fma_f32 v11, -v0, v10, v7
	v_fmac_f32_e32 v10, v11, v6
	v_fma_f32 v0, -v0, v10, v7
	v_div_fmas_f32 v0, v0, v6, v10
	v_div_fixup_f32 v5, v0, v5, v8
	v_div_scale_f32 v0, s[0:1], v4, v4, v9
	v_rcp_f32_e32 v6, v0
	s_nop 0
	v_fma_f32 v7, -v0, v6, 1.0
	v_fmac_f32_e32 v6, v7, v6
	v_div_scale_f32 v7, vcc, v9, v4, v9
	v_mul_f32_e32 v8, v7, v6
	v_fma_f32 v10, -v0, v8, v7
	v_fmac_f32_e32 v8, v10, v6
	v_fma_f32 v0, -v0, v8, v7
	v_div_fmas_f32 v0, v0, v6, v8
	v_div_fixup_f32 v4, v0, v4, v9
	v_pk_mul_f32 v[4:5], v[4:5], v[16:17]
	s_nop 0
	s_nop 0
	s_nop 0
	s_nop 0
	s_nop 0
	s_nop 0
	s_nop 0
	s_nop 0
	s_nop 0
	s_nop 0
	v_cvt_pk_bf16_f32 v3, v3, v5
	v_cvt_pk_bf16_f32 v2, v2, v4
	flat_store_dwordx2 v[18:19], v[2:3] offset:112

; #define LAS __attribute__((address_space(3)))
; __device__ __forceinline__ unsigned f2bf(float f) { unsigned u = __builtin_bit_cast(unsigned, f); return (u + 0x7fffu + ((u >> 16) & 1u)) >> 16; }
; __device__ __forceinline__ float bf1(bf16 h) { return __uint_as_float(((unsigned)h) << 16); }
; __device__ __forceinline__ void pool_item(const Args& A, const Ctx& C0, int l, int row0, int t0, int pos0, const float* hist, float* outpool) {
;     ...
;     { const int c = C.tid, gc = c >> 7, wdc = 2 << gc;
;       float s = 0.f;
;       for (int i = 0; i < wdc; ++i) s += bf1(P[(15 - i) * PP + c]);
; #pragma unroll 4
;       for (int t = 0; t < 32; ++t) { const int pos = pos0 + t; const float inv = 1.f / (float)((pos + 1) < wdc ? (pos + 1) : wdc);
;           const float cur = bf1(P[(15 + t) * PP + c]);
;           Dm[t * PP + c] = (bf16)f2bf(s * inv - cur);
;           s += bf1(P[(16 + t) * PP + c]) - bf1(P[(16 + t - wdc) * PP + c]); } }
;     __syncthreads();
;     const int g = C.wave & 3, ddh = C.wave >> 2, tk = C.lane & 31, h = C.lane >> 5;
;     const bf16* PW = WS_PTR(const bf16, WS_PWT) + (size_t)(l * 4 + g) * 128 * 128;
;     f32x16 acc[2];
; #pragma unroll
;     for (int dt = 0; dt < 2; ++dt)
; #pragma unroll
;         for (int r = 0; r < 16; ++r) acc[dt][r] = 0.f;
; #pragma unroll
;     for (int ks = 0; ks < 8; ++ks) { const bf16x8 df = *(const LAS bf16x8*)(Dm + tk * PP + g * 128 + ks * 16 + 8 * h);
; #pragma unroll
;         for (int dt = 0; dt < 2; ++dt) { const bf16x8 af = *(const bf16x8*)(PW + (size_t)(ddh * 64 + dt * 32 + tk) * 128 + ks * 16 + 8 * h);
;             acc[dt] = __builtin_amdgcn_mfma_f32_32x32x16_bf16(af, df, acc[dt], 0, 0, 0); }
;     }
.LBB0_757:
	s_add_i32 s1, s16, s0
	s_add_i32 s2, s1, 1
	v_min_i32_e32 v3, s2, v0
	v_cvt_f32_i32_e32 v3, v3
	s_waitcnt lgkmcnt(0)
	v_lshlrev_b32_e32 v5, 16, v5
	s_add_i32 s0, s0, 4
	v_div_scale_f32 v7, s[2:3], v3, v3, 1.0
	v_rcp_f32_e32 v8, v7
	s_add_i32 s2, s1, 2
	v_fma_f32 v9, -v7, v8, 1.0
	v_fmac_f32_e32 v8, v9, v8
	v_div_scale_f32 v9, vcc, 1.0, v3, 1.0
	v_mul_f32_e32 v10, v9, v8
	v_fma_f32 v11, -v7, v10, v9
	v_fmac_f32_e32 v10, v11, v8
	v_fma_f32 v7, -v7, v10, v9
	v_div_fmas_f32 v7, v7, v8, v10
	v_div_fixup_f32 v3, v7, v3, 1.0
	v_fma_f32 v3, v4, v3, -v5
	v_bfe_u32 v5, v3, 16, 1
	v_add3_u32 v3, v3, v5, s33
	ds_write_b16_d16_hi v6, v3 offset:33280
	v_add_u32_e32 v3, v6, v2
	ds_read_u16 v5, v3 offset:1040
	ds_read_u16 v7, v6 offset:1040
	s_waitcnt lgkmcnt(1)
	v_lshlrev_b32_e32 v5, 16, v5
	s_waitcnt lgkmcnt(0)
	v_lshlrev_b32_e32 v7, 16, v7
	v_sub_f32_e32 v5, v7, v5
	v_add_f32_e32 v4, v4, v5
	v_min_i32_e32 v5, s2, v0
	v_cvt_f32_i32_e32 v5, v5
	v_div_scale_f32 v8, s[2:3], v5, v5, 1.0
	v_rcp_f32_e32 v9, v8
	s_add_i32 s2, s1, 3
	s_add_i32 s1, s1, 4
	s_cmp_eq_u32 s0, 32
	v_fma_f32 v10, -v8, v9, 1.0
	v_fmac_f32_e32 v9, v10, v9
	v_div_scale_f32 v10, vcc, 1.0, v5, 1.0
	v_mul_f32_e32 v11, v10, v9
	v_fma_f32 v12, -v8, v11, v10
	v_fmac_f32_e32 v11, v12, v9
	v_fma_f32 v8, -v8, v11, v10
	v_div_fmas_f32 v8, v8, v9, v11
	v_div_fixup_f32 v5, v8, v5, 1.0
	v_fma_f32 v5, v4, v5, -v7
	v_bfe_u32 v7, v5, 16, 1
	v_add3_u32 v5, v5, v7, s33
	ds_write_b16_d16_hi v6, v5 offset:34320
	ds_read_u16 v5, v3 offset:2080
	ds_read_u16 v7, v6 offset:2080
	s_waitcnt lgkmcnt(1)
	v_lshlrev_b32_e32 v5, 16, v5
	s_waitcnt lgkmcnt(0)
	v_lshlrev_b32_e32 v7, 16, v7
	v_sub_f32_e32 v5, v7, v5
	v_add_f32_e32 v4, v4, v5
	v_min_i32_e32 v5, s2, v0
	v_cvt_f32_i32_e32 v5, v5
	v_div_scale_f32 v8, s[2:3], v5, v5, 1.0
	v_rcp_f32_e32 v9, v8
	s_nop 0
	v_fma_f32 v10, -v8, v9, 1.0
	v_fmac_f32_e32 v9, v10, v9
	v_div_scale_f32 v10, vcc, 1.0, v5, 1.0
	v_mul_f32_e32 v11, v10, v9
	v_fma_f32 v12, -v8, v11, v10
	v_fmac_f32_e32 v11, v12, v9
	v_fma_f32 v8, -v8, v11, v10
	v_div_fmas_f32 v8, v8, v9, v11
	v_div_fixup_f32 v5, v8, v5, 1.0
	v_fma_f32 v5, v4, v5, -v7
	v_bfe_u32 v7, v5, 16, 1
	v_add3_u32 v5, v5, v7, s33
	ds_write_b16_d16_hi v6, v5 offset:35360
	ds_read_u16 v5, v3 offset:3120
	ds_read_u16 v7, v6 offset:3120
	s_waitcnt lgkmcnt(1)
	v_lshlrev_b32_e32 v5, 16, v5
	s_waitcnt lgkmcnt(0)
	v_lshlrev_b32_e32 v7, 16, v7
	v_sub_f32_e32 v5, v7, v5
	v_add_f32_e32 v4, v4, v5
	v_min_i32_e32 v5, s1, v0
	v_cvt_f32_i32_e32 v5, v5
	v_div_scale_f32 v8, s[2:3], v5, v5, 1.0
	v_rcp_f32_e32 v9, v8
	s_nop 0
	v_fma_f32 v10, -v8, v9, 1.0
	v_fmac_f32_e32 v9, v10, v9
	v_div_scale_f32 v10, vcc, 1.0, v5, 1.0
	v_mul_f32_e32 v11, v10, v9
	v_fma_f32 v12, -v8, v11, v10
	v_fmac_f32_e32 v11, v12, v9
	v_fma_f32 v8, -v8, v11, v10
	v_div_fmas_f32 v8, v8, v9, v11
	v_div_fixup_f32 v5, v8, v5, 1.0
	v_fma_f32 v5, v4, v5, -v7
	v_bfe_u32 v7, v5, 16, 1
	v_add3_u32 v5, v5, v7, s33
	ds_write_b16_d16_hi v6, v5 offset:36400
	ds_read_u16 v5, v6 offset:4160
	ds_read_u16 v3, v3 offset:4160
	v_add_u32_e32 v7, 0x1040, v6
	s_waitcnt lgkmcnt(1)
	v_lshlrev_b32_e32 v6, 16, v5
	s_waitcnt lgkmcnt(0)
	v_lshlrev_b32_e32 v3, 16, v3
	v_sub_f32_e32 v3, v6, v3
	v_add_f32_e32 v4, v4, v3
	v_mov_b32_e32 v6, v7
	s_cbranch_scc0 .LBB0_757
	s_bfe_u32 s0, s75, 0x20006
	v_readlane_b32 s1, v255, 46
	s_or_b32 s2, s0, s1
	s_ashr_i32 s3, s2, 31
	s_lshl_b64 s[2:3], s[2:3], 15
	s_add_u32 s2, s24, s2
	v_bfe_u32 v48, v34, 5, 1
	v_and_b32_e32 v49, 31, v34
	s_addc_u32 s3, s25, s3
	s_lshl_b32 s1, s0, 8
	v_mul_u32_u24_e32 v2, 0x410, v49
	s_add_i32 s1, s1, 0
	v_lshlrev_b32_e32 v0, 4, v48
	v_add3_u32 v50, s1, v2, v0
	s_ashr_i32 s1, s75, 2
	s_andn2_b32 s1, s1, 63
	v_or_b32_e32 v10, s1, v49
	v_lshl_add_u64 v[2:3], s[2:3], 0, v[0:1]
	s_mov_b64 s[2:3], 0x7900000
	v_ashrrev_i32_e32 v11, 31, v10
	v_lshl_add_u64 v[12:13], v[2:3], 0, s[2:3]
	v_lshlrev_b64 v[2:3], 8, v[10:11]
	v_lshl_add_u64 v[44:45], v[12:13], 0, v[2:3]
	s_barrier
	s_lshl_b32 s0, s0, 7
	s_add_i32 s0, s0, s1
	v_add_u32_e32 v0, s10, v49
	s_cmp_lg_u64 s[60:61], 0
	s_movk_i32 s2, 0x1e00
	v_or_b32_e32 v2, 32, v10
	v_ashrrev_i32_e32 v3, 31, v2
	v_lshlrev_b64 v[2:3], 8, v[2:3]
	v_lshl_add_u64 v[46:47], v[12:13], 0, v[2:3]
	global_load_dwordx4 v[148:151], v[44:45], off
	global_load_dwordx4 v[180:183], v[46:47], off
	global_load_dwordx4 v[152:155], v[44:45], off offset:32
	global_load_dwordx4 v[188:191], v[46:47], off offset:32
	global_load_dwordx4 v[156:159], v[44:45], off offset:64
	global_load_dwordx4 v[192:195], v[46:47], off offset:64
	global_load_dwordx4 v[160:163], v[44:45], off offset:96
	global_load_dwordx4 v[196:199], v[46:47], off offset:96
	global_load_dwordx4 v[164:167], v[44:45], off offset:128
	global_load_dwordx4 v[200:203], v[46:47], off offset:128
	global_load_dwordx4 v[168:171], v[44:45], off offset:160
	global_load_dwordx4 v[208:211], v[46:47], off offset:160
	global_load_dwordx4 v[172:175], v[44:45], off offset:192
	global_load_dwordx4 v[212:215], v[46:47], off offset:192
	global_load_dwordx4 v[176:179], v[44:45], off offset:224
	global_load_dwordx4 v[216:219], v[46:47], off offset:224
	ds_read_b128 v[220:223], v50 offset:48880
	ds_read_b128 v[224:227], v50 offset:48912
	ds_read_b128 v[232:235], v50 offset:48944
	ds_read_b128 v[236:239], v50 offset:48976
	ds_read_b128 v[240:243], v50 offset:49008
	ds_read_b128 v[244:247], v50 offset:49040
	ds_read_b128 v[40:43], v50 offset:49072
	ds_read_b128 v[36:39], v50 offset:49104
	s_waitcnt vmcnt(15) lgkmcnt(7)
	v_mfma_f32_32x32x16_bf16 v[18:33], v[148:151], v[220:223], 0
	s_waitcnt vmcnt(14)
	v_mfma_f32_32x32x16_bf16 v[2:17], v[180:183], v[220:223], 0
	s_waitcnt vmcnt(13) lgkmcnt(6)
; #define LAS __attribute__((address_space(3)))
; __device__ __forceinline__ unsigned pk2(float lo, float hi) { return f2bf(lo) | (f2bf(hi) << 16); }
; __device__ __forceinline__ float bflo(unsigned w) { return __uint_as_float(w << 16); }
; __device__ __forceinline__ float bfhi(unsigned w) { return __uint_as_float(w & 0xffff0000u); }
; __device__ __forceinline__ float silu(float x) { return x / (1.f + __expf(-x)); }
; __device__ __forceinline__ void pool_item(const Args& A, const Ctx& C0, int l, int row0, int t0, int pos0, const float* hist, float* outpool) {
;     ...
;     for (int ks = 0; ks < 8; ++ks) { const bf16x8 df = *(const LAS bf16x8*)(Dm + tk * PP + g * 128 + ks * 16 + 8 * h);
; #pragma unroll
;         for (int dt = 0; dt < 2; ++dt) { const bf16x8 af = *(const bf16x8*)(PW + (size_t)(ddh * 64 + dt * 32 + tk) * 128 + ks * 16 + 8 * h);
;             acc[dt] = __builtin_amdgcn_mfma_f32_32x32x16_bf16(af, df, acc[dt], 0, 0, 0); }
;     }
;     const size_t row = (size_t)(row0 + tk);
;     const float* psc = A.in[I_POOLS] + l * 512;
; #pragma unroll
;     for (int dt = 0; dt < 2; ++dt)
; #pragma unroll
;         for (int rq = 0; rq < 4; ++rq) { const int cc = g * 128 + ddh * 64 + dt * 32 + 8 * rq + 4 * h;
;             const v2u gx = *(const v2u*)(U + row * DIN + C_GP + cc); const f32x4 sc = *(const f32x4*)(psc + cc);
;             const float o0 = acc[dt][4 * rq] * sc.x * silu(bflo(gx.x)), o1 = acc[dt][4 * rq + 1] * sc.y * silu(bfhi(gx.x)), o2 = acc[dt][4 * rq + 2] * sc.z * silu(bflo(gx.y)), o3 = acc[dt][4 * rq + 3] * sc.w * silu(bfhi(gx.y));
;             v2u o; o.x = pk2(o0, o1); o.y = pk2(o2, o3);
;             *(v2u*)(MIX + row * D + cc) = o; }
	v_mfma_f32_32x32x16_bf16 v[18:33], v[152:155], v[224:227], v[18:33]
	s_waitcnt vmcnt(12)
	v_mfma_f32_32x32x16_bf16 v[2:17], v[188:191], v[224:227], v[2:17]
	s_waitcnt vmcnt(11) lgkmcnt(5)
	v_mfma_f32_32x32x16_bf16 v[18:33], v[156:159], v[232:235], v[18:33]
	s_waitcnt vmcnt(10)
	v_mfma_f32_32x32x16_bf16 v[2:17], v[192:195], v[232:235], v[2:17]
	s_waitcnt vmcnt(9) lgkmcnt(4)
	v_mfma_f32_32x32x16_bf16 v[18:33], v[160:163], v[236:239], v[18:33]
	s_waitcnt vmcnt(8)
	v_mfma_f32_32x32x16_bf16 v[2:17], v[196:199], v[236:239], v[2:17]
	s_waitcnt vmcnt(7) lgkmcnt(3)
	v_mfma_f32_32x32x16_bf16 v[18:33], v[164:167], v[240:243], v[18:33]
	s_waitcnt vmcnt(6)
	v_mfma_f32_32x32x16_bf16 v[2:17], v[200:203], v[240:243], v[2:17]
	s_waitcnt vmcnt(5) lgkmcnt(2)
	v_mfma_f32_32x32x16_bf16 v[18:33], v[168:171], v[244:247], v[18:33]
	s_waitcnt vmcnt(4)
	v_mfma_f32_32x32x16_bf16 v[2:17], v[208:211], v[244:247], v[2:17]
	s_waitcnt vmcnt(3) lgkmcnt(1)
	v_mfma_f32_32x32x16_bf16 v[18:33], v[172:175], v[40:43], v[18:33]
	s_waitcnt vmcnt(2)
	v_mfma_f32_32x32x16_bf16 v[2:17], v[212:215], v[40:43], v[2:17]
	s_waitcnt vmcnt(1) lgkmcnt(0)
	v_mfma_f32_32x32x16_bf16 v[18:33], v[176:179], v[36:39], v[18:33]
	s_nop 11
	v_mov_b32_e32 v52, v18
	v_mov_b32_e32 v53, v20
	s_waitcnt vmcnt(0)
	v_mfma_f32_32x32x16_bf16 v[2:17], v[216:219], v[36:39], v[2:17]
	v_lshl_or_b32 v36, v48, 2, s0
	v_mov_b64_e32 v[38:39], s[62:63]
	s_movk_i32 s0, 0x2b00
	v_ashrrev_i32_e32 v37, 31, v36
	v_mad_u64_u32 v[38:39], s[0:1], v0, s0, v[38:39]
	v_lshlrev_b64 v[46:47], 1, v[36:37]
	v_lshl_add_u64 v[38:39], v[38:39], 0, v[46:47]
	flat_load_dwordx2 v[48:49], v[38:39] offset:1024
	v_lshlrev_b64 v[40:41], 12, v[0:1]
	v_lshl_add_u64 v[36:37], v[36:37], 2, s[78:79]
	v_lshl_add_u64 v[44:45], s[24:25], 0, v[40:41]
	global_load_dwordx4 v[40:43], v[36:37], off
	s_waitcnt vmcnt(0) lgkmcnt(0)
	v_lshlrev_b32_e32 v0, 16, v49
	v_lshlrev_b32_e32 v56, 16, v48
	v_mul_f32_e32 v50, 0xbfb8aa3b, v56
	v_mul_f32_e32 v18, 0xbfb8aa3b, v0
	v_exp_f32_e32 v50, v50
	v_exp_f32_e32 v51, v18
	v_mov_b32_e32 v54, v40
	v_mov_b32_e32 v55, v42
	v_and_b32_e32 v57, 0xffff0000, v49
	v_pk_add_f32 v[50:51], v[50:51], 1.0 op_sel_hi:[1,0]
	v_and_b32_e32 v58, 0xffff0000, v48
	v_div_scale_f32 v18, s[0:1], v51, v51, v0
	v_rcp_f32_e32 v20, v18
	v_mul_f32_e32 v48, 0xbfb8aa3b, v58
	v_exp_f32_e32 v48, v48
	v_pk_mul_f32 v[52:53], v[52:53], v[54:55]
	v_fma_f32 v40, -v18, v20, 1.0
	v_fmac_f32_e32 v20, v40, v20
	v_div_scale_f32 v40, vcc, v0, v51, v0
	v_mul_f32_e32 v42, v40, v20
	v_fma_f32 v49, -v18, v42, v40
	v_fmac_f32_e32 v42, v49, v20
	v_fma_f32 v18, -v18, v42, v40
	v_div_fmas_f32 v18, v18, v20, v42
	v_div_fixup_f32 v51, v18, v51, v0
	v_div_scale_f32 v0, s[0:1], v50, v50, v56
	v_rcp_f32_e32 v18, v0
	s_nop 0
	v_fma_f32 v20, -v0, v18, 1.0
	v_fmac_f32_e32 v18, v20, v18
	v_div_scale_f32 v20, vcc, v56, v50, v56
	v_mul_f32_e32 v40, v20, v18
	v_fma_f32 v42, -v0, v40, v20
	v_fmac_f32_e32 v40, v42, v18
	v_fma_f32 v0, -v0, v40, v20
	v_div_fmas_f32 v0, v0, v18, v40
	v_div_fixup_f32 v50, v0, v50, v56
	v_mul_f32_e32 v0, 0xbfb8aa3b, v57
	v_exp_f32_e32 v49, v0
	v_mov_b32_e32 v20, v19
	v_mov_b32_e32 v42, v41
	v_pk_mul_f32 v[18:19], v[20:21], v[42:43]
	v_pk_add_f32 v[20:21], v[48:49], 1.0 op_sel_hi:[1,0]
	v_pk_mul_f32 v[50:51], v[52:53], v[50:51]
	v_div_scale_f32 v0, s[0:1], v21, v21, v57
	v_rcp_f32_e32 v40, v0
	s_nop 0
	v_fma_f32 v41, -v0, v40, 1.0
	v_fmac_f32_e32 v40, v41, v40
	v_div_scale_f32 v41, vcc, v57, v21, v57
	v_mul_f32_e32 v42, v41, v40
	v_fma_f32 v43, -v0, v42, v41
	v_fmac_f32_e32 v42, v43, v40
	v_fma_f32 v0, -v0, v42, v41
	v_div_fmas_f32 v0, v0, v40, v42
	v_div_fixup_f32 v21, v0, v21, v57
	v_div_scale_f32 v0, s[0:1], v20, v20, v58
	v_rcp_f32_e32 v40, v0
	s_mov_b64 s[0:1], 0x7b27900
	v_fma_f32 v41, -v0, v40, 1.0
	v_fmac_f32_e32 v40, v41, v40
	v_div_scale_f32 v41, vcc, v58, v20, v58
	v_mul_f32_e32 v42, v41, v40
	v_fma_f32 v43, -v0, v42, v41
	v_fmac_f32_e32 v42, v43, v40
	v_fma_f32 v0, -v0, v42, v41
	v_div_fmas_f32 v0, v0, v40, v42
	v_div_fixup_f32 v20, v0, v20, v58
	v_pk_mul_f32 v[18:19], v[18:19], v[20:21]
	v_lshl_add_u64 v[40:41], v[44:45], 0, v[46:47]
	v_cvt_pk_bf16_f32 v21, v51, v19
	v_cvt_pk_bf16_f32 v20, v50, v18
	v_lshl_add_u64 v[18:19], v[40:41], 0, s[0:1]
	s_mov_b32 s0, 0x7b27000
	v_add_co_u32_e32 v40, vcc, s0, v40
	v_mov_b32_e32 v46, v22
	s_nop 0
	v_addc_co_u32_e32 v41, vcc, 0, v41, vcc
	flat_store_dwordx2 v[40:41], v[20:21] offset:2304
	flat_load_dwordx2 v[20:21], v[38:39] offset:1040
	s_nop 0
	global_load_dwordx4 v[40:43], v[36:37], off offset:32
	v_mov_b32_e32 v47, v24
	s_waitcnt vmcnt(0) lgkmcnt(0)
; __device__ __forceinline__ unsigned pk2(float lo, float hi) { return f2bf(lo) | (f2bf(hi) << 16); }
; __device__ __forceinline__ float bflo(unsigned w) { return __uint_as_float(w << 16); }
; __device__ __forceinline__ float bfhi(unsigned w) { return __uint_as_float(w & 0xffff0000u); }
; __device__ __forceinline__ float silu(float x) { return x / (1.f + __expf(-x)); }
; __device__ __forceinline__ void pool_item(const Args& A, const Ctx& C0, int l, int row0, int t0, int pos0, const float* hist, float* outpool) {
;     ...
; #pragma unroll
;     for (int dt = 0; dt < 2; ++dt)
; #pragma unroll
;         for (int rq = 0; rq < 4; ++rq) { const int cc = g * 128 + ddh * 64 + dt * 32 + 8 * rq + 4 * h;
;             const v2u gx = *(const v2u*)(U + row * DIN + C_GP + cc); const f32x4 sc = *(const f32x4*)(psc + cc);
;             const float o0 = acc[dt][4 * rq] * sc.x * silu(bflo(gx.x)), o1 = acc[dt][4 * rq + 1] * sc.y * silu(bfhi(gx.x)), o2 = acc[dt][4 * rq + 2] * sc.z * silu(bflo(gx.y)), o3 = acc[dt][4 * rq + 3] * sc.w * silu(bfhi(gx.y));
;             v2u o; o.x = pk2(o0, o1); o.y = pk2(o2, o3);
;             *(v2u*)(MIX + row * D + cc) = o; }
	v_lshlrev_b32_e32 v0, 16, v21
	v_lshlrev_b32_e32 v50, 16, v20
	v_mul_f32_e32 v44, 0xbfb8aa3b, v50
	v_and_b32_e32 v51, 0xffff0000, v21
	v_mul_f32_e32 v21, 0xbfb8aa3b, v0
	v_exp_f32_e32 v44, v44
	v_exp_f32_e32 v45, v21
	v_mov_b32_e32 v48, v40
	v_mov_b32_e32 v49, v42
	v_and_b32_e32 v52, 0xffff0000, v20
	v_pk_add_f32 v[44:45], v[44:45], 1.0 op_sel_hi:[1,0]
	v_mul_f32_e32 v20, 0xbfb8aa3b, v52
	v_div_scale_f32 v21, s[0:1], v45, v45, v0
	v_rcp_f32_e32 v22, v21
	v_exp_f32_e32 v20, v20
	v_pk_mul_f32 v[46:47], v[46:47], v[48:49]
	v_fma_f32 v24, -v21, v22, 1.0
	v_fmac_f32_e32 v22, v24, v22
	v_div_scale_f32 v24, vcc, v0, v45, v0
	v_mul_f32_e32 v40, v24, v22
	v_fma_f32 v42, -v21, v40, v24
	v_fmac_f32_e32 v40, v42, v22
	v_fma_f32 v21, -v21, v40, v24
	v_div_fmas_f32 v21, v21, v22, v40
	v_div_fixup_f32 v45, v21, v45, v0
	v_div_scale_f32 v0, s[0:1], v44, v44, v50
	v_rcp_f32_e32 v21, v0
	v_mov_b32_e32 v42, v41
	v_fma_f32 v22, -v0, v21, 1.0
	v_fmac_f32_e32 v21, v22, v21
	v_div_scale_f32 v22, vcc, v50, v44, v50
	v_mul_f32_e32 v24, v22, v21
	v_fma_f32 v40, -v0, v24, v22
	v_fmac_f32_e32 v24, v40, v21
	v_fma_f32 v0, -v0, v24, v22
	v_div_fmas_f32 v0, v0, v21, v24
	v_div_fixup_f32 v44, v0, v44, v50
	v_mul_f32_e32 v0, 0xbfb8aa3b, v51
	v_exp_f32_e32 v21, v0
	v_mov_b32_e32 v24, v23
	v_pk_mul_f32 v[22:23], v[24:25], v[42:43]
	v_pk_mul_f32 v[44:45], v[46:47], v[44:45]
	v_pk_add_f32 v[20:21], v[20:21], 1.0 op_sel_hi:[1,0]
	v_mov_b32_e32 v42, v26
	v_div_scale_f32 v0, s[0:1], v21, v21, v51
	v_rcp_f32_e32 v24, v0
	v_mov_b32_e32 v43, v28
	v_fma_f32 v25, -v0, v24, 1.0
	v_fmac_f32_e32 v24, v25, v24
	v_div_scale_f32 v25, vcc, v51, v21, v51
	v_mul_f32_e32 v40, v25, v24
	v_fma_f32 v41, -v0, v40, v25
	v_fmac_f32_e32 v40, v41, v24
	v_fma_f32 v0, -v0, v40, v25
	v_div_fmas_f32 v0, v0, v24, v40
	v_div_fixup_f32 v21, v0, v21, v51
	v_div_scale_f32 v0, s[0:1], v20, v20, v52
	v_rcp_f32_e32 v24, v0
	s_nop 0
	v_fma_f32 v25, -v0, v24, 1.0
	v_fmac_f32_e32 v24, v25, v24
	v_div_scale_f32 v25, vcc, v52, v20, v52
	v_mul_f32_e32 v40, v25, v24
	v_fma_f32 v41, -v0, v40, v25
	v_fmac_f32_e32 v40, v41, v24
	v_fma_f32 v0, -v0, v40, v25
	v_div_fmas_f32 v0, v0, v24, v40
	v_div_fixup_f32 v20, v0, v20, v52
	v_pk_mul_f32 v[20:21], v[22:23], v[20:21]
	v_cvt_pk_bf16_f32 v21, v45, v21
	v_cvt_pk_bf16_f32 v20, v44, v20
	flat_store_dwordx2 v[18:19], v[20:21] offset:16
	flat_load_dwordx2 v[24:25], v[38:39] offset:1056
	s_nop 0
	global_load_dwordx4 v[20:23], v[36:37], off offset:64
	s_waitcnt vmcnt(0) lgkmcnt(0)
	v_lshlrev_b32_e32 v0, 16, v25
	v_lshlrev_b32_e32 v46, 16, v24
	v_mul_f32_e32 v40, 0xbfb8aa3b, v46
	v_mov_b32_e32 v44, v20
	v_mul_f32_e32 v20, 0xbfb8aa3b, v0
	v_exp_f32_e32 v40, v40
	v_exp_f32_e32 v41, v20
	v_mov_b32_e32 v45, v22
	v_and_b32_e32 v47, 0xffff0000, v25
	v_and_b32_e32 v48, 0xffff0000, v24
	v_pk_add_f32 v[40:41], v[40:41], 1.0 op_sel_hi:[1,0]
	v_mul_f32_e32 v24, 0xbfb8aa3b, v48
	v_div_scale_f32 v20, s[0:1], v41, v41, v0
	v_rcp_f32_e32 v22, v20
	v_exp_f32_e32 v24, v24
	v_pk_mul_f32 v[42:43], v[42:43], v[44:45]
	v_fma_f32 v25, -v20, v22, 1.0
	v_fmac_f32_e32 v22, v25, v22
	v_div_scale_f32 v25, vcc, v0, v41, v0
	v_mul_f32_e32 v26, v25, v22
	v_fma_f32 v28, -v20, v26, v25
	v_fmac_f32_e32 v26, v28, v22
	v_fma_f32 v20, -v20, v26, v25
	v_div_fmas_f32 v20, v20, v22, v26
	v_div_fixup_f32 v41, v20, v41, v0
	v_div_scale_f32 v0, s[0:1], v40, v40, v46
	v_rcp_f32_e32 v20, v0
	v_mov_b32_e32 v28, v27
	v_fma_f32 v22, -v0, v20, 1.0
	v_fmac_f32_e32 v20, v22, v20
	v_div_scale_f32 v22, vcc, v46, v40, v46
	v_mul_f32_e32 v25, v22, v20
	v_fma_f32 v26, -v0, v25, v22
	v_fmac_f32_e32 v25, v26, v20
	v_fma_f32 v0, -v0, v25, v22
	v_div_fmas_f32 v0, v0, v20, v25
	v_div_fixup_f32 v40, v0, v40, v46
	v_mul_f32_e32 v0, 0xbfb8aa3b, v47
	v_exp_f32_e32 v25, v0
	v_mov_b32_e32 v22, v21
	v_pk_mul_f32 v[20:21], v[28:29], v[22:23]
	v_pk_mul_f32 v[40:41], v[42:43], v[40:41]
	v_pk_add_f32 v[22:23], v[24:25], 1.0 op_sel_hi:[1,0]
	v_mov_b32_e32 v28, v30
	v_div_scale_f32 v0, s[0:1], v23, v23, v47
	v_rcp_f32_e32 v24, v0
	v_mov_b32_e32 v29, v32
	v_fma_f32 v25, -v0, v24, 1.0
	v_fmac_f32_e32 v24, v25, v24
	v_div_scale_f32 v25, vcc, v47, v23, v47
	v_mul_f32_e32 v26, v25, v24
	v_fma_f32 v27, -v0, v26, v25
	v_fmac_f32_e32 v26, v27, v24
	v_fma_f32 v0, -v0, v26, v25
	v_div_fmas_f32 v0, v0, v24, v26
	v_div_fixup_f32 v23, v0, v23, v47
	v_div_scale_f32 v0, s[0:1], v22, v22, v48
	v_rcp_f32_e32 v24, v0
	s_nop 0
	v_fma_f32 v25, -v0, v24, 1.0
	v_fmac_f32_e32 v24, v25, v24
	v_div_scale_f32 v25, vcc, v48, v22, v48
	v_mul_f32_e32 v26, v25, v24
	v_fma_f32 v27, -v0, v26, v25
	v_fmac_f32_e32 v26, v27, v24
	v_fma_f32 v0, -v0, v26, v25
	v_div_fmas_f32 v0, v0, v24, v26
	v_div_fixup_f32 v22, v0, v22, v48
	v_pk_mul_f32 v[20:21], v[20:21], v[22:23]
	v_cvt_pk_bf16_f32 v21, v41, v21
	v_cvt_pk_bf16_f32 v20, v40, v20
	flat_store_dwordx2 v[18:19], v[20:21] offset:32
	flat_load_dwordx2 v[20:21], v[38:39] offset:1072
	s_nop 0
	global_load_dwordx4 v[22:25], v[36:37], off offset:96
	s_waitcnt vmcnt(0) lgkmcnt(0)
; __device__ __forceinline__ unsigned pk2(float lo, float hi) { return f2bf(lo) | (f2bf(hi) << 16); }
; __device__ __forceinline__ float bflo(unsigned w) { return __uint_as_float(w << 16); }
; __device__ __forceinline__ float bfhi(unsigned w) { return __uint_as_float(w & 0xffff0000u); }
; __device__ __forceinline__ float silu(float x) { return x / (1.f + __expf(-x)); }
; __device__ __forceinline__ void pool_item(const Args& A, const Ctx& C0, int l, int row0, int t0, int pos0, const float* hist, float* outpool) {
;     ...
; #pragma unroll
;     for (int dt = 0; dt < 2; ++dt)
; #pragma unroll
;         for (int rq = 0; rq < 4; ++rq) { const int cc = g * 128 + ddh * 64 + dt * 32 + 8 * rq + 4 * h;
;             const v2u gx = *(const v2u*)(U + row * DIN + C_GP + cc); const f32x4 sc = *(const f32x4*)(psc + cc);
;             const float o0 = acc[dt][4 * rq] * sc.x * silu(bflo(gx.x)), o1 = acc[dt][4 * rq + 1] * sc.y * silu(bfhi(gx.x)), o2 = acc[dt][4 * rq + 2] * sc.z * silu(bflo(gx.y)), o3 = acc[dt][4 * rq + 3] * sc.w * silu(bfhi(gx.y));
;             v2u o; o.x = pk2(o0, o1); o.y = pk2(o2, o3);
;             *(v2u*)(MIX + row * D + cc) = o; }
	v_lshlrev_b32_e32 v0, 16, v21
	v_lshlrev_b32_e32 v42, 16, v20
	v_mul_f32_e32 v26, 0xbfb8aa3b, v42
	v_and_b32_e32 v43, 0xffff0000, v21
	v_mul_f32_e32 v21, 0xbfb8aa3b, v0
	v_exp_f32_e32 v26, v26
	v_exp_f32_e32 v27, v21
	v_mov_b32_e32 v40, v22
	v_mov_b32_e32 v41, v24
	v_and_b32_e32 v44, 0xffff0000, v20
	v_pk_add_f32 v[26:27], v[26:27], 1.0 op_sel_hi:[1,0]
	v_mul_f32_e32 v20, 0xbfb8aa3b, v44
	v_div_scale_f32 v21, s[0:1], v27, v27, v0
	v_rcp_f32_e32 v22, v21
	v_exp_f32_e32 v20, v20
	v_pk_mul_f32 v[28:29], v[28:29], v[40:41]
	v_fma_f32 v24, -v21, v22, 1.0
	v_fmac_f32_e32 v22, v24, v22
	v_div_scale_f32 v24, vcc, v0, v27, v0
	v_mul_f32_e32 v30, v24, v22
	v_fma_f32 v32, -v21, v30, v24
	v_fmac_f32_e32 v30, v32, v22
	v_fma_f32 v21, -v21, v30, v24
	v_div_fmas_f32 v21, v21, v22, v30
	v_div_fixup_f32 v27, v21, v27, v0
	v_div_scale_f32 v0, s[0:1], v26, v26, v42
	v_rcp_f32_e32 v21, v0
	v_mov_b32_e32 v32, v31
	v_fma_f32 v22, -v0, v21, 1.0
	v_fmac_f32_e32 v21, v22, v21
	v_div_scale_f32 v22, vcc, v42, v26, v42
	v_mul_f32_e32 v24, v22, v21
	v_fma_f32 v30, -v0, v24, v22
	v_fmac_f32_e32 v24, v30, v21
	v_fma_f32 v0, -v0, v24, v22
	v_div_fmas_f32 v0, v0, v21, v24
	v_div_fixup_f32 v26, v0, v26, v42
	v_mul_f32_e32 v0, 0xbfb8aa3b, v43
	v_exp_f32_e32 v21, v0
	v_mov_b32_e32 v24, v23
	v_pk_mul_f32 v[22:23], v[32:33], v[24:25]
	v_pk_mul_f32 v[26:27], v[28:29], v[26:27]
	v_pk_add_f32 v[20:21], v[20:21], 1.0 op_sel_hi:[1,0]
	s_nop 0
	v_div_scale_f32 v0, s[0:1], v21, v21, v43
	v_rcp_f32_e32 v24, v0
	s_nop 0
	v_fma_f32 v25, -v0, v24, 1.0
	v_fmac_f32_e32 v24, v25, v24
	v_div_scale_f32 v25, vcc, v43, v21, v43
	v_mul_f32_e32 v28, v25, v24
	v_fma_f32 v29, -v0, v28, v25
	v_fmac_f32_e32 v28, v29, v24
	v_fma_f32 v0, -v0, v28, v25
	v_div_fmas_f32 v0, v0, v24, v28
	v_div_fixup_f32 v21, v0, v21, v43
	v_div_scale_f32 v0, s[0:1], v20, v20, v44
	v_rcp_f32_e32 v24, v0
	s_nop 0
	v_fma_f32 v25, -v0, v24, 1.0
	v_fmac_f32_e32 v24, v25, v24
	v_div_scale_f32 v25, vcc, v44, v20, v44
	v_mul_f32_e32 v28, v25, v24
	v_fma_f32 v29, -v0, v28, v25
	v_fmac_f32_e32 v28, v29, v24
	v_fma_f32 v0, -v0, v28, v25
	v_div_fmas_f32 v0, v0, v24, v28
	v_div_fixup_f32 v20, v0, v20, v44
	v_pk_mul_f32 v[20:21], v[22:23], v[20:21]
	v_cvt_pk_bf16_f32 v21, v27, v21
	v_cvt_pk_bf16_f32 v20, v26, v20
	flat_store_dwordx2 v[18:19], v[20:21] offset:48
	flat_load_dwordx2 v[20:21], v[38:39] offset:1088
	s_nop 0
	global_load_dwordx4 v[22:25], v[36:37], off offset:128
	v_mov_b32_e32 v28, v2
	v_mov_b32_e32 v29, v4
	s_waitcnt vmcnt(0) lgkmcnt(0)
	v_lshlrev_b32_e32 v0, 16, v21
	v_lshlrev_b32_e32 v32, 16, v20
	v_mul_f32_e32 v26, 0xbfb8aa3b, v32
	v_mul_f32_e32 v2, 0xbfb8aa3b, v0
	v_exp_f32_e32 v26, v26
	v_exp_f32_e32 v27, v2
	v_and_b32_e32 v33, 0xffff0000, v21
	v_mov_b32_e32 v30, v22
	v_mov_b32_e32 v31, v24
	v_pk_add_f32 v[26:27], v[26:27], 1.0 op_sel_hi:[1,0]
	v_and_b32_e32 v40, 0xffff0000, v20
	v_div_scale_f32 v2, s[0:1], v27, v27, v0
	v_rcp_f32_e32 v4, v2
	v_mul_f32_e32 v20, 0xbfb8aa3b, v40
	v_exp_f32_e32 v20, v20
	v_pk_mul_f32 v[28:29], v[28:29], v[30:31]
	v_fma_f32 v21, -v2, v4, 1.0
	v_fmac_f32_e32 v4, v21, v4
	v_div_scale_f32 v21, vcc, v0, v27, v0
	v_mul_f32_e32 v22, v21, v4
	v_fma_f32 v24, -v2, v22, v21
	v_fmac_f32_e32 v22, v24, v4
	v_fma_f32 v2, -v2, v22, v21
	v_div_fmas_f32 v2, v2, v4, v22
	v_div_fixup_f32 v27, v2, v27, v0
	v_div_scale_f32 v0, s[0:1], v26, v26, v32
	v_rcp_f32_e32 v2, v0
	v_mov_b32_e32 v24, v23
	v_fma_f32 v4, -v0, v2, 1.0
	v_fmac_f32_e32 v2, v4, v2
	v_div_scale_f32 v4, vcc, v32, v26, v32
	v_mul_f32_e32 v21, v4, v2
	v_fma_f32 v22, -v0, v21, v4
	v_fmac_f32_e32 v21, v22, v2
	v_fma_f32 v0, -v0, v21, v4
	v_div_fmas_f32 v0, v0, v2, v21
	v_div_fixup_f32 v26, v0, v26, v32
	v_mul_f32_e32 v0, 0xbfb8aa3b, v33
	v_exp_f32_e32 v21, v0
	v_mov_b32_e32 v4, v3
	v_pk_mul_f32 v[2:3], v[4:5], v[24:25]
	v_pk_mul_f32 v[26:27], v[28:29], v[26:27]
	v_pk_add_f32 v[4:5], v[20:21], 1.0 op_sel_hi:[1,0]
	v_mov_b32_e32 v24, v6
	v_div_scale_f32 v0, s[0:1], v5, v5, v33
	v_rcp_f32_e32 v20, v0
	v_mov_b32_e32 v25, v8
	v_fma_f32 v21, -v0, v20, 1.0
	v_fmac_f32_e32 v20, v21, v20
	v_div_scale_f32 v21, vcc, v33, v5, v33
	v_mul_f32_e32 v22, v21, v20
	v_fma_f32 v23, -v0, v22, v21
	v_fmac_f32_e32 v22, v23, v20
	v_fma_f32 v0, -v0, v22, v21
	v_div_fmas_f32 v0, v0, v20, v22
	v_div_fixup_f32 v5, v0, v5, v33
	v_div_scale_f32 v0, s[0:1], v4, v4, v40
	v_rcp_f32_e32 v20, v0
	s_nop 0
	v_fma_f32 v21, -v0, v20, 1.0
	v_fmac_f32_e32 v20, v21, v20
	v_div_scale_f32 v21, vcc, v40, v4, v40
	v_mul_f32_e32 v22, v21, v20
	v_fma_f32 v23, -v0, v22, v21
	v_fmac_f32_e32 v22, v23, v20
	v_fma_f32 v0, -v0, v22, v21
	v_div_fmas_f32 v0, v0, v20, v22
	v_div_fixup_f32 v4, v0, v4, v40
	v_pk_mul_f32 v[2:3], v[2:3], v[4:5]
	v_cvt_pk_bf16_f32 v3, v27, v3
	v_cvt_pk_bf16_f32 v2, v26, v2
	flat_store_dwordx2 v[18:19], v[2:3] offset:64
	flat_load_dwordx2 v[20:21], v[38:39] offset:1104
	s_nop 0
	global_load_dwordx4 v[2:5], v[36:37], off offset:160
	s_waitcnt vmcnt(0) lgkmcnt(0)
; __device__ __forceinline__ unsigned pk2(float lo, float hi) { return f2bf(lo) | (f2bf(hi) << 16); }
; __device__ __forceinline__ float bflo(unsigned w) { return __uint_as_float(w << 16); }
; __device__ __forceinline__ float bfhi(unsigned w) { return __uint_as_float(w & 0xffff0000u); }
; __device__ __forceinline__ float silu(float x) { return x / (1.f + __expf(-x)); }
; __device__ __forceinline__ void pool_item(const Args& A, const Ctx& C0, int l, int row0, int t0, int pos0, const float* hist, float* outpool) {
;     ...
; #pragma unroll
;     for (int dt = 0; dt < 2; ++dt)
; #pragma unroll
;         for (int rq = 0; rq < 4; ++rq) { const int cc = g * 128 + ddh * 64 + dt * 32 + 8 * rq + 4 * h;
;             const v2u gx = *(const v2u*)(U + row * DIN + C_GP + cc); const f32x4 sc = *(const f32x4*)(psc + cc);
;             const float o0 = acc[dt][4 * rq] * sc.x * silu(bflo(gx.x)), o1 = acc[dt][4 * rq + 1] * sc.y * silu(bfhi(gx.x)), o2 = acc[dt][4 * rq + 2] * sc.z * silu(bflo(gx.y)), o3 = acc[dt][4 * rq + 3] * sc.w * silu(bfhi(gx.y));
;             v2u o; o.x = pk2(o0, o1); o.y = pk2(o2, o3);
;             *(v2u*)(MIX + row * D + cc) = o; }
	v_lshlrev_b32_e32 v0, 16, v21
	v_lshlrev_b32_e32 v28, 16, v20
	v_mul_f32_e32 v22, 0xbfb8aa3b, v28
	v_mov_b32_e32 v26, v2
	v_mul_f32_e32 v2, 0xbfb8aa3b, v0
	v_exp_f32_e32 v22, v22
	v_exp_f32_e32 v23, v2
	v_mov_b32_e32 v27, v4
	v_and_b32_e32 v29, 0xffff0000, v21
	v_and_b32_e32 v30, 0xffff0000, v20
	v_pk_add_f32 v[22:23], v[22:23], 1.0 op_sel_hi:[1,0]
	v_mul_f32_e32 v20, 0xbfb8aa3b, v30
	v_div_scale_f32 v2, s[0:1], v23, v23, v0
	v_rcp_f32_e32 v4, v2
	v_exp_f32_e32 v20, v20
	v_pk_mul_f32 v[24:25], v[24:25], v[26:27]
	v_fma_f32 v6, -v2, v4, 1.0
	v_fmac_f32_e32 v4, v6, v4
	v_div_scale_f32 v6, vcc, v0, v23, v0
	v_mul_f32_e32 v8, v6, v4
	v_fma_f32 v21, -v2, v8, v6
	v_fmac_f32_e32 v8, v21, v4
	v_fma_f32 v2, -v2, v8, v6
	v_div_fmas_f32 v2, v2, v4, v8
	v_div_fixup_f32 v23, v2, v23, v0
	v_div_scale_f32 v0, s[0:1], v22, v22, v28
	v_rcp_f32_e32 v2, v0
	s_nop 0
	v_fma_f32 v4, -v0, v2, 1.0
	v_fmac_f32_e32 v2, v4, v2
	v_div_scale_f32 v4, vcc, v28, v22, v28
	v_mul_f32_e32 v6, v4, v2
	v_fma_f32 v8, -v0, v6, v4
	v_fmac_f32_e32 v6, v8, v2
	v_fma_f32 v0, -v0, v6, v4
	v_div_fmas_f32 v0, v0, v2, v6
	v_div_fixup_f32 v22, v0, v22, v28
	v_mul_f32_e32 v0, 0xbfb8aa3b, v29
	v_exp_f32_e32 v21, v0
	v_mov_b32_e32 v8, v7
	v_mov_b32_e32 v4, v3
	v_pk_mul_f32 v[2:3], v[8:9], v[4:5]
	v_pk_add_f32 v[4:5], v[20:21], 1.0 op_sel_hi:[1,0]
	v_pk_mul_f32 v[22:23], v[24:25], v[22:23]
	v_div_scale_f32 v0, s[0:1], v5, v5, v29
	v_rcp_f32_e32 v6, v0
	v_mov_b32_e32 v20, v10
	v_mov_b32_e32 v21, v12
	v_fma_f32 v7, -v0, v6, 1.0
	v_fmac_f32_e32 v6, v7, v6
	v_div_scale_f32 v7, vcc, v29, v5, v29
	v_mul_f32_e32 v8, v7, v6
	v_fma_f32 v9, -v0, v8, v7
	v_fmac_f32_e32 v8, v9, v6
	v_fma_f32 v0, -v0, v8, v7
	v_div_fmas_f32 v0, v0, v6, v8
	v_div_fixup_f32 v5, v0, v5, v29
	v_div_scale_f32 v0, s[0:1], v4, v4, v30
	v_rcp_f32_e32 v6, v0
	s_nop 0
	v_fma_f32 v7, -v0, v6, 1.0
	v_fmac_f32_e32 v6, v7, v6
	v_div_scale_f32 v7, vcc, v30, v4, v30
	v_mul_f32_e32 v8, v7, v6
	v_fma_f32 v9, -v0, v8, v7
	v_fmac_f32_e32 v8, v9, v6
	v_fma_f32 v0, -v0, v8, v7
	v_div_fmas_f32 v0, v0, v6, v8
	v_div_fixup_f32 v4, v0, v4, v30
	v_pk_mul_f32 v[2:3], v[2:3], v[4:5]
	v_cvt_pk_bf16_f32 v3, v23, v3
	v_cvt_pk_bf16_f32 v2, v22, v2
	flat_store_dwordx2 v[18:19], v[2:3] offset:80
	flat_load_dwordx2 v[6:7], v[38:39] offset:1120
	s_nop 0
	global_load_dwordx4 v[2:5], v[36:37], off offset:192
	s_waitcnt vmcnt(0) lgkmcnt(0)
	v_lshlrev_b32_e32 v0, 16, v7
	v_lshlrev_b32_e32 v24, 16, v6
	v_mul_f32_e32 v8, 0xbfb8aa3b, v24
	v_mov_b32_e32 v22, v2
	v_mul_f32_e32 v2, 0xbfb8aa3b, v0
	v_exp_f32_e32 v8, v8
	v_exp_f32_e32 v9, v2
	v_mov_b32_e32 v23, v4
	v_and_b32_e32 v25, 0xffff0000, v7
	v_and_b32_e32 v26, 0xffff0000, v6
	v_pk_add_f32 v[8:9], v[8:9], 1.0 op_sel_hi:[1,0]
	v_mul_f32_e32 v6, 0xbfb8aa3b, v26
	v_div_scale_f32 v2, s[0:1], v9, v9, v0
	v_rcp_f32_e32 v4, v2
	v_exp_f32_e32 v6, v6
	v_pk_mul_f32 v[20:21], v[20:21], v[22:23]
	v_fma_f32 v7, -v2, v4, 1.0
	v_fmac_f32_e32 v4, v7, v4
	v_div_scale_f32 v7, vcc, v0, v9, v0
	v_mul_f32_e32 v10, v7, v4
	v_fma_f32 v12, -v2, v10, v7
	v_fmac_f32_e32 v10, v12, v4
	v_fma_f32 v2, -v2, v10, v7
	v_div_fmas_f32 v2, v2, v4, v10
	v_div_fixup_f32 v9, v2, v9, v0
	v_div_scale_f32 v0, s[0:1], v8, v8, v24
	v_rcp_f32_e32 v2, v0
	v_mov_b32_e32 v12, v11
	v_fma_f32 v4, -v0, v2, 1.0
	v_fmac_f32_e32 v2, v4, v2
	v_div_scale_f32 v4, vcc, v24, v8, v24
	v_mul_f32_e32 v7, v4, v2
	v_fma_f32 v10, -v0, v7, v4
	v_fmac_f32_e32 v7, v10, v2
	v_fma_f32 v0, -v0, v7, v4
	v_div_fmas_f32 v0, v0, v2, v7
	v_div_fixup_f32 v8, v0, v8, v24
	v_mul_f32_e32 v0, 0xbfb8aa3b, v25
	v_exp_f32_e32 v7, v0
	v_mov_b32_e32 v4, v3
	v_pk_mul_f32 v[2:3], v[12:13], v[4:5]
	v_pk_mul_f32 v[8:9], v[20:21], v[8:9]
	v_pk_add_f32 v[4:5], v[6:7], 1.0 op_sel_hi:[1,0]
	s_nop 0
	v_div_scale_f32 v0, s[0:1], v5, v5, v25
	v_rcp_f32_e32 v6, v0
	s_nop 0
	v_fma_f32 v7, -v0, v6, 1.0
	v_fmac_f32_e32 v6, v7, v6
	v_div_scale_f32 v7, vcc, v25, v5, v25
	v_mul_f32_e32 v10, v7, v6
	v_fma_f32 v11, -v0, v10, v7
	v_fmac_f32_e32 v10, v11, v6
	v_fma_f32 v0, -v0, v10, v7
	v_div_fmas_f32 v0, v0, v6, v10
	v_div_fixup_f32 v5, v0, v5, v25
	v_div_scale_f32 v0, s[0:1], v4, v4, v26
	v_rcp_f32_e32 v6, v0
	s_nop 0
	v_fma_f32 v7, -v0, v6, 1.0
	v_fmac_f32_e32 v6, v7, v6
	v_div_scale_f32 v7, vcc, v26, v4, v26
	v_mul_f32_e32 v10, v7, v6
	v_fma_f32 v11, -v0, v10, v7
	v_fmac_f32_e32 v10, v11, v6
	v_fma_f32 v0, -v0, v10, v7
	v_div_fmas_f32 v0, v0, v6, v10
	v_div_fixup_f32 v4, v0, v4, v26
	v_pk_mul_f32 v[2:3], v[2:3], v[4:5]
	v_cvt_pk_bf16_f32 v3, v9, v3
	v_cvt_pk_bf16_f32 v2, v8, v2
	flat_store_dwordx2 v[18:19], v[2:3] offset:96
	flat_load_dwordx2 v[2:3], v[38:39] offset:1136
	s_nop 0
	global_load_dwordx4 v[4:7], v[36:37], off offset:224
	v_mov_b32_e32 v10, v14
	v_mov_b32_e32 v11, v16
	v_mov_b32_e32 v16, v15
	s_waitcnt vmcnt(0) lgkmcnt(0)
; __device__ __forceinline__ unsigned pk2(float lo, float hi) { return f2bf(lo) | (f2bf(hi) << 16); }
; __device__ __forceinline__ float bflo(unsigned w) { return __uint_as_float(w << 16); }
; __device__ __forceinline__ float bfhi(unsigned w) { return __uint_as_float(w & 0xffff0000u); }
; __device__ __forceinline__ float bf1(bf16 h) { return __uint_as_float(((unsigned)h) << 16); }
; __device__ __forceinline__ float silu(float x) { return x / (1.f + __expf(-x)); }
; __device__ __forceinline__ void pool_item(const Args& A, const Ctx& C0, int l, int row0, int t0, int pos0, const float* hist, float* outpool) {
;     ...
; #pragma unroll
;     for (int dt = 0; dt < 2; ++dt)
; #pragma unroll
;         for (int rq = 0; rq < 4; ++rq) { const int cc = g * 128 + ddh * 64 + dt * 32 + 8 * rq + 4 * h;
;             const v2u gx = *(const v2u*)(U + row * DIN + C_GP + cc); const f32x4 sc = *(const f32x4*)(psc + cc);
;             const float o0 = acc[dt][4 * rq] * sc.x * silu(bflo(gx.x)), o1 = acc[dt][4 * rq + 1] * sc.y * silu(bfhi(gx.x)), o2 = acc[dt][4 * rq + 2] * sc.z * silu(bflo(gx.y)), o3 = acc[dt][4 * rq + 3] * sc.w * silu(bfhi(gx.y));
;             v2u o; o.x = pk2(o0, o1); o.y = pk2(o2, o3);
;             *(v2u*)(MIX + row * D + cc) = o; }
;     if (outpool) for (int idx = C.tid; idx < 15 * 512; idx += 512) { const int rr = idx >> 9, cc = idx & 511; outpool[idx] = bf1(P[(32 + rr) * PP + cc]); }
	v_lshlrev_b32_e32 v0, 16, v3
	v_lshlrev_b32_e32 v20, 16, v2
	v_mul_f32_e32 v8, 0xbfb8aa3b, v20
	v_and_b32_e32 v21, 0xffff0000, v3
	v_mul_f32_e32 v3, 0xbfb8aa3b, v0
	v_exp_f32_e32 v8, v8
	v_exp_f32_e32 v9, v3
	v_mov_b32_e32 v12, v4
	v_mov_b32_e32 v13, v6
	v_pk_mul_f32 v[10:11], v[10:11], v[12:13]
	v_pk_add_f32 v[8:9], v[8:9], 1.0 op_sel_hi:[1,0]
	v_and_b32_e32 v22, 0xffff0000, v2
	v_div_scale_f32 v3, s[0:1], v9, v9, v0
	v_rcp_f32_e32 v4, v3
	v_mul_f32_e32 v2, 0xbfb8aa3b, v22
	v_exp_f32_e32 v2, v2
	v_fma_f32 v6, -v3, v4, 1.0
	v_fmac_f32_e32 v4, v6, v4
	v_div_scale_f32 v6, vcc, v0, v9, v0
	v_mul_f32_e32 v12, v6, v4
	v_fma_f32 v13, -v3, v12, v6
	v_fmac_f32_e32 v12, v13, v4
	v_fma_f32 v3, -v3, v12, v6
	v_div_fmas_f32 v3, v3, v4, v12
	v_div_fixup_f32 v9, v3, v9, v0
	v_div_scale_f32 v0, s[0:1], v8, v8, v20
	v_rcp_f32_e32 v3, v0
	s_nop 0
	v_fma_f32 v4, -v0, v3, 1.0
	v_fmac_f32_e32 v3, v4, v3
	v_div_scale_f32 v4, vcc, v20, v8, v20
	v_mul_f32_e32 v6, v4, v3
	v_fma_f32 v12, -v0, v6, v4
	v_fmac_f32_e32 v6, v12, v3
	v_fma_f32 v0, -v0, v6, v4
	v_div_fmas_f32 v0, v0, v3, v6
	v_div_fixup_f32 v8, v0, v8, v20
	v_mul_f32_e32 v0, 0xbfb8aa3b, v21
	v_exp_f32_e32 v3, v0
	v_mov_b32_e32 v6, v5
	v_pk_mul_f32 v[4:5], v[16:17], v[6:7]
	v_pk_mul_f32 v[8:9], v[10:11], v[8:9]
	v_pk_add_f32 v[2:3], v[2:3], 1.0 op_sel_hi:[1,0]
	s_nop 0
	v_div_scale_f32 v0, s[0:1], v3, v3, v21
	v_rcp_f32_e32 v6, v0
	s_nop 0
	v_fma_f32 v7, -v0, v6, 1.0
	v_fmac_f32_e32 v6, v7, v6
	v_div_scale_f32 v7, vcc, v21, v3, v21
	v_mul_f32_e32 v10, v7, v6
	v_fma_f32 v11, -v0, v10, v7
	v_fmac_f32_e32 v10, v11, v6
	v_fma_f32 v0, -v0, v10, v7
	v_div_fmas_f32 v0, v0, v6, v10
	v_div_fixup_f32 v3, v0, v3, v21
	v_div_scale_f32 v0, s[0:1], v2, v2, v22
	v_rcp_f32_e32 v6, v0
	s_cselect_b64 s[0:1], -1, 0
	v_fma_f32 v7, -v0, v6, 1.0
	v_fmac_f32_e32 v6, v7, v6
	v_div_scale_f32 v7, vcc, v22, v2, v22
	v_mul_f32_e32 v10, v7, v6
	v_fma_f32 v11, -v0, v10, v7
	v_fmac_f32_e32 v10, v11, v6
	v_fma_f32 v0, -v0, v10, v7
	v_div_fmas_f32 v0, v0, v6, v10
	v_div_fixup_f32 v2, v0, v2, v22
	v_pk_mul_f32 v[2:3], v[4:5], v[2:3]
	v_cmp_gt_i32_e32 vcc, s2, v34
	v_cvt_pk_bf16_f32 v3, v9, v3
	v_cvt_pk_bf16_f32 v2, v8, v2
	s_and_b64 s[2:3], s[0:1], vcc
	flat_store_dwordx2 v[18:19], v[2:3] offset:112
	s_and_saveexec_b64 s[0:1], s[2:3]
	s_cbranch_execz .LBB0_766
	v_max_i32_e32 v2, 0x1c00, v34
	v_sub_u32_e32 v2, v2, v34
	v_and_b32_e32 v0, 0x1ff, v34
	v_add_u32_e32 v2, 0x1ff, v2
	s_movk_i32 s2, 0x1ff
	v_cmp_lt_u32_e32 vcc, s2, v2
	s_mov_b64 s[2:3], -1
	v_lshl_add_u32 v0, v0, 1, 0
	s_and_saveexec_b64 s[24:25], vcc
	s_cbranch_execz .LBB0_763
	v_lshrrev_b32_e32 v2, 9, v2
	v_add_u32_e32 v4, 1, v2
	v_and_b32_e32 v5, 0xfffffe, v4
	s_mov_b64 s[30:31], 0
	v_mov_b32_e32 v6, v5
	v_mov_b64_e32 v[2:3], v[34:35]
	s_movk_i32 s2, 0x410

; __device__ __forceinline__ unsigned pk2(float lo, float hi) { return f2bf(lo) | (f2bf(hi) << 16); }
; __device__ __forceinline__ float bflo(unsigned w) { return __uint_as_float(w << 16); }
; __device__ __forceinline__ float bfhi(unsigned w) { return __uint_as_float(w & 0xffff0000u); }
; __device__ __forceinline__ float silu(float x) { return x / (1.f + __expf(-x)); }
; __device__ __forceinline__ void attn_unit(const Args& A, const Ctx& C0, int l, int u_qrow0, int u_nq, int u_krow0, int u_krow1, int u_krow2, int u_g, const float* u_ck, const float* u_cv, unsigned u_vmask) {
;     ...
;         const size_t row = (size_t)(u.qrow0 + qi);
; #pragma unroll
;         for (int dt = 0; dt < 2; ++dt)
; #pragma unroll
;             for (int rq = 0; rq < 4; ++rq) { const int d = dt * 32 + 8 * rq + 4 * h;
;                 const v2u gx = gxa[qt][dt][rq];
;                 const float o0 = oacc[dt][4 * rq] * silu(bflo(gx.x)), o1 = oacc[dt][4 * rq + 1] * silu(bfhi(gx.x)), o2 = oacc[dt][4 * rq + 2] * silu(bflo(gx.y)), o3 = oacc[dt][4 * rq + 3] * silu(bfhi(gx.y));
;                 v2u o; o.x = pk2(o0, o1); o.y = pk2(o2, o3);
;                 *(v2u*)(MIX + row * D + 512 + hq * 64 + d) = o; }
.LBB0_980:
	v_lshlrev_b32_e32 v0, 12, v184
	v_and_b32_e32 v43, 0xffff0000, v162
	v_lshl_add_u64 v[34:35], s[0:1], 0, v[0:1]
	v_lshlrev_b32_e32 v0, 16, v163
	v_lshlrev_b32_e32 v39, 16, v162
	v_mul_f32_e32 v37, 0xbfb8aa3b, v43
	v_mul_f32_e32 v36, 0xbfb8aa3b, v39
	v_exp_f32_e32 v38, v37
	v_mul_f32_e32 v37, 0xbfb8aa3b, v0
	v_exp_f32_e32 v36, v36
	v_exp_f32_e32 v37, v37
	v_and_b32_e32 v42, 0xffff0000, v163
	v_lshl_add_u64 v[34:35], s[36:37], 1, v[34:35]
	v_pk_add_f32 v[36:37], v[36:37], 1.0 op_sel_hi:[1,0]
	s_nop 0
	v_div_scale_f32 v40, s[2:3], v37, v37, v0
	v_rcp_f32_e32 v41, v40
	s_nop 0
	v_fma_f32 v44, -v40, v41, 1.0
	v_fmac_f32_e32 v41, v44, v41
	v_div_scale_f32 v44, vcc, v0, v37, v0
	v_mul_f32_e32 v45, v44, v41
	v_fma_f32 v46, -v40, v45, v44
	v_fmac_f32_e32 v45, v46, v41
	v_fma_f32 v40, -v40, v45, v44
	v_div_fmas_f32 v40, v40, v41, v45
	v_div_fixup_f32 v37, v40, v37, v0
	v_div_scale_f32 v0, s[2:3], v36, v36, v39
	v_rcp_f32_e32 v40, v0
	s_nop 0
	v_fma_f32 v41, -v0, v40, 1.0
	v_fmac_f32_e32 v40, v41, v40
	v_div_scale_f32 v41, vcc, v39, v36, v39
	v_mul_f32_e32 v44, v41, v40
	v_fma_f32 v45, -v0, v44, v41
	v_fmac_f32_e32 v44, v45, v40
	v_fma_f32 v0, -v0, v44, v41
	v_div_fmas_f32 v0, v0, v40, v44
	v_div_fixup_f32 v36, v0, v36, v39
	v_mul_f32_e32 v0, 0xbfb8aa3b, v42
	v_exp_f32_e32 v39, v0
	v_mov_b32_e32 v40, v18
	v_mov_b32_e32 v41, v20
	v_pk_mul_f32 v[36:37], v[36:37], v[40:41]
	v_pk_add_f32 v[38:39], v[38:39], 1.0 op_sel_hi:[1,0]
	s_nop 0
	v_div_scale_f32 v0, s[2:3], v39, v39, v42
	v_rcp_f32_e32 v18, v0
	s_nop 0
	v_fma_f32 v20, -v0, v18, 1.0
	v_fmac_f32_e32 v18, v20, v18
	v_div_scale_f32 v20, vcc, v42, v39, v42
	v_mul_f32_e32 v40, v20, v18
	v_fma_f32 v41, -v0, v40, v20
	v_fmac_f32_e32 v40, v41, v18
	v_fma_f32 v0, -v0, v40, v20
	v_div_fmas_f32 v0, v0, v18, v40
	v_div_fixup_f32 v39, v0, v39, v42
	v_div_scale_f32 v0, s[2:3], v38, v38, v43
	v_rcp_f32_e32 v18, v0
	s_mov_b64 s[2:3], 0x7b27d00
	v_fma_f32 v20, -v0, v18, 1.0
	v_fmac_f32_e32 v18, v20, v18
	v_div_scale_f32 v20, vcc, v43, v38, v43
	v_mul_f32_e32 v40, v20, v18
	v_fma_f32 v41, -v0, v40, v20
	v_fmac_f32_e32 v40, v41, v18
	v_fma_f32 v0, -v0, v40, v20
	v_div_fmas_f32 v0, v0, v18, v40
	v_div_fixup_f32 v38, v0, v38, v43
	v_mov_b32_e32 v20, v19
	v_pk_mul_f32 v[18:19], v[38:39], v[20:21]
	v_cvt_pk_bf16_f32 v21, v37, v19
	v_lshlrev_b32_e32 v0, 1, v191
	v_lshl_add_u64 v[34:35], v[34:35], 0, v[0:1]
	v_cvt_pk_bf16_f32 v20, v36, v18
	v_lshl_add_u64 v[18:19], v[34:35], 0, s[2:3]
	s_mov_b32 s2, 0x7b27000
	v_add_co_u32_e32 v34, vcc, s2, v34
	v_and_b32_e32 v39, 0xffff0000, v160
	s_nop 0
	v_addc_co_u32_e32 v35, vcc, 0, v35, vcc
	flat_store_dwordx2 v[34:35], v[20:21] offset:3328
	v_lshlrev_b32_e32 v35, 16, v161
	v_lshlrev_b32_e32 v36, 16, v160
	v_mul_f32_e32 v21, 0xbfb8aa3b, v39
	v_mul_f32_e32 v20, 0xbfb8aa3b, v36
	v_exp_f32_e32 v34, v21
	v_mul_f32_e32 v21, 0xbfb8aa3b, v35
	v_exp_f32_e32 v20, v20
	v_exp_f32_e32 v21, v21
	v_and_b32_e32 v38, 0xffff0000, v161
	v_pk_add_f32 v[20:21], v[20:21], 1.0 op_sel_hi:[1,0]
	s_nop 0
	v_div_scale_f32 v37, s[2:3], v21, v21, v35
	v_rcp_f32_e32 v40, v37
	s_nop 0
	v_fma_f32 v41, -v37, v40, 1.0
	v_fmac_f32_e32 v40, v41, v40
	v_div_scale_f32 v41, vcc, v35, v21, v35
	v_mul_f32_e32 v42, v41, v40
	v_fma_f32 v43, -v37, v42, v41
	v_fmac_f32_e32 v42, v43, v40
	v_fma_f32 v37, -v37, v42, v41
	v_div_fmas_f32 v37, v37, v40, v42
	v_div_fixup_f32 v21, v37, v21, v35
	v_div_scale_f32 v35, s[2:3], v20, v20, v36
	v_rcp_f32_e32 v37, v35
	s_nop 0
	v_fma_f32 v40, -v35, v37, 1.0
	v_fmac_f32_e32 v37, v40, v37
	v_div_scale_f32 v40, vcc, v36, v20, v36
	v_mul_f32_e32 v41, v40, v37
	v_fma_f32 v42, -v35, v41, v40
	v_fmac_f32_e32 v41, v42, v37
	v_fma_f32 v35, -v35, v41, v40
	v_div_fmas_f32 v35, v35, v37, v41
	v_div_fixup_f32 v20, v35, v20, v36
	v_mov_b32_e32 v36, v22
	v_mul_f32_e32 v22, 0xbfb8aa3b, v38
	v_exp_f32_e32 v35, v22
	v_mov_b32_e32 v37, v24
	v_pk_mul_f32 v[20:21], v[20:21], v[36:37]
	v_pk_add_f32 v[34:35], v[34:35], 1.0 op_sel_hi:[1,0]
	s_nop 0
	v_div_scale_f32 v22, s[2:3], v35, v35, v38
	v_rcp_f32_e32 v24, v22
	s_nop 0
	v_fma_f32 v36, -v22, v24, 1.0
	v_fmac_f32_e32 v24, v36, v24
	v_div_scale_f32 v36, vcc, v38, v35, v38
	v_mul_f32_e32 v37, v36, v24
	v_fma_f32 v40, -v22, v37, v36
	v_fmac_f32_e32 v37, v40, v24
	v_fma_f32 v22, -v22, v37, v36
	v_div_fmas_f32 v22, v22, v24, v37
	v_div_fixup_f32 v35, v22, v35, v38
	v_div_scale_f32 v22, s[2:3], v34, v34, v39
	v_rcp_f32_e32 v24, v22
	s_nop 0
	v_fma_f32 v36, -v22, v24, 1.0
	v_fmac_f32_e32 v24, v36, v24
	v_div_scale_f32 v36, vcc, v39, v34, v39
	v_mul_f32_e32 v37, v36, v24
	v_fma_f32 v38, -v22, v37, v36
	v_fmac_f32_e32 v37, v38, v24
	v_fma_f32 v22, -v22, v37, v36
	v_div_fmas_f32 v22, v22, v24, v37
	v_div_fixup_f32 v34, v22, v34, v39
	v_mov_b32_e32 v24, v23
	v_pk_mul_f32 v[22:23], v[34:35], v[24:25]
	v_cvt_pk_bf16_f32 v21, v21, v23
	v_cvt_pk_bf16_f32 v20, v20, v22
	v_and_b32_e32 v35, 0xffff0000, v158
	flat_store_dwordx2 v[18:19], v[20:21] offset:16
	v_lshlrev_b32_e32 v23, 16, v159
	v_lshlrev_b32_e32 v24, 16, v158
	v_mul_f32_e32 v21, 0xbfb8aa3b, v35
	v_mul_f32_e32 v20, 0xbfb8aa3b, v24
	v_exp_f32_e32 v22, v21
	v_mul_f32_e32 v21, 0xbfb8aa3b, v23
	v_exp_f32_e32 v20, v20
	v_exp_f32_e32 v21, v21
	v_and_b32_e32 v34, 0xffff0000, v159
	v_pk_add_f32 v[20:21], v[20:21], 1.0 op_sel_hi:[1,0]
	s_nop 0
	v_div_scale_f32 v25, s[2:3], v21, v21, v23
	v_rcp_f32_e32 v36, v25
	s_nop 0
	v_fma_f32 v37, -v25, v36, 1.0
	v_fmac_f32_e32 v36, v37, v36
	v_div_scale_f32 v37, vcc, v23, v21, v23
	v_mul_f32_e32 v38, v37, v36
	v_fma_f32 v39, -v25, v38, v37
	v_fmac_f32_e32 v38, v39, v36
	v_fma_f32 v25, -v25, v38, v37
	v_div_fmas_f32 v25, v25, v36, v38
	v_div_fixup_f32 v21, v25, v21, v23
; __device__ __forceinline__ unsigned pk2(float lo, float hi) { return f2bf(lo) | (f2bf(hi) << 16); }
; __device__ __forceinline__ float bflo(unsigned w) { return __uint_as_float(w << 16); }
; __device__ __forceinline__ float bfhi(unsigned w) { return __uint_as_float(w & 0xffff0000u); }
; __device__ __forceinline__ float silu(float x) { return x / (1.f + __expf(-x)); }
; __device__ __forceinline__ void attn_unit(const Args& A, const Ctx& C0, int l, int u_qrow0, int u_nq, int u_krow0, int u_krow1, int u_krow2, int u_g, const float* u_ck, const float* u_cv, unsigned u_vmask) {
;     ...
;         const size_t row = (size_t)(u.qrow0 + qi);
; #pragma unroll
;         for (int dt = 0; dt < 2; ++dt)
; #pragma unroll
;             for (int rq = 0; rq < 4; ++rq) { const int d = dt * 32 + 8 * rq + 4 * h;
;                 const v2u gx = gxa[qt][dt][rq];
;                 const float o0 = oacc[dt][4 * rq] * silu(bflo(gx.x)), o1 = oacc[dt][4 * rq + 1] * silu(bfhi(gx.x)), o2 = oacc[dt][4 * rq + 2] * silu(bflo(gx.y)), o3 = oacc[dt][4 * rq + 3] * silu(bfhi(gx.y));
;                 v2u o; o.x = pk2(o0, o1); o.y = pk2(o2, o3);
;                 *(v2u*)(MIX + row * D + 512 + hq * 64 + d) = o; }
	v_div_scale_f32 v23, s[2:3], v20, v20, v24
	v_rcp_f32_e32 v25, v23
	s_nop 0
	v_fma_f32 v36, -v23, v25, 1.0
	v_fmac_f32_e32 v25, v36, v25
	v_div_scale_f32 v36, vcc, v24, v20, v24
	v_mul_f32_e32 v37, v36, v25
	v_fma_f32 v38, -v23, v37, v36
	v_fmac_f32_e32 v37, v38, v25
	v_fma_f32 v23, -v23, v37, v36
	v_div_fmas_f32 v23, v23, v25, v37
	v_div_fixup_f32 v20, v23, v20, v24
	v_mul_f32_e32 v23, 0xbfb8aa3b, v34
	v_exp_f32_e32 v23, v23
	v_mov_b32_e32 v24, v26
	v_mov_b32_e32 v25, v28
	v_pk_mul_f32 v[20:21], v[20:21], v[24:25]
	v_pk_add_f32 v[22:23], v[22:23], 1.0 op_sel_hi:[1,0]
	s_nop 0
	v_div_scale_f32 v24, s[2:3], v23, v23, v34
	v_rcp_f32_e32 v25, v24
	s_nop 0
	v_fma_f32 v26, -v24, v25, 1.0
	v_fmac_f32_e32 v25, v26, v25
	v_div_scale_f32 v26, vcc, v34, v23, v34
	v_mul_f32_e32 v28, v26, v25
	v_fma_f32 v36, -v24, v28, v26
	v_fmac_f32_e32 v28, v36, v25
	v_fma_f32 v24, -v24, v28, v26
	v_div_fmas_f32 v24, v24, v25, v28
	v_div_fixup_f32 v23, v24, v23, v34
	v_div_scale_f32 v24, s[2:3], v22, v22, v35
	v_rcp_f32_e32 v25, v24
	s_nop 0
	v_fma_f32 v26, -v24, v25, 1.0
	v_fmac_f32_e32 v25, v26, v25
	v_div_scale_f32 v26, vcc, v35, v22, v35
	v_mul_f32_e32 v28, v26, v25
	v_fma_f32 v34, -v24, v28, v26
	v_fmac_f32_e32 v28, v34, v25
	v_fma_f32 v24, -v24, v28, v26
	v_div_fmas_f32 v24, v24, v25, v28
	v_div_fixup_f32 v22, v24, v22, v35
	v_mov_b32_e32 v28, v27
	v_pk_mul_f32 v[22:23], v[22:23], v[28:29]
	v_cvt_pk_bf16_f32 v21, v21, v23
	v_cvt_pk_bf16_f32 v20, v20, v22
	v_and_b32_e32 v27, 0xffff0000, v156
	flat_store_dwordx2 v[18:19], v[20:21] offset:32
	v_lshlrev_b32_e32 v23, 16, v157
	v_lshlrev_b32_e32 v24, 16, v156
	v_mul_f32_e32 v21, 0xbfb8aa3b, v27
	v_mul_f32_e32 v20, 0xbfb8aa3b, v24
	v_exp_f32_e32 v22, v21
	v_mul_f32_e32 v21, 0xbfb8aa3b, v23
	v_exp_f32_e32 v20, v20
	v_exp_f32_e32 v21, v21
	v_and_b32_e32 v26, 0xffff0000, v157
	v_pk_add_f32 v[20:21], v[20:21], 1.0 op_sel_hi:[1,0]
	s_nop 0
	v_div_scale_f32 v25, s[2:3], v21, v21, v23
	v_rcp_f32_e32 v28, v25
	s_nop 0
	v_fma_f32 v29, -v25, v28, 1.0
	v_fmac_f32_e32 v28, v29, v28
	v_div_scale_f32 v29, vcc, v23, v21, v23
	v_mul_f32_e32 v34, v29, v28
	v_fma_f32 v35, -v25, v34, v29
	v_fmac_f32_e32 v34, v35, v28
	v_fma_f32 v25, -v25, v34, v29
	v_div_fmas_f32 v25, v25, v28, v34
	v_div_fixup_f32 v21, v25, v21, v23
	v_div_scale_f32 v23, s[2:3], v20, v20, v24
	v_rcp_f32_e32 v25, v23
	s_nop 0
	v_fma_f32 v28, -v23, v25, 1.0
	v_fmac_f32_e32 v25, v28, v25
	v_div_scale_f32 v28, vcc, v24, v20, v24
	v_mul_f32_e32 v29, v28, v25
	v_fma_f32 v34, -v23, v29, v28
	v_fmac_f32_e32 v29, v34, v25
	v_fma_f32 v23, -v23, v29, v28
	v_div_fmas_f32 v23, v23, v25, v29
	v_div_fixup_f32 v20, v23, v20, v24
	v_mul_f32_e32 v23, 0xbfb8aa3b, v26
	v_exp_f32_e32 v23, v23
	v_mov_b32_e32 v24, v30
	v_mov_b32_e32 v25, v32
	v_pk_mul_f32 v[20:21], v[20:21], v[24:25]
	v_pk_add_f32 v[22:23], v[22:23], 1.0 op_sel_hi:[1,0]
	v_mov_b32_e32 v32, v31
	v_div_scale_f32 v24, s[2:3], v23, v23, v26
	v_rcp_f32_e32 v25, v24
	s_nop 0
	v_fma_f32 v28, -v24, v25, 1.0
	v_fmac_f32_e32 v25, v28, v25
	v_div_scale_f32 v28, vcc, v26, v23, v26
	v_mul_f32_e32 v29, v28, v25
	v_fma_f32 v30, -v24, v29, v28
	v_fmac_f32_e32 v29, v30, v25
	v_fma_f32 v24, -v24, v29, v28
	v_div_fmas_f32 v24, v24, v25, v29
	v_div_fixup_f32 v23, v24, v23, v26
	v_div_scale_f32 v24, s[2:3], v22, v22, v27
	v_rcp_f32_e32 v25, v24
	s_nop 0
	v_fma_f32 v26, -v24, v25, 1.0
	v_fmac_f32_e32 v25, v26, v25
	v_div_scale_f32 v26, vcc, v27, v22, v27
	v_mul_f32_e32 v28, v26, v25
	v_fma_f32 v29, -v24, v28, v26
	v_fmac_f32_e32 v28, v29, v25
	v_fma_f32 v24, -v24, v28, v26
	v_div_fmas_f32 v24, v24, v25, v28
	v_div_fixup_f32 v22, v24, v22, v27
	v_pk_mul_f32 v[22:23], v[22:23], v[32:33]
	v_cvt_pk_bf16_f32 v21, v21, v23
	v_cvt_pk_bf16_f32 v20, v20, v22
	v_and_b32_e32 v27, 0xffff0000, v154
	flat_store_dwordx2 v[18:19], v[20:21] offset:48
	v_lshlrev_b32_e32 v23, 16, v155
	v_lshlrev_b32_e32 v24, 16, v154
	v_mul_f32_e32 v21, 0xbfb8aa3b, v27
	v_mul_f32_e32 v20, 0xbfb8aa3b, v24
	v_exp_f32_e32 v22, v21
	v_mul_f32_e32 v21, 0xbfb8aa3b, v23
	v_exp_f32_e32 v20, v20
	v_exp_f32_e32 v21, v21
	v_and_b32_e32 v26, 0xffff0000, v155
	v_pk_add_f32 v[20:21], v[20:21], 1.0 op_sel_hi:[1,0]
	s_nop 0
	v_div_scale_f32 v25, s[2:3], v21, v21, v23
	v_rcp_f32_e32 v28, v25
	s_nop 0
	v_fma_f32 v29, -v25, v28, 1.0
	v_fmac_f32_e32 v28, v29, v28
	v_div_scale_f32 v29, vcc, v23, v21, v23
	v_mul_f32_e32 v30, v29, v28
	v_fma_f32 v31, -v25, v30, v29
	v_fmac_f32_e32 v30, v31, v28
	v_fma_f32 v25, -v25, v30, v29
	v_div_fmas_f32 v25, v25, v28, v30
	v_div_fixup_f32 v21, v25, v21, v23
	v_div_scale_f32 v23, s[2:3], v20, v20, v24
	v_rcp_f32_e32 v25, v23
	s_nop 0
	v_fma_f32 v28, -v23, v25, 1.0
	v_fmac_f32_e32 v25, v28, v25
	v_div_scale_f32 v28, vcc, v24, v20, v24
	v_mul_f32_e32 v29, v28, v25
	v_fma_f32 v30, -v23, v29, v28
	v_fmac_f32_e32 v29, v30, v25
	v_fma_f32 v23, -v23, v29, v28
	v_div_fmas_f32 v23, v23, v25, v29
	v_div_fixup_f32 v20, v23, v20, v24
	v_mov_b32_e32 v24, v2
	v_mul_f32_e32 v2, 0xbfb8aa3b, v26
	v_exp_f32_e32 v23, v2
	v_mov_b32_e32 v25, v4
	v_pk_mul_f32 v[20:21], v[20:21], v[24:25]
	v_pk_add_f32 v[22:23], v[22:23], 1.0 op_sel_hi:[1,0]
	s_nop 0
	v_div_scale_f32 v2, s[2:3], v23, v23, v26
	v_rcp_f32_e32 v4, v2
	s_nop 0
	v_fma_f32 v24, -v2, v4, 1.0
	v_fmac_f32_e32 v4, v24, v4
	v_div_scale_f32 v24, vcc, v26, v23, v26
	v_mul_f32_e32 v25, v24, v4
	v_fma_f32 v28, -v2, v25, v24
	v_fmac_f32_e32 v25, v28, v4
	v_fma_f32 v2, -v2, v25, v24
	v_div_fmas_f32 v2, v2, v4, v25
	v_div_fixup_f32 v23, v2, v23, v26
	v_div_scale_f32 v2, s[2:3], v22, v22, v27
	v_rcp_f32_e32 v4, v2
	s_nop 0
	v_fma_f32 v24, -v2, v4, 1.0
	v_fmac_f32_e32 v4, v24, v4
	v_div_scale_f32 v24, vcc, v27, v22, v27
	v_mul_f32_e32 v25, v24, v4
; __device__ __forceinline__ unsigned pk2(float lo, float hi) { return f2bf(lo) | (f2bf(hi) << 16); }
; __device__ __forceinline__ float bflo(unsigned w) { return __uint_as_float(w << 16); }
; __device__ __forceinline__ float bfhi(unsigned w) { return __uint_as_float(w & 0xffff0000u); }
; __device__ __forceinline__ float silu(float x) { return x / (1.f + __expf(-x)); }
; __device__ __forceinline__ void attn_unit(const Args& A, const Ctx& C0, int l, int u_qrow0, int u_nq, int u_krow0, int u_krow1, int u_krow2, int u_g, const float* u_ck, const float* u_cv, unsigned u_vmask) {
;     ...
;         const size_t row = (size_t)(u.qrow0 + qi);
; #pragma unroll
;         for (int dt = 0; dt < 2; ++dt)
; #pragma unroll
;             for (int rq = 0; rq < 4; ++rq) { const int d = dt * 32 + 8 * rq + 4 * h;
;                 const v2u gx = gxa[qt][dt][rq];
;                 const float o0 = oacc[dt][4 * rq] * silu(bflo(gx.x)), o1 = oacc[dt][4 * rq + 1] * silu(bfhi(gx.x)), o2 = oacc[dt][4 * rq + 2] * silu(bflo(gx.y)), o3 = oacc[dt][4 * rq + 3] * silu(bfhi(gx.y));
;                 v2u o; o.x = pk2(o0, o1); o.y = pk2(o2, o3);
;                 *(v2u*)(MIX + row * D + 512 + hq * 64 + d) = o; }
	v_fma_f32 v26, -v2, v25, v24
	v_fmac_f32_e32 v25, v26, v4
	v_fma_f32 v2, -v2, v25, v24
	v_div_fmas_f32 v2, v2, v4, v25
	v_div_fixup_f32 v22, v2, v22, v27
	v_mov_b32_e32 v4, v3
	v_pk_mul_f32 v[2:3], v[22:23], v[4:5]
	v_cvt_pk_bf16_f32 v3, v21, v3
	v_cvt_pk_bf16_f32 v2, v20, v2
	v_and_b32_e32 v23, 0xffff0000, v152
	flat_store_dwordx2 v[18:19], v[2:3] offset:64
	v_lshlrev_b32_e32 v5, 16, v153
	v_lshlrev_b32_e32 v20, 16, v152
	v_mul_f32_e32 v3, 0xbfb8aa3b, v23
	v_mul_f32_e32 v2, 0xbfb8aa3b, v20
	v_exp_f32_e32 v4, v3
	v_mul_f32_e32 v3, 0xbfb8aa3b, v5
	v_exp_f32_e32 v2, v2
	v_exp_f32_e32 v3, v3
	v_and_b32_e32 v22, 0xffff0000, v153
	v_pk_add_f32 v[2:3], v[2:3], 1.0 op_sel_hi:[1,0]
	s_nop 0
	v_div_scale_f32 v21, s[2:3], v3, v3, v5
	v_rcp_f32_e32 v24, v21
	s_nop 0
	v_fma_f32 v25, -v21, v24, 1.0
	v_fmac_f32_e32 v24, v25, v24
	v_div_scale_f32 v25, vcc, v5, v3, v5
	v_mul_f32_e32 v26, v25, v24
	v_fma_f32 v27, -v21, v26, v25
	v_fmac_f32_e32 v26, v27, v24
	v_fma_f32 v21, -v21, v26, v25
	v_div_fmas_f32 v21, v21, v24, v26
	v_div_fixup_f32 v3, v21, v3, v5
	v_div_scale_f32 v5, s[2:3], v2, v2, v20
	v_rcp_f32_e32 v21, v5
	s_nop 0
	v_fma_f32 v24, -v5, v21, 1.0
	v_fmac_f32_e32 v21, v24, v21
	v_div_scale_f32 v24, vcc, v20, v2, v20
	v_mul_f32_e32 v25, v24, v21
	v_fma_f32 v26, -v5, v25, v24
	v_fmac_f32_e32 v25, v26, v21
	v_fma_f32 v5, -v5, v25, v24
	v_div_fmas_f32 v5, v5, v21, v25
	v_div_fixup_f32 v2, v5, v2, v20
	v_mul_f32_e32 v5, 0xbfb8aa3b, v22
	v_exp_f32_e32 v5, v5
	v_mov_b32_e32 v20, v6
	v_mov_b32_e32 v21, v8
	v_pk_mul_f32 v[2:3], v[2:3], v[20:21]
	v_pk_add_f32 v[4:5], v[4:5], 1.0 op_sel_hi:[1,0]
	s_nop 0
	v_div_scale_f32 v6, s[2:3], v5, v5, v22
	v_rcp_f32_e32 v8, v6
	s_nop 0
	v_fma_f32 v20, -v6, v8, 1.0
	v_fmac_f32_e32 v8, v20, v8
	v_div_scale_f32 v20, vcc, v22, v5, v22
	v_mul_f32_e32 v21, v20, v8
	v_fma_f32 v24, -v6, v21, v20
	v_fmac_f32_e32 v21, v24, v8
	v_fma_f32 v6, -v6, v21, v20
	v_div_fmas_f32 v6, v6, v8, v21
	v_div_fixup_f32 v5, v6, v5, v22
	v_div_scale_f32 v6, s[2:3], v4, v4, v23
	v_rcp_f32_e32 v8, v6
	s_nop 0
	v_fma_f32 v20, -v6, v8, 1.0
	v_fmac_f32_e32 v8, v20, v8
	v_div_scale_f32 v20, vcc, v23, v4, v23
	v_mul_f32_e32 v21, v20, v8
	v_fma_f32 v22, -v6, v21, v20
	v_fmac_f32_e32 v21, v22, v8
	v_fma_f32 v6, -v6, v21, v20
	v_div_fmas_f32 v6, v6, v8, v21
	v_div_fixup_f32 v4, v6, v4, v23
	v_mov_b32_e32 v8, v7
	v_pk_mul_f32 v[4:5], v[4:5], v[8:9]
	v_cvt_pk_bf16_f32 v3, v3, v5
	v_cvt_pk_bf16_f32 v2, v2, v4
	v_and_b32_e32 v9, 0xffff0000, v150
	flat_store_dwordx2 v[18:19], v[2:3] offset:80
	v_lshlrev_b32_e32 v5, 16, v151
	v_lshlrev_b32_e32 v6, 16, v150
	v_mul_f32_e32 v3, 0xbfb8aa3b, v9
	v_mul_f32_e32 v2, 0xbfb8aa3b, v6
	v_exp_f32_e32 v4, v3
	v_mul_f32_e32 v3, 0xbfb8aa3b, v5
	v_exp_f32_e32 v2, v2
	v_exp_f32_e32 v3, v3
	v_and_b32_e32 v8, 0xffff0000, v151
	v_pk_add_f32 v[2:3], v[2:3], 1.0 op_sel_hi:[1,0]
	s_nop 0
	v_div_scale_f32 v7, s[2:3], v3, v3, v5
	v_rcp_f32_e32 v20, v7
	s_nop 0
	v_fma_f32 v21, -v7, v20, 1.0
	v_fmac_f32_e32 v20, v21, v20
	v_div_scale_f32 v21, vcc, v5, v3, v5
	v_mul_f32_e32 v22, v21, v20
	v_fma_f32 v23, -v7, v22, v21
	v_fmac_f32_e32 v22, v23, v20
	v_fma_f32 v7, -v7, v22, v21
	v_div_fmas_f32 v7, v7, v20, v22
	v_div_fixup_f32 v3, v7, v3, v5
	v_div_scale_f32 v5, s[2:3], v2, v2, v6
	v_rcp_f32_e32 v7, v5
	s_nop 0
	v_fma_f32 v20, -v5, v7, 1.0
	v_fmac_f32_e32 v7, v20, v7
	v_div_scale_f32 v20, vcc, v6, v2, v6
	v_mul_f32_e32 v21, v20, v7
	v_fma_f32 v22, -v5, v21, v20
	v_fmac_f32_e32 v21, v22, v7
	v_fma_f32 v5, -v5, v21, v20
	v_div_fmas_f32 v5, v5, v7, v21
	v_div_fixup_f32 v2, v5, v2, v6
	v_mul_f32_e32 v5, 0xbfb8aa3b, v8
	v_exp_f32_e32 v5, v5
	v_mov_b32_e32 v6, v10
	v_mov_b32_e32 v7, v12
	v_pk_mul_f32 v[2:3], v[2:3], v[6:7]
	v_pk_add_f32 v[4:5], v[4:5], 1.0 op_sel_hi:[1,0]
	s_nop 0
	v_div_scale_f32 v6, s[2:3], v5, v5, v8
	v_rcp_f32_e32 v7, v6
	s_nop 0
	v_fma_f32 v10, -v6, v7, 1.0
	v_fmac_f32_e32 v7, v10, v7
	v_div_scale_f32 v10, vcc, v8, v5, v8
	v_mul_f32_e32 v12, v10, v7
	v_fma_f32 v20, -v6, v12, v10
	v_fmac_f32_e32 v12, v20, v7
	v_fma_f32 v6, -v6, v12, v10
	v_div_fmas_f32 v6, v6, v7, v12
	v_div_fixup_f32 v5, v6, v5, v8
	v_div_scale_f32 v6, s[2:3], v4, v4, v9
	v_rcp_f32_e32 v7, v6
	s_nop 0
	v_fma_f32 v8, -v6, v7, 1.0
	v_fmac_f32_e32 v7, v8, v7
	v_div_scale_f32 v8, vcc, v9, v4, v9
	v_mul_f32_e32 v10, v8, v7
	v_fma_f32 v12, -v6, v10, v8
	v_fmac_f32_e32 v10, v12, v7
	v_fma_f32 v6, -v6, v10, v8
	v_div_fmas_f32 v6, v6, v7, v10
	v_div_fixup_f32 v4, v6, v4, v9
	v_mov_b32_e32 v12, v11
	v_pk_mul_f32 v[4:5], v[4:5], v[12:13]
	v_cvt_pk_bf16_f32 v3, v3, v5
	v_cvt_pk_bf16_f32 v2, v2, v4
	v_and_b32_e32 v9, 0xffff0000, v148
	flat_store_dwordx2 v[18:19], v[2:3] offset:96
	v_lshlrev_b32_e32 v5, 16, v149
	v_lshlrev_b32_e32 v6, 16, v148
	v_mul_f32_e32 v3, 0xbfb8aa3b, v9
	v_mul_f32_e32 v2, 0xbfb8aa3b, v6
	v_exp_f32_e32 v4, v3
	v_mul_f32_e32 v3, 0xbfb8aa3b, v5
	v_exp_f32_e32 v2, v2
	v_exp_f32_e32 v3, v3
	v_and_b32_e32 v8, 0xffff0000, v149
	v_pk_add_f32 v[2:3], v[2:3], 1.0 op_sel_hi:[1,0]
	s_nop 0
	v_div_scale_f32 v7, s[2:3], v3, v3, v5
	v_rcp_f32_e32 v10, v7
	s_nop 0
	v_fma_f32 v11, -v7, v10, 1.0
	v_fmac_f32_e32 v10, v11, v10
	v_div_scale_f32 v11, vcc, v5, v3, v5
	v_mul_f32_e32 v12, v11, v10
	v_fma_f32 v13, -v7, v12, v11
	v_fmac_f32_e32 v12, v13, v10
	v_fma_f32 v7, -v7, v12, v11
	v_div_fmas_f32 v7, v7, v10, v12
	v_div_fixup_f32 v3, v7, v3, v5
	v_div_scale_f32 v5, s[2:3], v2, v2, v6
	v_rcp_f32_e32 v7, v5
	s_nop 0
	v_fma_f32 v10, -v5, v7, 1.0
	v_fmac_f32_e32 v7, v10, v7
	v_div_scale_f32 v10, vcc, v6, v2, v6
	v_mul_f32_e32 v11, v10, v7
	v_fma_f32 v12, -v5, v11, v10
	v_fmac_f32_e32 v11, v12, v7
	v_fma_f32 v5, -v5, v11, v10
	v_div_fmas_f32 v5, v5, v7, v11
	v_div_fixup_f32 v2, v5, v2, v6
	v_mul_f32_e32 v5, 0xbfb8aa3b, v8
	v_exp_f32_e32 v5, v5
	v_mov_b32_e32 v6, v14
	v_mov_b32_e32 v7, v16
	v_pk_mul_f32 v[2:3], v[2:3], v[6:7]
	v_pk_add_f32 v[4:5], v[4:5], 1.0 op_sel_hi:[1,0]
	v_mov_b32_e32 v16, v15
	v_div_scale_f32 v6, s[2:3], v5, v5, v8
	v_rcp_f32_e32 v7, v6
	s_nop 0
	v_fma_f32 v10, -v6, v7, 1.0
	v_fmac_f32_e32 v7, v10, v7
	v_div_scale_f32 v10, vcc, v8, v5, v8
	v_mul_f32_e32 v11, v10, v7
	v_fma_f32 v12, -v6, v11, v10
	v_fmac_f32_e32 v11, v12, v7
	v_fma_f32 v6, -v6, v11, v10
	v_div_fmas_f32 v6, v6, v7, v11
	v_div_fixup_f32 v5, v6, v5, v8
	v_div_scale_f32 v6, s[2:3], v4, v4, v9
	v_rcp_f32_e32 v7, v6
	s_nop 0
	v_fma_f32 v8, -v6, v7, 1.0
	v_fmac_f32_e32 v7, v8, v7
	v_div_scale_f32 v8, vcc, v9, v4, v9
	v_mul_f32_e32 v10, v8, v7
	v_fma_f32 v11, -v6, v10, v8
	v_fmac_f32_e32 v10, v11, v7
	v_fma_f32 v6, -v6, v10, v8
	v_div_fmas_f32 v6, v6, v7, v10
	v_div_fixup_f32 v4, v6, v4, v9
	v_pk_mul_f32 v[4:5], v[4:5], v[16:17]
	s_nop 0
	s_nop 0
	s_nop 0
	s_nop 0
	s_nop 0
	s_nop 0
	s_nop 0
	s_nop 0
	s_nop 0
	s_nop 0
	s_andn2_b64 vcc, exec, s[52:53]
	s_mov_b64 s[52:53], s[78:79]
	s_mov_b64 s[78:79], s[48:49]
	v_readlane_b32 s48, v255, 56
	v_cvt_pk_bf16_f32 v3, v3, v5
	v_cvt_pk_bf16_f32 v2, v2, v4
	v_readlane_b32 s49, v255, 57
	flat_store_dwordx2 v[18:19], v[2:3] offset:112
	s_cbranch_vccnz .LBB0_1155
; #define LAS __attribute__((address_space(3)))
; __device__ __forceinline__ void attn_unit(const Args& A, const Ctx& C0, int l, int u_qrow0, int u_nq, int u_krow0, int u_krow1, int u_krow2, int u_g, const float* u_ck, const float* u_cv, unsigned u_vmask) {
;     ...
;         f32x16 sacc[6];
; #pragma unroll
;         for (int kt = 0; kt < 6; ++kt) {
; #pragma unroll
;             for (int r = 0; r < 16; ++r) sacc[kt][r] = 0.f;
; #pragma unroll
;             for (int ks = 0; ks < 4; ++ks) { const bf16x8 kf = *(const LAS bf16x8*)(Ks + (kt * 32 + li) * KP + ks * 16 + 8 * h);
;                 sacc[kt] = __builtin_amdgcn_mfma_f32_32x32x16_bf16(kf, qf[ks], sacc[kt], 0, 0, 0); }
;             asm volatile("" ::: "memory");
;         }
;         float mx = sink;
; #pragma unroll
;         for (int kt = 0; kt < 6; ++kt) { const bool valid = (u.vmask >> kt) & 1u;
; #pragma unroll
;             for (int r = 0; r < 16; ++r) { const int j = kt * 32 + (r & 3) + 8 * (r >> 2) + 4 * h;
;                 const float lg = valid ? sacc[kt][r] * 0.125f + bL[j - qi + 63] : -1e30f; sacc[kt][r] = lg; mx = fmaxf(mx, lg); }
	v_mul_u32_u24_e32 v2, 0x90, v187
	v_add_u32_e32 v118, v190, v2
	ds_read_b128 v[2:5], v118
	s_and_b64 vcc, exec, s[38:39]
	s_waitcnt lgkmcnt(0)
	v_mfma_f32_32x32x16_bf16 v[82:97], v[2:5], v[114:117], 0
	ds_read_b128 v[2:5], v118 offset:32
	s_waitcnt lgkmcnt(0)
	v_mfma_f32_32x32x16_bf16 v[82:97], v[2:5], v[110:113], v[82:97]
	ds_read_b128 v[2:5], v118 offset:64
	s_waitcnt lgkmcnt(0)
	v_mfma_f32_32x32x16_bf16 v[82:97], v[2:5], v[106:109], v[82:97]
	ds_read_b128 v[2:5], v118 offset:96
	s_waitcnt lgkmcnt(0)
	v_mfma_f32_32x32x16_bf16 v[82:97], v[2:5], v[102:105], v[82:97]
	ds_read_b128 v[2:5], v118 offset:4608
	s_waitcnt lgkmcnt(0)
	v_mfma_f32_32x32x16_bf16 v[66:81], v[2:5], v[114:117], 0
	ds_read_b128 v[2:5], v118 offset:4640
	s_waitcnt lgkmcnt(0)
	v_mfma_f32_32x32x16_bf16 v[66:81], v[2:5], v[110:113], v[66:81]
	ds_read_b128 v[2:5], v118 offset:4672
	s_waitcnt lgkmcnt(0)
	v_mfma_f32_32x32x16_bf16 v[66:81], v[2:5], v[106:109], v[66:81]
	ds_read_b128 v[2:5], v118 offset:4704
	s_waitcnt lgkmcnt(0)
	v_mfma_f32_32x32x16_bf16 v[66:81], v[2:5], v[102:105], v[66:81]
	ds_read_b128 v[2:5], v118 offset:9216
	s_waitcnt lgkmcnt(0)
	v_mfma_f32_32x32x16_bf16 v[50:65], v[2:5], v[114:117], 0
	ds_read_b128 v[2:5], v118 offset:9248
	s_waitcnt lgkmcnt(0)
	v_mfma_f32_32x32x16_bf16 v[50:65], v[2:5], v[110:113], v[50:65]
	ds_read_b128 v[2:5], v118 offset:9280
	s_waitcnt lgkmcnt(0)
	v_mfma_f32_32x32x16_bf16 v[50:65], v[2:5], v[106:109], v[50:65]
	ds_read_b128 v[2:5], v118 offset:9312
	s_waitcnt lgkmcnt(0)
	v_mfma_f32_32x32x16_bf16 v[50:65], v[2:5], v[102:105], v[50:65]
	ds_read_b128 v[2:5], v118 offset:13824
	s_waitcnt lgkmcnt(0)
	v_mfma_f32_32x32x16_bf16 v[34:49], v[2:5], v[114:117], 0
	ds_read_b128 v[2:5], v118 offset:13856
	s_waitcnt lgkmcnt(0)
	v_mfma_f32_32x32x16_bf16 v[34:49], v[2:5], v[110:113], v[34:49]
	ds_read_b128 v[2:5], v118 offset:13888
	s_waitcnt lgkmcnt(0)
	v_mfma_f32_32x32x16_bf16 v[34:49], v[2:5], v[106:109], v[34:49]
	ds_read_b128 v[2:5], v118 offset:13920
	ds_read_b128 v[18:21], v118 offset:18464
	s_waitcnt lgkmcnt(0)
	v_mfma_f32_32x32x16_bf16 v[34:49], v[2:5], v[102:105], v[34:49]
	ds_read_b128 v[2:5], v118 offset:18432
	s_waitcnt lgkmcnt(0)
	v_mfma_f32_32x32x16_bf16 v[2:17], v[2:5], v[114:117], 0
	v_mfma_f32_32x32x16_bf16 v[2:17], v[18:21], v[110:113], v[2:17]
	ds_read_b128 v[18:21], v118 offset:18496
	s_waitcnt lgkmcnt(0)
	v_mfma_f32_32x32x16_bf16 v[2:17], v[18:21], v[106:109], v[2:17]
	ds_read_b128 v[18:21], v118 offset:18528
	s_waitcnt lgkmcnt(0)
	v_mfma_f32_32x32x16_bf16 v[2:17], v[18:21], v[102:105], v[2:17]
	ds_read_b128 v[18:21], v118 offset:23040
	s_waitcnt lgkmcnt(0)
	v_mfma_f32_32x32x16_bf16 v[18:33], v[18:21], v[114:117], 0
	ds_read_b128 v[114:117], v118 offset:23072
	s_waitcnt lgkmcnt(0)
	v_mfma_f32_32x32x16_bf16 v[18:33], v[114:117], v[110:113], v[18:33]
	ds_read_b128 v[110:113], v118 offset:23104
	s_waitcnt lgkmcnt(0)
	v_mfma_f32_32x32x16_bf16 v[18:33], v[110:113], v[106:109], v[18:33]
	ds_read_b128 v[108:111], v118 offset:23136
	v_mov_b32_e32 v106, 0xf149f2ca
	v_mov_b32_e32 v107, 0xf149f2ca
	s_waitcnt lgkmcnt(0)
	v_mfma_f32_32x32x16_bf16 v[18:33], v[108:111], v[102:105], v[18:33]
	s_cbranch_vccnz .Lmy_att5_inv
	s_waitcnt lgkmcnt(0)
	ds_read_b32 v218, v188 offset:52860
	ds_read_b32 v219, v188 offset:52864
	ds_read_b32 v220, v188 offset:52868
	ds_read_b32 v221, v188 offset:52872
	ds_read_b32 v222, v188 offset:52892
	ds_read_b32 v223, v188 offset:52896
	ds_read_b32 v224, v188 offset:52900
	ds_read_b32 v225, v188 offset:52904
	s_waitcnt lgkmcnt(4)
	v_fmamk_f32 v107, v82, 0x3e000000, v218
	v_fmamk_f32 v106, v83, 0x3e000000, v219
	v_fmamk_f32 v83, v84, 0x3e000000, v220
	v_fmamk_f32 v82, v85, 0x3e000000, v221
	ds_read_b32 v226, v188 offset:52924
	ds_read_b32 v227, v188 offset:52928
	ds_read_b32 v228, v188 offset:52932
	ds_read_b32 v230, v188 offset:52936
	s_waitcnt lgkmcnt(4)
	v_fmamk_f32 v85, v86, 0x3e000000, v222
	v_fmamk_f32 v84, v87, 0x3e000000, v223
	v_fmamk_f32 v87, v88, 0x3e000000, v224
	v_fmamk_f32 v86, v89, 0x3e000000, v225
	ds_read_b32 v231, v188 offset:52956
	ds_read_b32 v232, v188 offset:52960
	ds_read_b32 v233, v188 offset:52964
	ds_read_b32 v234, v188 offset:52968
	s_waitcnt lgkmcnt(4)
	v_fmamk_f32 v89, v90, 0x3e000000, v226
	v_fmamk_f32 v88, v91, 0x3e000000, v227
	v_fmamk_f32 v91, v92, 0x3e000000, v228
	v_fmamk_f32 v90, v93, 0x3e000000, v230
	s_waitcnt lgkmcnt(0)
	v_fmamk_f32 v93, v94, 0x3e000000, v231
	v_fmamk_f32 v92, v95, 0x3e000000, v232
	v_fmamk_f32 v95, v96, 0x3e000000, v233
	v_fmamk_f32 v94, v97, 0x3e000000, v234
	s_branch .LBB0_998

; __device__ __forceinline__ unsigned pk2(float lo, float hi) { return f2bf(lo) | (f2bf(hi) << 16); }
; __device__ __forceinline__ float bflo(unsigned w) { return __uint_as_float(w << 16); }
; __device__ __forceinline__ float bfhi(unsigned w) { return __uint_as_float(w & 0xffff0000u); }
; __device__ __forceinline__ float silu(float x) { return x / (1.f + __expf(-x)); }
; __device__ __forceinline__ void attn_unit(const Args& A, const Ctx& C0, int l, int u_qrow0, int u_nq, int u_krow0, int u_krow1, int u_krow2, int u_g, const float* u_ck, const float* u_cv, unsigned u_vmask) {
;     ...
;         const size_t row = (size_t)(u.qrow0 + qi);
; #pragma unroll
;         for (int dt = 0; dt < 2; ++dt)
; #pragma unroll
;             for (int rq = 0; rq < 4; ++rq) { const int d = dt * 32 + 8 * rq + 4 * h;
;                 const v2u gx = gxa[qt][dt][rq];
;                 const float o0 = oacc[dt][4 * rq] * silu(bflo(gx.x)), o1 = oacc[dt][4 * rq + 1] * silu(bfhi(gx.x)), o2 = oacc[dt][4 * rq + 2] * silu(bflo(gx.y)), o3 = oacc[dt][4 * rq + 3] * silu(bfhi(gx.y));
;                 v2u o; o.x = pk2(o0, o1); o.y = pk2(o2, o3);
;                 *(v2u*)(MIX + row * D + 512 + hq * 64 + d) = o; }
.LBB0_1154:
	v_and_b32_e32 v43, 0xffff0000, v146
	v_lshlrev_b32_e32 v39, 16, v147
	v_lshlrev_b32_e32 v40, 16, v146
	v_mul_f32_e32 v37, 0xbfb8aa3b, v43
	v_mul_f32_e32 v36, 0xbfb8aa3b, v40
	v_exp_f32_e32 v38, v37
	v_mul_f32_e32 v37, 0xbfb8aa3b, v39
	v_exp_f32_e32 v36, v36
	v_exp_f32_e32 v37, v37
	v_mov_b32_e32 v34, 0x10000
	v_lshl_add_u32 v34, v184, 11, v34
	v_mov_b32_e32 v35, v1
	v_pk_add_f32 v[36:37], v[36:37], 1.0 op_sel_hi:[1,0]
	v_lshl_add_u64 v[34:35], v[34:35], 1, s[0:1]
	v_div_scale_f32 v41, s[0:1], v37, v37, v39
	v_rcp_f32_e32 v44, v41
	v_and_b32_e32 v42, 0xffff0000, v147
	v_lshl_add_u64 v[34:35], s[36:37], 1, v[34:35]
	v_lshl_add_u64 v[34:35], v[34:35], 0, v[0:1]
	v_fma_f32 v45, -v41, v44, 1.0
	v_fmac_f32_e32 v44, v45, v44
	v_div_scale_f32 v45, vcc, v39, v37, v39
	v_mul_f32_e32 v46, v45, v44
	v_fma_f32 v47, -v41, v46, v45
	v_fmac_f32_e32 v46, v47, v44
	v_fma_f32 v41, -v41, v46, v45
	v_div_fmas_f32 v41, v41, v44, v46
	v_div_fixup_f32 v37, v41, v37, v39
	v_div_scale_f32 v39, s[0:1], v36, v36, v40
	v_rcp_f32_e32 v41, v39
	v_lshlrev_b32_e32 v0, 16, v145
	v_fma_f32 v44, -v39, v41, 1.0
	v_fmac_f32_e32 v41, v44, v41
	v_div_scale_f32 v44, vcc, v40, v36, v40
	v_mul_f32_e32 v45, v44, v41
	v_fma_f32 v46, -v39, v45, v44
	v_fmac_f32_e32 v45, v46, v41
	v_fma_f32 v39, -v39, v45, v44
	v_div_fmas_f32 v39, v39, v41, v45
	v_div_fixup_f32 v36, v39, v36, v40
	v_mov_b32_e32 v40, v18
	v_mul_f32_e32 v18, 0xbfb8aa3b, v42
	v_exp_f32_e32 v39, v18
	v_mov_b32_e32 v41, v20
	v_pk_mul_f32 v[36:37], v[36:37], v[40:41]
	v_pk_add_f32 v[38:39], v[38:39], 1.0 op_sel_hi:[1,0]
	s_nop 0
	v_div_scale_f32 v18, s[0:1], v39, v39, v42
	v_rcp_f32_e32 v20, v18
	s_nop 0
	v_fma_f32 v40, -v18, v20, 1.0
	v_fmac_f32_e32 v20, v40, v20
	v_div_scale_f32 v40, vcc, v42, v39, v42
	v_mul_f32_e32 v41, v40, v20
	v_fma_f32 v44, -v18, v41, v40
	v_fmac_f32_e32 v41, v44, v20
	v_fma_f32 v18, -v18, v41, v40
	v_div_fmas_f32 v18, v18, v20, v41
	v_div_fixup_f32 v39, v18, v39, v42
	v_div_scale_f32 v18, s[0:1], v38, v38, v43
	v_rcp_f32_e32 v20, v18
	s_mov_b64 s[0:1], 0x7b27d00
	v_fma_f32 v40, -v18, v20, 1.0
	v_fmac_f32_e32 v20, v40, v20
	v_div_scale_f32 v40, vcc, v43, v38, v43
	v_mul_f32_e32 v41, v40, v20
	v_fma_f32 v42, -v18, v41, v40
	v_fmac_f32_e32 v41, v42, v20
	v_fma_f32 v18, -v18, v41, v40
	v_div_fmas_f32 v18, v18, v20, v41
	v_div_fixup_f32 v38, v18, v38, v43
	v_mov_b32_e32 v20, v19
	v_pk_mul_f32 v[18:19], v[38:39], v[20:21]
	v_and_b32_sdwa v20, v37, v252 dst_sel:DWORD dst_unused:UNUSED_PAD src0_sel:WORD_1 src1_sel:DWORD
	v_and_b32_sdwa v21, v36, v252 dst_sel:DWORD dst_unused:UNUSED_PAD src0_sel:WORD_1 src1_sel:DWORD
	v_add3_u32 v36, v36, v21, s33
	v_add3_u32 v20, v37, v20, s33
	v_and_b32_sdwa v21, v19, v252 dst_sel:DWORD dst_unused:UNUSED_PAD src0_sel:WORD_1 src1_sel:DWORD
	v_and_b32_sdwa v37, v18, v252 dst_sel:DWORD dst_unused:UNUSED_PAD src0_sel:WORD_1 src1_sel:DWORD
	v_add3_u32 v19, v19, v21, s33
	v_add3_u32 v18, v18, v37, s33
	v_and_b32_e32 v19, 0xffff0000, v19
	v_and_b32_e32 v18, 0xffff0000, v18
	v_or_b32_sdwa v21, v19, v20 dst_sel:DWORD dst_unused:UNUSED_PAD src0_sel:DWORD src1_sel:WORD_1
	v_or_b32_sdwa v20, v18, v36 dst_sel:DWORD dst_unused:UNUSED_PAD src0_sel:DWORD src1_sel:WORD_1
	v_lshl_add_u64 v[18:19], v[34:35], 0, s[0:1]
	s_mov_b32 s0, 0x7b27000
	v_add_co_u32_e32 v34, vcc, s0, v34
	v_and_b32_e32 v39, 0xffff0000, v144
	s_nop 0
	v_addc_co_u32_e32 v35, vcc, 0, v35, vcc
	flat_store_dwordx2 v[34:35], v[20:21] offset:3328
	v_lshlrev_b32_e32 v35, 16, v144
	v_mul_f32_e32 v21, 0xbfb8aa3b, v39
	v_mul_f32_e32 v20, 0xbfb8aa3b, v35
	v_exp_f32_e32 v34, v21
	v_mul_f32_e32 v21, 0xbfb8aa3b, v0
	v_exp_f32_e32 v20, v20
	v_exp_f32_e32 v21, v21
	v_and_b32_e32 v38, 0xffff0000, v145
	v_pk_add_f32 v[20:21], v[20:21], 1.0 op_sel_hi:[1,0]
	s_nop 0
	v_div_scale_f32 v36, s[0:1], v21, v21, v0
	v_rcp_f32_e32 v37, v36
	s_nop 0
	v_fma_f32 v40, -v36, v37, 1.0
	v_fmac_f32_e32 v37, v40, v37
	v_div_scale_f32 v40, vcc, v0, v21, v0
	v_mul_f32_e32 v41, v40, v37
	v_fma_f32 v42, -v36, v41, v40
	v_fmac_f32_e32 v41, v42, v37
	v_fma_f32 v36, -v36, v41, v40
	v_div_fmas_f32 v36, v36, v37, v41
	v_div_fixup_f32 v21, v36, v21, v0
	v_div_scale_f32 v0, s[0:1], v20, v20, v35
	v_rcp_f32_e32 v36, v0
	s_nop 0
	v_fma_f32 v37, -v0, v36, 1.0
	v_fmac_f32_e32 v36, v37, v36
	v_div_scale_f32 v37, vcc, v35, v20, v35
	v_mul_f32_e32 v40, v37, v36
	v_fma_f32 v41, -v0, v40, v37
	v_fmac_f32_e32 v40, v41, v36
	v_fma_f32 v0, -v0, v40, v37
	v_div_fmas_f32 v0, v0, v36, v40
	v_div_fixup_f32 v20, v0, v20, v35
	v_mul_f32_e32 v0, 0xbfb8aa3b, v38
	v_exp_f32_e32 v35, v0
	v_mov_b32_e32 v36, v22
	v_mov_b32_e32 v37, v24
	v_pk_mul_f32 v[20:21], v[20:21], v[36:37]
	v_pk_add_f32 v[34:35], v[34:35], 1.0 op_sel_hi:[1,0]
	s_nop 0
	v_div_scale_f32 v0, s[0:1], v35, v35, v38
	v_rcp_f32_e32 v22, v0
	s_nop 0
	v_fma_f32 v24, -v0, v22, 1.0
	v_fmac_f32_e32 v22, v24, v22
	v_div_scale_f32 v24, vcc, v38, v35, v38
	v_mul_f32_e32 v36, v24, v22
	v_fma_f32 v37, -v0, v36, v24
	v_fmac_f32_e32 v36, v37, v22
	v_fma_f32 v0, -v0, v36, v24
	v_div_fmas_f32 v0, v0, v22, v36
	v_div_fixup_f32 v35, v0, v35, v38
	v_div_scale_f32 v0, s[0:1], v34, v34, v39
	v_rcp_f32_e32 v22, v0
	s_nop 0
	v_fma_f32 v24, -v0, v22, 1.0
	v_fmac_f32_e32 v22, v24, v22
	v_div_scale_f32 v24, vcc, v39, v34, v39
	v_mul_f32_e32 v36, v24, v22
	v_fma_f32 v37, -v0, v36, v24
	v_fmac_f32_e32 v36, v37, v22
	v_fma_f32 v0, -v0, v36, v24
	v_div_fmas_f32 v0, v0, v22, v36
	v_div_fixup_f32 v34, v0, v34, v39
	v_mov_b32_e32 v24, v23
	v_pk_mul_f32 v[22:23], v[34:35], v[24:25]
	v_cvt_pk_bf16_f32 v21, v21, v23
	v_cvt_pk_bf16_f32 v20, v20, v22
	v_and_b32_e32 v35, 0xffff0000, v140
	flat_store_dwordx2 v[18:19], v[20:21] offset:16
; __device__ __forceinline__ unsigned pk2(float lo, float hi) { return f2bf(lo) | (f2bf(hi) << 16); }
; __device__ __forceinline__ float bflo(unsigned w) { return __uint_as_float(w << 16); }
; __device__ __forceinline__ float bfhi(unsigned w) { return __uint_as_float(w & 0xffff0000u); }
; __device__ __forceinline__ float silu(float x) { return x / (1.f + __expf(-x)); }
; __device__ __forceinline__ void attn_unit(const Args& A, const Ctx& C0, int l, int u_qrow0, int u_nq, int u_krow0, int u_krow1, int u_krow2, int u_g, const float* u_ck, const float* u_cv, unsigned u_vmask) {
;     ...
;         const size_t row = (size_t)(u.qrow0 + qi);
; #pragma unroll
;         for (int dt = 0; dt < 2; ++dt)
; #pragma unroll
;             for (int rq = 0; rq < 4; ++rq) { const int d = dt * 32 + 8 * rq + 4 * h;
;                 const v2u gx = gxa[qt][dt][rq];
;                 const float o0 = oacc[dt][4 * rq] * silu(bflo(gx.x)), o1 = oacc[dt][4 * rq + 1] * silu(bfhi(gx.x)), o2 = oacc[dt][4 * rq + 2] * silu(bflo(gx.y)), o3 = oacc[dt][4 * rq + 3] * silu(bfhi(gx.y));
;                 v2u o; o.x = pk2(o0, o1); o.y = pk2(o2, o3);
;                 *(v2u*)(MIX + row * D + 512 + hq * 64 + d) = o; }
	v_lshlrev_b32_e32 v0, 16, v141
	v_lshlrev_b32_e32 v23, 16, v140
	v_mul_f32_e32 v21, 0xbfb8aa3b, v35
	v_mul_f32_e32 v20, 0xbfb8aa3b, v23
	v_exp_f32_e32 v22, v21
	v_mul_f32_e32 v21, 0xbfb8aa3b, v0
	v_exp_f32_e32 v20, v20
	v_exp_f32_e32 v21, v21
	v_and_b32_e32 v34, 0xffff0000, v141
	v_pk_add_f32 v[20:21], v[20:21], 1.0 op_sel_hi:[1,0]
	s_nop 0
	v_div_scale_f32 v24, s[0:1], v21, v21, v0
	v_rcp_f32_e32 v25, v24
	s_nop 0
	v_fma_f32 v36, -v24, v25, 1.0
	v_fmac_f32_e32 v25, v36, v25
	v_div_scale_f32 v36, vcc, v0, v21, v0
	v_mul_f32_e32 v37, v36, v25
	v_fma_f32 v38, -v24, v37, v36
	v_fmac_f32_e32 v37, v38, v25
	v_fma_f32 v24, -v24, v37, v36
	v_div_fmas_f32 v24, v24, v25, v37
	v_div_fixup_f32 v21, v24, v21, v0
	v_div_scale_f32 v0, s[0:1], v20, v20, v23
	v_rcp_f32_e32 v24, v0
	s_nop 0
	v_fma_f32 v25, -v0, v24, 1.0
	v_fmac_f32_e32 v24, v25, v24
	v_div_scale_f32 v25, vcc, v23, v20, v23
	v_mul_f32_e32 v36, v25, v24
	v_fma_f32 v37, -v0, v36, v25
	v_fmac_f32_e32 v36, v37, v24
	v_fma_f32 v0, -v0, v36, v25
	v_div_fmas_f32 v0, v0, v24, v36
	v_div_fixup_f32 v20, v0, v20, v23
	v_mul_f32_e32 v0, 0xbfb8aa3b, v34
	v_exp_f32_e32 v23, v0
	v_mov_b32_e32 v24, v26
	v_mov_b32_e32 v25, v28
	v_pk_mul_f32 v[20:21], v[20:21], v[24:25]
	v_pk_add_f32 v[22:23], v[22:23], 1.0 op_sel_hi:[1,0]
	s_nop 0
	v_div_scale_f32 v0, s[0:1], v23, v23, v34
	v_rcp_f32_e32 v24, v0
	s_nop 0
	v_fma_f32 v25, -v0, v24, 1.0
	v_fmac_f32_e32 v24, v25, v24
	v_div_scale_f32 v25, vcc, v34, v23, v34
	v_mul_f32_e32 v26, v25, v24
	v_fma_f32 v28, -v0, v26, v25
	v_fmac_f32_e32 v26, v28, v24
	v_fma_f32 v0, -v0, v26, v25
	v_div_fmas_f32 v0, v0, v24, v26
	v_div_fixup_f32 v23, v0, v23, v34
	v_div_scale_f32 v0, s[0:1], v22, v22, v35
	v_rcp_f32_e32 v24, v0
	s_nop 0
	v_fma_f32 v25, -v0, v24, 1.0
	v_fmac_f32_e32 v24, v25, v24
	v_div_scale_f32 v25, vcc, v35, v22, v35
	v_mul_f32_e32 v26, v25, v24
	v_fma_f32 v28, -v0, v26, v25
	v_fmac_f32_e32 v26, v28, v24
	v_fma_f32 v0, -v0, v26, v25
	v_div_fmas_f32 v0, v0, v24, v26
	v_div_fixup_f32 v22, v0, v22, v35
	v_mov_b32_e32 v28, v27
	v_pk_mul_f32 v[22:23], v[22:23], v[28:29]
	v_cvt_pk_bf16_f32 v21, v21, v23
	v_cvt_pk_bf16_f32 v20, v20, v22
	v_and_b32_e32 v27, 0xffff0000, v138
	flat_store_dwordx2 v[18:19], v[20:21] offset:32
	v_lshlrev_b32_e32 v0, 16, v139
	v_lshlrev_b32_e32 v23, 16, v138
	v_mul_f32_e32 v21, 0xbfb8aa3b, v27
	v_mul_f32_e32 v20, 0xbfb8aa3b, v23
	v_exp_f32_e32 v22, v21
	v_mul_f32_e32 v21, 0xbfb8aa3b, v0
	v_exp_f32_e32 v20, v20
	v_exp_f32_e32 v21, v21
	v_and_b32_e32 v26, 0xffff0000, v139
	v_pk_add_f32 v[20:21], v[20:21], 1.0 op_sel_hi:[1,0]
	s_nop 0
	v_div_scale_f32 v24, s[0:1], v21, v21, v0
	v_rcp_f32_e32 v25, v24
	s_nop 0
	v_fma_f32 v28, -v24, v25, 1.0
	v_fmac_f32_e32 v25, v28, v25
	v_div_scale_f32 v28, vcc, v0, v21, v0
	v_mul_f32_e32 v29, v28, v25
	v_fma_f32 v34, -v24, v29, v28
	v_fmac_f32_e32 v29, v34, v25
	v_fma_f32 v24, -v24, v29, v28
	v_div_fmas_f32 v24, v24, v25, v29
	v_div_fixup_f32 v21, v24, v21, v0
	v_div_scale_f32 v0, s[0:1], v20, v20, v23
	v_rcp_f32_e32 v24, v0
	s_nop 0
	v_fma_f32 v25, -v0, v24, 1.0
	v_fmac_f32_e32 v24, v25, v24
	v_div_scale_f32 v25, vcc, v23, v20, v23
	v_mul_f32_e32 v28, v25, v24
	v_fma_f32 v29, -v0, v28, v25
	v_fmac_f32_e32 v28, v29, v24
	v_fma_f32 v0, -v0, v28, v25
	v_div_fmas_f32 v0, v0, v24, v28
	v_div_fixup_f32 v20, v0, v20, v23
	v_mul_f32_e32 v0, 0xbfb8aa3b, v26
	v_exp_f32_e32 v23, v0
	v_mov_b32_e32 v24, v30
	v_mov_b32_e32 v25, v32
	v_pk_mul_f32 v[20:21], v[20:21], v[24:25]
	v_pk_add_f32 v[22:23], v[22:23], 1.0 op_sel_hi:[1,0]
	v_mov_b32_e32 v32, v31
	v_div_scale_f32 v0, s[0:1], v23, v23, v26
	v_rcp_f32_e32 v24, v0
	s_nop 0
	v_fma_f32 v25, -v0, v24, 1.0
	v_fmac_f32_e32 v24, v25, v24
	v_div_scale_f32 v25, vcc, v26, v23, v26
	v_mul_f32_e32 v28, v25, v24
	v_fma_f32 v29, -v0, v28, v25
	v_fmac_f32_e32 v28, v29, v24
	v_fma_f32 v0, -v0, v28, v25
	v_div_fmas_f32 v0, v0, v24, v28
	v_div_fixup_f32 v23, v0, v23, v26
	v_div_scale_f32 v0, s[0:1], v22, v22, v27
	v_rcp_f32_e32 v24, v0
	s_nop 0
	v_fma_f32 v25, -v0, v24, 1.0
	v_fmac_f32_e32 v24, v25, v24
	v_div_scale_f32 v25, vcc, v27, v22, v27
	v_mul_f32_e32 v26, v25, v24
	v_fma_f32 v28, -v0, v26, v25
	v_fmac_f32_e32 v26, v28, v24
	v_fma_f32 v0, -v0, v26, v25
	v_div_fmas_f32 v0, v0, v24, v26
	v_div_fixup_f32 v22, v0, v22, v27
	v_pk_mul_f32 v[22:23], v[22:23], v[32:33]
	v_cvt_pk_bf16_f32 v21, v21, v23
	v_cvt_pk_bf16_f32 v20, v20, v22
	v_and_b32_e32 v27, 0xffff0000, v136
	flat_store_dwordx2 v[18:19], v[20:21] offset:48
	v_lshlrev_b32_e32 v0, 16, v137
	v_lshlrev_b32_e32 v23, 16, v136
	v_mul_f32_e32 v21, 0xbfb8aa3b, v27
	v_mul_f32_e32 v20, 0xbfb8aa3b, v23
	v_exp_f32_e32 v22, v21
	v_mul_f32_e32 v21, 0xbfb8aa3b, v0
	v_exp_f32_e32 v20, v20
	v_exp_f32_e32 v21, v21
	v_and_b32_e32 v26, 0xffff0000, v137
	v_pk_add_f32 v[20:21], v[20:21], 1.0 op_sel_hi:[1,0]
	s_nop 0
	v_div_scale_f32 v24, s[0:1], v21, v21, v0
	v_rcp_f32_e32 v25, v24
	s_nop 0
	v_fma_f32 v28, -v24, v25, 1.0
	v_fmac_f32_e32 v25, v28, v25
	v_div_scale_f32 v28, vcc, v0, v21, v0
	v_mul_f32_e32 v29, v28, v25
	v_fma_f32 v30, -v24, v29, v28
	v_fmac_f32_e32 v29, v30, v25
	v_fma_f32 v24, -v24, v29, v28
	v_div_fmas_f32 v24, v24, v25, v29
	v_div_fixup_f32 v21, v24, v21, v0
	v_div_scale_f32 v0, s[0:1], v20, v20, v23
	v_rcp_f32_e32 v24, v0
	s_nop 0
	v_fma_f32 v25, -v0, v24, 1.0
	v_fmac_f32_e32 v24, v25, v24
	v_div_scale_f32 v25, vcc, v23, v20, v23
	v_mul_f32_e32 v28, v25, v24
	v_fma_f32 v29, -v0, v28, v25
	v_fmac_f32_e32 v28, v29, v24
	v_fma_f32 v0, -v0, v28, v25
	v_div_fmas_f32 v0, v0, v24, v28
	v_div_fixup_f32 v20, v0, v20, v23
	v_mul_f32_e32 v0, 0xbfb8aa3b, v26
	v_exp_f32_e32 v23, v0
	v_mov_b32_e32 v24, v2
	v_mov_b32_e32 v25, v4
; __device__ __forceinline__ unsigned pk2(float lo, float hi) { return f2bf(lo) | (f2bf(hi) << 16); }
; __device__ __forceinline__ float bflo(unsigned w) { return __uint_as_float(w << 16); }
; __device__ __forceinline__ float bfhi(unsigned w) { return __uint_as_float(w & 0xffff0000u); }
; __device__ __forceinline__ float silu(float x) { return x / (1.f + __expf(-x)); }
; __device__ __forceinline__ void attn_unit(const Args& A, const Ctx& C0, int l, int u_qrow0, int u_nq, int u_krow0, int u_krow1, int u_krow2, int u_g, const float* u_ck, const float* u_cv, unsigned u_vmask) {
;     ...
;         const size_t row = (size_t)(u.qrow0 + qi);
; #pragma unroll
;         for (int dt = 0; dt < 2; ++dt)
; #pragma unroll
;             for (int rq = 0; rq < 4; ++rq) { const int d = dt * 32 + 8 * rq + 4 * h;
;                 const v2u gx = gxa[qt][dt][rq];
;                 const float o0 = oacc[dt][4 * rq] * silu(bflo(gx.x)), o1 = oacc[dt][4 * rq + 1] * silu(bfhi(gx.x)), o2 = oacc[dt][4 * rq + 2] * silu(bflo(gx.y)), o3 = oacc[dt][4 * rq + 3] * silu(bfhi(gx.y));
;                 v2u o; o.x = pk2(o0, o1); o.y = pk2(o2, o3);
;                 *(v2u*)(MIX + row * D + 512 + hq * 64 + d) = o; }
	v_pk_mul_f32 v[20:21], v[20:21], v[24:25]
	v_pk_add_f32 v[22:23], v[22:23], 1.0 op_sel_hi:[1,0]
	s_nop 0
	v_div_scale_f32 v0, s[0:1], v23, v23, v26
	v_rcp_f32_e32 v2, v0
	s_nop 0
	v_fma_f32 v4, -v0, v2, 1.0
	v_fmac_f32_e32 v2, v4, v2
	v_div_scale_f32 v4, vcc, v26, v23, v26
	v_mul_f32_e32 v24, v4, v2
	v_fma_f32 v25, -v0, v24, v4
	v_fmac_f32_e32 v24, v25, v2
	v_fma_f32 v0, -v0, v24, v4
	v_div_fmas_f32 v0, v0, v2, v24
	v_div_fixup_f32 v23, v0, v23, v26
	v_div_scale_f32 v0, s[0:1], v22, v22, v27
	v_rcp_f32_e32 v2, v0
	s_nop 0
	v_fma_f32 v4, -v0, v2, 1.0
	v_fmac_f32_e32 v2, v4, v2
	v_div_scale_f32 v4, vcc, v27, v22, v27
	v_mul_f32_e32 v24, v4, v2
	v_fma_f32 v25, -v0, v24, v4
	v_fmac_f32_e32 v24, v25, v2
	v_fma_f32 v0, -v0, v24, v4
	v_div_fmas_f32 v0, v0, v2, v24
	v_div_fixup_f32 v22, v0, v22, v27
	v_mov_b32_e32 v4, v3
	v_pk_mul_f32 v[2:3], v[22:23], v[4:5]
	v_cvt_pk_bf16_f32 v3, v21, v3
	v_cvt_pk_bf16_f32 v2, v20, v2
	v_and_b32_e32 v23, 0xffff0000, v134
	flat_store_dwordx2 v[18:19], v[2:3] offset:64
	v_lshlrev_b32_e32 v0, 16, v135
	v_lshlrev_b32_e32 v5, 16, v134
	v_mul_f32_e32 v3, 0xbfb8aa3b, v23
	v_mul_f32_e32 v2, 0xbfb8aa3b, v5
	v_exp_f32_e32 v4, v3
	v_mul_f32_e32 v3, 0xbfb8aa3b, v0
	v_exp_f32_e32 v2, v2
	v_exp_f32_e32 v3, v3
	v_and_b32_e32 v22, 0xffff0000, v135
	v_pk_add_f32 v[2:3], v[2:3], 1.0 op_sel_hi:[1,0]
	s_nop 0
	v_div_scale_f32 v20, s[0:1], v3, v3, v0
	v_rcp_f32_e32 v21, v20
	s_nop 0
	v_fma_f32 v24, -v20, v21, 1.0
	v_fmac_f32_e32 v21, v24, v21
	v_div_scale_f32 v24, vcc, v0, v3, v0
	v_mul_f32_e32 v25, v24, v21
	v_fma_f32 v26, -v20, v25, v24
	v_fmac_f32_e32 v25, v26, v21
	v_fma_f32 v20, -v20, v25, v24
	v_div_fmas_f32 v20, v20, v21, v25
	v_div_fixup_f32 v3, v20, v3, v0
	v_div_scale_f32 v0, s[0:1], v2, v2, v5
	v_rcp_f32_e32 v20, v0
	s_nop 0
	v_fma_f32 v21, -v0, v20, 1.0
	v_fmac_f32_e32 v20, v21, v20
	v_div_scale_f32 v21, vcc, v5, v2, v5
	v_mul_f32_e32 v24, v21, v20
	v_fma_f32 v25, -v0, v24, v21
	v_fmac_f32_e32 v24, v25, v20
	v_fma_f32 v0, -v0, v24, v21
	v_div_fmas_f32 v0, v0, v20, v24
	v_div_fixup_f32 v2, v0, v2, v5
	v_mul_f32_e32 v0, 0xbfb8aa3b, v22
	v_exp_f32_e32 v5, v0
	v_mov_b32_e32 v20, v6
	v_mov_b32_e32 v21, v8
	v_pk_mul_f32 v[2:3], v[2:3], v[20:21]
	v_pk_add_f32 v[4:5], v[4:5], 1.0 op_sel_hi:[1,0]
	s_nop 0
	v_div_scale_f32 v0, s[0:1], v5, v5, v22
	v_rcp_f32_e32 v6, v0
	s_nop 0
	v_fma_f32 v8, -v0, v6, 1.0
	v_fmac_f32_e32 v6, v8, v6
	v_div_scale_f32 v8, vcc, v22, v5, v22
	v_mul_f32_e32 v20, v8, v6
	v_fma_f32 v21, -v0, v20, v8
	v_fmac_f32_e32 v20, v21, v6
	v_fma_f32 v0, -v0, v20, v8
	v_div_fmas_f32 v0, v0, v6, v20
	v_div_fixup_f32 v5, v0, v5, v22
	v_div_scale_f32 v0, s[0:1], v4, v4, v23
	v_rcp_f32_e32 v6, v0
	s_nop 0
	v_fma_f32 v8, -v0, v6, 1.0
	v_fmac_f32_e32 v6, v8, v6
	v_div_scale_f32 v8, vcc, v23, v4, v23
	v_mul_f32_e32 v20, v8, v6
	v_fma_f32 v21, -v0, v20, v8
	v_fmac_f32_e32 v20, v21, v6
	v_fma_f32 v0, -v0, v20, v8
	v_div_fmas_f32 v0, v0, v6, v20
	v_div_fixup_f32 v4, v0, v4, v23
	v_mov_b32_e32 v8, v7
	v_pk_mul_f32 v[4:5], v[4:5], v[8:9]
	v_cvt_pk_bf16_f32 v3, v3, v5
	v_cvt_pk_bf16_f32 v2, v2, v4
	v_and_b32_e32 v9, 0xffff0000, v132
	flat_store_dwordx2 v[18:19], v[2:3] offset:80
	v_lshlrev_b32_e32 v0, 16, v133
	v_lshlrev_b32_e32 v5, 16, v132
	v_mul_f32_e32 v3, 0xbfb8aa3b, v9
	v_mul_f32_e32 v2, 0xbfb8aa3b, v5
	v_exp_f32_e32 v4, v3
	v_mul_f32_e32 v3, 0xbfb8aa3b, v0
	v_exp_f32_e32 v2, v2
	v_exp_f32_e32 v3, v3
	v_and_b32_e32 v8, 0xffff0000, v133
	v_pk_add_f32 v[2:3], v[2:3], 1.0 op_sel_hi:[1,0]
	s_nop 0
	v_div_scale_f32 v6, s[0:1], v3, v3, v0
	v_rcp_f32_e32 v7, v6
	s_nop 0
	v_fma_f32 v20, -v6, v7, 1.0
	v_fmac_f32_e32 v7, v20, v7
	v_div_scale_f32 v20, vcc, v0, v3, v0
	v_mul_f32_e32 v21, v20, v7
	v_fma_f32 v22, -v6, v21, v20
; __device__ __forceinline__ unsigned pk2(float lo, float hi) { return f2bf(lo) | (f2bf(hi) << 16); }
; __device__ __forceinline__ float bflo(unsigned w) { return __uint_as_float(w << 16); }
; __device__ __forceinline__ float bfhi(unsigned w) { return __uint_as_float(w & 0xffff0000u); }
; __device__ __forceinline__ float silu(float x) { return x / (1.f + __expf(-x)); }
; __device__ __forceinline__ void attn_unit(const Args& A, const Ctx& C0, int l, int u_qrow0, int u_nq, int u_krow0, int u_krow1, int u_krow2, int u_g, const float* u_ck, const float* u_cv, unsigned u_vmask) {
;     ...
;         const size_t row = (size_t)(u.qrow0 + qi);
; #pragma unroll
;         for (int dt = 0; dt < 2; ++dt)
; #pragma unroll
;             for (int rq = 0; rq < 4; ++rq) { const int d = dt * 32 + 8 * rq + 4 * h;
;                 const v2u gx = gxa[qt][dt][rq];
;                 const float o0 = oacc[dt][4 * rq] * silu(bflo(gx.x)), o1 = oacc[dt][4 * rq + 1] * silu(bfhi(gx.x)), o2 = oacc[dt][4 * rq + 2] * silu(bflo(gx.y)), o3 = oacc[dt][4 * rq + 3] * silu(bfhi(gx.y));
;                 v2u o; o.x = pk2(o0, o1); o.y = pk2(o2, o3);
;                 *(v2u*)(MIX + row * D + 512 + hq * 64 + d) = o; }
	v_fmac_f32_e32 v21, v22, v7
	v_fma_f32 v6, -v6, v21, v20
	v_div_fmas_f32 v6, v6, v7, v21
	v_div_fixup_f32 v3, v6, v3, v0
	v_div_scale_f32 v0, s[0:1], v2, v2, v5
	v_rcp_f32_e32 v6, v0
	s_nop 0
	v_fma_f32 v7, -v0, v6, 1.0
	v_fmac_f32_e32 v6, v7, v6
	v_div_scale_f32 v7, vcc, v5, v2, v5
	v_mul_f32_e32 v20, v7, v6
	v_fma_f32 v21, -v0, v20, v7
	v_fmac_f32_e32 v20, v21, v6
	v_fma_f32 v0, -v0, v20, v7
	v_div_fmas_f32 v0, v0, v6, v20
	v_div_fixup_f32 v2, v0, v2, v5
	v_mul_f32_e32 v0, 0xbfb8aa3b, v8
	v_exp_f32_e32 v5, v0
	v_mov_b32_e32 v6, v10
	v_mov_b32_e32 v7, v12
	v_pk_mul_f32 v[2:3], v[2:3], v[6:7]
	v_pk_add_f32 v[4:5], v[4:5], 1.0 op_sel_hi:[1,0]
	s_nop 0
	v_div_scale_f32 v0, s[0:1], v5, v5, v8
	v_rcp_f32_e32 v6, v0
	s_nop 0
	v_fma_f32 v7, -v0, v6, 1.0
	v_fmac_f32_e32 v6, v7, v6
	v_div_scale_f32 v7, vcc, v8, v5, v8
	v_mul_f32_e32 v10, v7, v6
	v_fma_f32 v12, -v0, v10, v7
	v_fmac_f32_e32 v10, v12, v6
	v_fma_f32 v0, -v0, v10, v7
	v_div_fmas_f32 v0, v0, v6, v10
	v_div_fixup_f32 v5, v0, v5, v8
	v_div_scale_f32 v0, s[0:1], v4, v4, v9
	v_rcp_f32_e32 v6, v0
	v_mov_b32_e32 v12, v11
	v_fma_f32 v7, -v0, v6, 1.0
	v_fmac_f32_e32 v6, v7, v6
	v_div_scale_f32 v7, vcc, v9, v4, v9
	v_mul_f32_e32 v8, v7, v6
	v_fma_f32 v10, -v0, v8, v7
	v_fmac_f32_e32 v8, v10, v6
	v_fma_f32 v0, -v0, v8, v7
	v_div_fmas_f32 v0, v0, v6, v8
	v_div_fixup_f32 v4, v0, v4, v9
	v_pk_mul_f32 v[4:5], v[4:5], v[12:13]
	v_cvt_pk_bf16_f32 v3, v3, v5
	v_cvt_pk_bf16_f32 v2, v2, v4
	v_and_b32_e32 v9, 0xffff0000, v130
	flat_store_dwordx2 v[18:19], v[2:3] offset:96
	v_lshlrev_b32_e32 v0, 16, v131
	v_lshlrev_b32_e32 v5, 16, v130
	v_mul_f32_e32 v3, 0xbfb8aa3b, v9
	v_mul_f32_e32 v2, 0xbfb8aa3b, v5
	v_exp_f32_e32 v4, v3
	v_mul_f32_e32 v3, 0xbfb8aa3b, v0
	v_exp_f32_e32 v2, v2
	v_exp_f32_e32 v3, v3
	v_and_b32_e32 v8, 0xffff0000, v131
	v_pk_add_f32 v[2:3], v[2:3], 1.0 op_sel_hi:[1,0]
	s_nop 0
	v_div_scale_f32 v6, s[0:1], v3, v3, v0
	v_rcp_f32_e32 v7, v6
	s_nop 0
	v_fma_f32 v10, -v6, v7, 1.0
	v_fmac_f32_e32 v7, v10, v7
	v_div_scale_f32 v10, vcc, v0, v3, v0
	v_mul_f32_e32 v11, v10, v7
	v_fma_f32 v12, -v6, v11, v10
	v_fmac_f32_e32 v11, v12, v7
	v_fma_f32 v6, -v6, v11, v10
	v_div_fmas_f32 v6, v6, v7, v11
	v_div_fixup_f32 v3, v6, v3, v0
	v_div_scale_f32 v0, s[0:1], v2, v2, v5
	v_rcp_f32_e32 v6, v0
	s_nop 0
	v_fma_f32 v7, -v0, v6, 1.0
	v_fmac_f32_e32 v6, v7, v6
	v_div_scale_f32 v7, vcc, v5, v2, v5
	v_mul_f32_e32 v10, v7, v6
	v_fma_f32 v11, -v0, v10, v7
	v_fmac_f32_e32 v10, v11, v6
	v_fma_f32 v0, -v0, v10, v7
	v_div_fmas_f32 v0, v0, v6, v10
	v_div_fixup_f32 v2, v0, v2, v5
	v_mul_f32_e32 v0, 0xbfb8aa3b, v8
	v_exp_f32_e32 v5, v0
	v_mov_b32_e32 v6, v14
	v_mov_b32_e32 v7, v16
	v_pk_mul_f32 v[2:3], v[2:3], v[6:7]
	v_pk_add_f32 v[4:5], v[4:5], 1.0 op_sel_hi:[1,0]
	v_mov_b32_e32 v16, v15
	v_div_scale_f32 v0, s[0:1], v5, v5, v8
	v_rcp_f32_e32 v6, v0
	s_nop 0
	v_fma_f32 v7, -v0, v6, 1.0
	v_fmac_f32_e32 v6, v7, v6
	v_div_scale_f32 v7, vcc, v8, v5, v8
	v_mul_f32_e32 v10, v7, v6
	v_fma_f32 v11, -v0, v10, v7
	v_fmac_f32_e32 v10, v11, v6
	v_fma_f32 v0, -v0, v10, v7
	v_div_fmas_f32 v0, v0, v6, v10
	v_div_fixup_f32 v5, v0, v5, v8
	v_div_scale_f32 v0, s[0:1], v4, v4, v9
	v_rcp_f32_e32 v6, v0
	s_nop 0
	v_fma_f32 v7, -v0, v6, 1.0
	v_fmac_f32_e32 v6, v7, v6
	v_div_scale_f32 v7, vcc, v9, v4, v9
	v_mul_f32_e32 v8, v7, v6
	v_fma_f32 v10, -v0, v8, v7
	v_fmac_f32_e32 v8, v10, v6
	v_fma_f32 v0, -v0, v8, v7
	v_div_fmas_f32 v0, v0, v6, v8
	v_div_fixup_f32 v4, v0, v4, v9
	v_pk_mul_f32 v[4:5], v[4:5], v[16:17]
	s_nop 0
	s_nop 0
	s_nop 0
	s_nop 0
	s_nop 0
	s_nop 0
	s_nop 0
	s_nop 0
	s_nop 0
	s_nop 0
	v_cvt_pk_bf16_f32 v3, v3, v5
	v_cvt_pk_bf16_f32 v2, v2, v4
	flat_store_dwordx2 v[18:19], v[2:3] offset:112
